# packed f32 VALU ops split into scalar pairs in all phases
# baseline (speedup 1.0000x reference)
.LBB0_250:
	v_mov_b32_e32 v1, s83
	v_or_b32_e32 v0, s82, v76
	v_lshl_add_u64 v[48:49], v[0:1], 0, s[80:81]
	v_or_b32_e32 v0, v48, v134
	v_mov_b32_e32 v1, v49
	v_lshlrev_b64 v[0:1], 12, v[0:1]
	v_lshl_add_u64 v[0:1], s[50:51], 0, v[0:1]
	s_lshl_b32 s28, s89, 1
	v_lshl_add_u64 v[0:1], v[0:1], 0, s[28:29]
	v_mov_b32_e32 v93, v72
	v_lshl_add_u64 v[0:1], v[0:1], 0, v[92:93]
	v_or_b32_e32 v4, v48, v136
	v_mov_b32_e32 v5, v49
	v_add_co_u32_e32 v50, vcc, s87, v0
	v_lshlrev_b64 v[4:5], 12, v[4:5]
	s_nop 0
	v_addc_co_u32_e32 v51, vcc, 0, v1, vcc
	v_lshl_add_u64 v[4:5], s[50:51], 0, v[4:5]
	global_load_dwordx4 v[0:3], v[50:51], off offset:2048
	v_lshl_add_u64 v[4:5], v[4:5], 0, s[28:29]
	v_lshl_add_u64 v[4:5], v[4:5], 0, v[92:93]
	v_add_co_u32_e32 v52, vcc, s87, v4
	s_nop 1
	v_addc_co_u32_e32 v53, vcc, 0, v5, vcc
	global_load_dwordx4 v[4:7], v[52:53], off offset:2048
	ds_write_b128 v169, v[16:19]
	ds_write_b128 v169, v[20:23] offset:64
	ds_write_b128 v169, v[24:27] offset:128
	ds_write_b128 v169, v[32:35] offset:192
	ds_write_b128 v169, v[28:31] offset:256
	ds_write_b128 v169, v[36:39] offset:320
	ds_write_b128 v169, v[40:43] offset:384
	ds_write_b128 v169, v[44:47] offset:448
	v_or_b32_e32 v16, v48, v132
	v_mov_b32_e32 v17, v49
	v_lshlrev_b64 v[16:17], 12, v[16:17]
	v_lshl_add_u64 v[16:17], s[50:51], 0, v[16:17]
	v_lshl_add_u64 v[16:17], v[16:17], 0, s[28:29]
	v_lshl_add_u64 v[16:17], v[16:17], 0, v[92:93]
	v_add_co_u32_e32 v32, vcc, s87, v16
	ds_read_b128 v[8:11], v170
	ds_read_b128 v[12:15], v170 offset:16
	v_addc_co_u32_e32 v33, vcc, 0, v17, vcc
	global_load_dwordx4 v[16:19], v[32:33], off offset:2048
	v_or_b32_e32 v48, v48, v130
	v_lshlrev_b64 v[28:29], 12, v[48:49]
	v_lshl_add_u64 v[28:29], s[50:51], 0, v[28:29]
	v_lshl_add_u64 v[28:29], v[28:29], 0, s[28:29]
	v_lshl_add_u64 v[28:29], v[28:29], 0, v[92:93]
	v_add_co_u32_e32 v34, vcc, s87, v28
	ds_read_b128 v[20:23], v170 offset:2112
	ds_read_b128 v[24:27], v170 offset:2128
	v_addc_co_u32_e32 v35, vcc, 0, v29, vcc
	global_load_dwordx4 v[28:31], v[34:35], off offset:2048
	s_waitcnt vmcnt(3)
	v_and_b32_e32 v37, 0xffff0000, v0
	v_lshlrev_b32_e32 v36, 16, v0
	v_and_b32_e32 v39, 0xffff0000, v2
	v_lshlrev_b32_e32 v38, 16, v2
	v_and_b32_e32 v41, 0xffff0000, v1
	v_lshlrev_b32_e32 v40, 16, v1
	v_and_b32_e32 v1, 0xffff0000, v3
	v_lshlrev_b32_e32 v0, 16, v3
	s_waitcnt lgkmcnt(3)
	v_mul_f32_e32 v2, v8, v36
	v_mul_f32_e32 v3, v9, v37
	s_waitcnt lgkmcnt(2)
	v_mul_f32_e32 v8, v12, v38
	v_mul_f32_e32 v9, v13, v39
	v_mul_f32_e32 v10, v10, v40
	v_mul_f32_e32 v11, v11, v41
	v_mul_f32_e32 v0, v14, v0
	v_mul_f32_e32 v1, v15, v1
	v_bfe_u32 v14, v9, 16, 1
	v_bfe_u32 v15, v8, 16, 1
	v_bfe_u32 v38, v3, 16, 1
	v_bfe_u32 v39, v2, 16, 1
	v_add3_u32 v39, v2, v39, s84
	v_add3_u32 v38, v3, v38, s84
	v_add3_u32 v2, v8, v15, s84
	v_add3_u32 v8, v9, v14, s84
	v_cvt_pk_bf16_f32 v3, v0, v1
	v_perm_b32 v2, v8, v2, s85
	v_cvt_pk_bf16_f32 v1, v10, v11
	v_perm_b32 v0, v38, v39, s85
	s_waitcnt vmcnt(2)
	v_and_b32_e32 v9, 0xffff0000, v5
	v_lshlrev_b32_e32 v8, 16, v5
	v_and_b32_e32 v43, 0xffff0000, v4
	global_store_dwordx4 v[50:51], v[0:3], off offset:2048
	v_lshlrev_b32_e32 v42, 16, v4
	s_waitcnt lgkmcnt(1)
	v_mul_f32_e32 v4, v22, v8
	v_mul_f32_e32 v5, v23, v9
	v_and_b32_e32 v3, 0xffff0000, v6
	v_lshlrev_b32_e32 v2, 16, v6
	v_and_b32_e32 v9, 0xffff0000, v7
	v_lshlrev_b32_e32 v8, 16, v7
	v_mul_f32_e32 v0, v20, v42
	v_mul_f32_e32 v1, v21, v43
	s_waitcnt lgkmcnt(0)
	v_mul_f32_e32 v2, v24, v2
	v_mul_f32_e32 v3, v25, v3
	v_mul_f32_e32 v6, v26, v8
	v_mul_f32_e32 v7, v27, v9
	v_bfe_u32 v10, v3, 16, 1
	v_bfe_u32 v8, v7, 16, 1
	v_bfe_u32 v9, v6, 16, 1
	v_bfe_u32 v11, v2, 16, 1
	v_bfe_u32 v12, v5, 16, 1
	v_bfe_u32 v13, v4, 16, 1
	v_bfe_u32 v14, v1, 16, 1
	v_bfe_u32 v15, v0, 16, 1
	v_add3_u32 v0, v0, v15, s84
	v_add3_u32 v14, v1, v14, s84
	v_add3_u32 v1, v4, v13, s84
	v_add3_u32 v4, v5, v12, s84
	v_add3_u32 v2, v2, v11, s84
	v_add3_u32 v5, v3, v10, s84
	v_add3_u32 v3, v6, v9, s84
	v_add3_u32 v6, v7, v8, s84
	v_perm_b32 v3, v6, v3, s85
	v_perm_b32 v2, v5, v2, s85
	v_perm_b32 v1, v4, v1, s85
	v_perm_b32 v0, v14, v0, s85
	ds_read_b128 v[4:7], v170 offset:4224
	global_store_dwordx4 v[52:53], v[0:3], off offset:2048
	ds_read_b128 v[0:3], v170 offset:4240
	s_waitcnt vmcnt(3)
	v_and_b32_e32 v9, 0xffff0000, v16
	v_lshlrev_b32_e32 v8, 16, v16
	s_waitcnt lgkmcnt(1)
	v_mul_f32_e32 v4, v4, v8
	v_mul_f32_e32 v5, v5, v9
	v_and_b32_e32 v9, 0xffff0000, v18
	v_lshlrev_b32_e32 v8, 16, v18
	s_waitcnt lgkmcnt(0)
	v_mul_f32_e32 v0, v0, v8
	v_mul_f32_e32 v1, v1, v9
	v_and_b32_e32 v9, 0xffff0000, v17
	v_lshlrev_b32_e32 v8, 16, v17
	v_mul_f32_e32 v6, v6, v8
	v_mul_f32_e32 v7, v7, v9
	v_and_b32_e32 v9, 0xffff0000, v19
	v_lshlrev_b32_e32 v8, 16, v19
	v_mul_f32_e32 v2, v2, v8
	v_mul_f32_e32 v3, v3, v9
	v_cvt_pk_bf16_f32 v3, v2, v3
	v_cvt_pk_bf16_f32 v2, v0, v1
	v_cvt_pk_bf16_f32 v1, v6, v7
	v_cvt_pk_bf16_f32 v0, v4, v5
	ds_read_b128 v[4:7], v170 offset:6336
	global_store_dwordx4 v[32:33], v[0:3], off offset:2048
	ds_read_b128 v[0:3], v170 offset:6352
	s_waitcnt vmcnt(3)
	v_and_b32_e32 v9, 0xffff0000, v28
	v_lshlrev_b32_e32 v8, 16, v28
	s_waitcnt lgkmcnt(1)
	v_mul_f32_e32 v4, v4, v8
	v_mul_f32_e32 v5, v5, v9
	v_and_b32_e32 v9, 0xffff0000, v30
	v_lshlrev_b32_e32 v8, 16, v30
	s_waitcnt lgkmcnt(0)
	v_mul_f32_e32 v0, v0, v8
	v_mul_f32_e32 v1, v1, v9
	v_and_b32_e32 v9, 0xffff0000, v29
	v_lshlrev_b32_e32 v8, 16, v29
	v_mul_f32_e32 v6, v6, v8
	v_mul_f32_e32 v7, v7, v9
	v_and_b32_e32 v9, 0xffff0000, v31
	v_lshlrev_b32_e32 v8, 16, v31
	v_mul_f32_e32 v2, v2, v8
	v_mul_f32_e32 v3, v3, v9
	v_cvt_pk_bf16_f32 v3, v2, v3
	v_cvt_pk_bf16_f32 v2, v0, v1
	v_cvt_pk_bf16_f32 v1, v6, v7
	v_cvt_pk_bf16_f32 v0, v4, v5
	global_store_dwordx4 v[34:35], v[0:3], off offset:2048
	s_barrier

.LBB0_254:
	s_and_b32 s10, s88, 7
	s_lshl_b32 s28, s10, 15
	v_readfirstlane_b32 s8, v129
	v_lshl_add_u64 v[4:5], v[78:79], 0, s[28:29]
	s_mov_b32 m0, s8
	v_readfirstlane_b32 s8, v141
	s_barrier
	global_load_lds_dwordx4 v[4:5], off
	v_lshl_add_u64 v[0:1], v[4:5], 0, s[38:39]
	s_mov_b32 m0, s8
	v_readfirstlane_b32 s8, v142
	s_add_i32 s9, s88, 0xfffff800
	global_load_lds_dwordx4 v[0:1], off
	v_lshl_add_u64 v[0:1], v[4:5], 0, s[46:47]
	s_mov_b32 m0, s8
	v_readfirstlane_b32 s8, v143
	global_load_lds_dwordx4 v[0:1], off
	v_lshl_add_u64 v[0:1], v[4:5], 0, s[52:53]
	s_mov_b32 m0, s8
	s_lshl_b32 s28, s9, 15
	v_readfirstlane_b32 s8, v144
	global_load_lds_dwordx4 v[0:1], off
	v_lshl_add_u64 v[6:7], v[80:81], 0, s[28:29]
	s_mov_b32 m0, s8
	v_readfirstlane_b32 s8, v145
	global_load_lds_dwordx4 v[6:7], off
	v_lshl_add_u64 v[0:1], v[6:7], 0, s[38:39]
	s_mov_b32 m0, s8
	v_readfirstlane_b32 s8, v146
	global_load_lds_dwordx4 v[0:1], off
	v_lshl_add_u64 v[0:1], v[6:7], 0, s[46:47]
	s_mov_b32 m0, s8
	v_readfirstlane_b32 s8, v147
	global_load_lds_dwordx4 v[0:1], off
	v_lshl_add_u64 v[0:1], v[6:7], 0, s[52:53]
	s_mov_b32 m0, s8
	v_readfirstlane_b32 s8, v148
	global_load_lds_dwordx4 v[0:1], off
	v_lshl_add_u64 v[8:9], v[4:5], 0, s[56:57]
	s_mov_b32 m0, s8
	v_readfirstlane_b32 s8, v150
	s_waitcnt vmcnt(0)
	s_barrier
	ds_read_b128 v[0:3], v166 offset:16384
	ds_read_b128 v[28:31], v166 offset:18432
	ds_read_b128 v[32:35], v166 offset:20480
	global_load_lds_dwordx4 v[8:9], off
	v_lshl_add_u64 v[8:9], v[4:5], 0, s[58:59]
	s_mov_b32 m0, s8
	v_readfirstlane_b32 s8, v151
	global_load_lds_dwordx4 v[8:9], off
	v_lshl_add_u64 v[8:9], v[4:5], 0, s[60:61]
	s_mov_b32 m0, s8
	v_readfirstlane_b32 s8, v160
	global_load_lds_dwordx4 v[8:9], off
	v_lshl_add_u64 v[4:5], v[4:5], 0, s[64:65]
	s_mov_b32 m0, s8
	v_readfirstlane_b32 s8, v161
	global_load_lds_dwordx4 v[4:5], off
	v_lshl_add_u64 v[4:5], v[6:7], 0, s[56:57]
	s_mov_b32 m0, s8
	v_readfirstlane_b32 s8, v162
	global_load_lds_dwordx4 v[4:5], off
	v_lshl_add_u64 v[4:5], v[6:7], 0, s[58:59]
	s_mov_b32 m0, s8
	v_readfirstlane_b32 s8, v163
	global_load_lds_dwordx4 v[4:5], off
	v_lshl_add_u64 v[4:5], v[6:7], 0, s[60:61]
	s_mov_b32 m0, s8
	v_readfirstlane_b32 s8, v164
	global_load_lds_dwordx4 v[4:5], off
	v_lshl_add_u64 v[4:5], v[6:7], 0, s[64:65]
	s_mov_b32 m0, s8
	s_lshl_b32 s9, s9, 4
	global_load_lds_dwordx4 v[4:5], off
	ds_read_b128 v[36:39], v165
	ds_read_b128 v[64:67], v165 offset:2048
	ds_read_b128 v[44:47], v166 offset:22528
	ds_read_b128 v[48:51], v166 offset:24576
	ds_read_b128 v[52:55], v166 offset:26624
	ds_read_b128 v[56:59], v166 offset:28672
	ds_read_b128 v[68:71], v166 offset:30720
	ds_read_b128 v[60:63], v167
	ds_read_b128 v[94:97], v167 offset:2048
	ds_read_b128 v[98:101], v168 offset:16384
	ds_read_b128 v[40:43], v168 offset:18432
	ds_read_b128 v[174:177], v168 offset:20480
	ds_read_b128 v[178:181], v168 offset:22528
	ds_read_b128 v[182:185], v168 offset:24576
	ds_read_b128 v[186:189], v168 offset:26624
	ds_read_b128 v[190:193], v168 offset:28672
	ds_read_b128 v[194:197], v168 offset:30720
	s_waitcnt vmcnt(0)
	s_barrier
	ds_read_b128 v[198:201], v165 offset:32768
	ds_read_b128 v[202:205], v165 offset:34816
	ds_read_b128 v[206:209], v166 offset:49152
	ds_read_b128 v[210:213], v166 offset:51200
	ds_read_b128 v[214:217], v166 offset:61440
	ds_read_b128 v[218:221], v166 offset:53248
	ds_read_b128 v[222:225], v166 offset:59392
	ds_read_b128 v[226:229], v166 offset:55296
	ds_read_b128 v[230:233], v166 offset:57344
	ds_read_b128 v[234:237], v166 offset:63488
	ds_read_b128 v[242:245], v167 offset:32768
	s_waitcnt lgkmcnt(0)
	v_mfma_f32_16x16x32_bf16 v[4:7], v[64:67], v[56:59], 0
	s_and_b32 s9, s9, 0x3f80
	s_lshl_b32 s28, s10, 8
	v_mov_b32_e32 v93, v72
	v_mfma_f32_16x16x32_bf16 v[4:7], v[94:97], v[190:193], v[4:7]
	v_add_u32_e32 v73, s9, v109
	v_add_u32_e32 v85, s9, v111
	s_lshl_b32 s8, s10, 7
	v_mfma_f32_16x16x32_bf16 v[16:19], v[202:205], v[214:217], v[4:7]
	v_mfma_f32_16x16x32_bf16 v[4:7], v[64:67], v[52:55], 0
	v_mfma_f32_16x16x32_bf16 v[4:7], v[94:97], v[186:189], v[4:7]
	v_mfma_f32_16x16x32_bf16 v[24:27], v[202:205], v[222:225], v[4:7]
	v_mfma_f32_16x16x32_bf16 v[4:7], v[64:67], v[48:51], 0
	v_mfma_f32_16x16x32_bf16 v[4:7], v[94:97], v[182:185], v[4:7]
	v_mfma_f32_16x16x32_bf16 v[20:23], v[202:205], v[230:233], v[4:7]
	v_mfma_f32_16x16x32_bf16 v[4:7], v[64:67], v[44:47], 0
	v_mfma_f32_16x16x32_bf16 v[4:7], v[94:97], v[178:181], v[4:7]
	v_mfma_f32_16x16x32_bf16 v[12:15], v[202:205], v[226:229], v[4:7]
	v_mfma_f32_16x16x32_bf16 v[4:7], v[64:67], v[32:35], 0
	v_mfma_f32_16x16x32_bf16 v[4:7], v[94:97], v[174:177], v[4:7]
	v_mfma_f32_16x16x32_bf16 v[8:11], v[202:205], v[218:221], v[4:7]
	v_mfma_f32_16x16x32_bf16 v[4:7], v[64:67], v[28:31], 0
	v_mfma_f32_16x16x32_bf16 v[4:7], v[94:97], v[40:43], v[4:7]
	v_mfma_f32_16x16x32_bf16 v[28:31], v[36:39], v[28:31], 0
	v_mfma_f32_16x16x32_bf16 v[28:31], v[60:63], v[40:43], v[28:31]
	ds_read_b128 v[40:43], v167 offset:34816
	v_mfma_f32_16x16x32_bf16 v[4:7], v[202:205], v[210:213], v[4:7]
	v_mfma_f32_16x16x32_bf16 v[210:213], v[198:201], v[210:213], v[28:31]
	v_mfma_f32_16x16x32_bf16 v[28:31], v[36:39], v[32:35], 0
	v_mfma_f32_16x16x32_bf16 v[28:31], v[60:63], v[174:177], v[28:31]
	ds_read_b128 v[174:177], v168 offset:49152
	v_mfma_f32_16x16x32_bf16 v[32:35], v[198:201], v[218:221], v[28:31]
	v_mfma_f32_16x16x32_bf16 v[28:31], v[36:39], v[44:47], 0
	v_mfma_f32_16x16x32_bf16 v[28:31], v[60:63], v[178:181], v[28:31]
	v_mfma_f32_16x16x32_bf16 v[178:181], v[198:201], v[226:229], v[28:31]
	s_nop 6
	ds_read_b128 v[28:31], v168 offset:51200
	v_mfma_f32_16x16x32_bf16 v[44:47], v[36:39], v[48:51], 0
	v_mfma_f32_16x16x32_bf16 v[44:47], v[60:63], v[182:185], v[44:47]
	v_mfma_f32_16x16x32_bf16 v[182:185], v[198:201], v[230:233], v[44:47]
	s_nop 6
	ds_read_b128 v[44:47], v168 offset:53248
	v_mfma_f32_16x16x32_bf16 v[48:51], v[36:39], v[52:55], 0
	v_mfma_f32_16x16x32_bf16 v[48:51], v[60:63], v[186:189], v[48:51]
	v_mfma_f32_16x16x32_bf16 v[186:189], v[198:201], v[222:225], v[48:51]
	s_nop 6
	ds_read_b128 v[48:51], v168 offset:55296
	v_mfma_f32_16x16x32_bf16 v[52:55], v[36:39], v[56:59], 0
	v_mfma_f32_16x16x32_bf16 v[52:55], v[60:63], v[190:193], v[52:55]
	v_mfma_f32_16x16x32_bf16 v[190:193], v[198:201], v[214:217], v[52:55]
	s_nop 6
	ds_read_b128 v[52:55], v168 offset:57344
	ds_read_b128 v[56:59], v168 offset:59392
	v_mfma_f32_16x16x32_bf16 v[238:241], v[36:39], v[0:3], 0
	v_mfma_f32_16x16x32_bf16 v[238:241], v[60:63], v[98:101], v[238:241]
	v_mfma_f32_16x16x32_bf16 v[36:39], v[36:39], v[68:71], 0
	v_mfma_f32_16x16x32_bf16 v[36:39], v[60:63], v[194:197], v[36:39]
	ds_read_b128 v[60:63], v168 offset:61440
	v_mfma_f32_16x16x32_bf16 v[0:3], v[64:67], v[0:3], 0
	v_mfma_f32_16x16x32_bf16 v[64:67], v[64:67], v[68:71], 0
	ds_read_b128 v[68:71], v168 offset:63488
	s_barrier
	v_mfma_f32_16x16x32_bf16 v[238:241], v[198:201], v[206:209], v[238:241]
	v_mfma_f32_16x16x32_bf16 v[36:39], v[198:201], v[234:237], v[36:39]
	v_mfma_f32_16x16x32_bf16 v[0:3], v[94:97], v[98:101], v[0:3]
	v_mfma_f32_16x16x32_bf16 v[64:67], v[94:97], v[194:197], v[64:67]
	s_waitcnt lgkmcnt(0)
	v_mfma_f32_16x16x32_bf16 v[94:97], v[242:245], v[174:177], v[238:241]
	v_mfma_f32_16x16x32_bf16 v[98:101], v[242:245], v[28:31], v[210:213]
	s_nop 7
	ds_write2_b32 v171, v97, v101 offset0:128 offset1:144
	v_mfma_f32_16x16x32_bf16 v[32:35], v[242:245], v[44:47], v[32:35]
	ds_write2_b32 v171, v96, v100 offset1:16
	v_mfma_f32_16x16x32_bf16 v[178:181], v[242:245], v[48:51], v[178:181]
	s_nop 7
	ds_write2_b32 v171, v35, v181 offset0:160 offset1:176
	v_mfma_f32_16x16x32_bf16 v[182:185], v[242:245], v[52:55], v[182:185]
	ds_write2_b32 v171, v34, v180 offset0:32 offset1:48
	v_mfma_f32_16x16x32_bf16 v[186:189], v[242:245], v[56:59], v[186:189]
	s_nop 7
	ds_write2_b32 v171, v185, v189 offset0:192 offset1:208
	v_mfma_f32_16x16x32_bf16 v[190:193], v[242:245], v[60:63], v[190:193]
	ds_write2_b32 v171, v184, v188 offset0:64 offset1:80
	v_mfma_f32_16x16x32_bf16 v[36:39], v[242:245], v[68:71], v[36:39]
	ds_write2_b32 v102, v183, v187 offset0:192 offset1:208
	s_nop 4
	ds_write2st64_b32 v103, v192, v193 offset0:4 offset1:6
	s_nop 0
	ds_write2st64_b32 v104, v38, v39 offset0:4 offset1:6
	ds_write2_b32 v102, v182, v186 offset0:64 offset1:80
	ds_write2_b32 v102, v33, v179 offset0:160 offset1:176
	ds_write2_b32 v102, v32, v178 offset0:32 offset1:48
	ds_write2_b32 v102, v95, v99 offset0:128 offset1:144
	ds_write2_b32 v102, v94, v98 offset1:16
	ds_write2st64_b32 v103, v190, v191 offset1:2
	ds_write2st64_b32 v104, v36, v37 offset1:2
	ds_read_b128 v[32:35], v110 offset:16
	ds_read_b128 v[36:39], v110
	ds_read_b128 v[94:97], v108 offset:16
	v_mfma_f32_16x16x32_bf16 v[8:11], v[40:43], v[44:47], v[8:11]
	v_mfma_f32_16x16x32_bf16 v[12:15], v[40:43], v[48:51], v[12:15]
	ds_read_b128 v[46:49], v108
	ds_read_b128 v[98:101], v106 offset:16
	v_mfma_f32_16x16x32_bf16 v[4:7], v[40:43], v[28:31], v[4:7]
	v_mfma_f32_16x16x32_bf16 v[20:23], v[40:43], v[52:55], v[20:23]
	v_add_u32_e32 v53, s9, v107
	v_add_lshl_u32 v52, s8, v105, 2
	v_mfma_f32_16x16x32_bf16 v[28:31], v[40:43], v[56:59], v[24:27]
	ds_read_b128 v[54:57], v106
	v_mfma_f32_16x16x32_bf16 v[16:19], v[40:43], v[60:63], v[16:19]
	ds_read_b128 v[58:61], v77 offset:16
	v_mfma_f32_16x16x32_bf16 v[64:67], v[202:205], v[234:237], v[64:67]
	v_mfma_f32_16x16x32_bf16 v[24:27], v[40:43], v[68:71], v[64:67]
	s_nop 6
	ds_read_b128 v[62:65], v77
	v_mfma_f32_16x16x32_bf16 v[0:3], v[202:205], v[206:209], v[0:3]
	v_mfma_f32_16x16x32_bf16 v[0:3], v[40:43], v[174:177], v[0:3]
	v_add_u32_e32 v42, s9, v105
	v_lshlrev_b32_e32 v40, 11, v42
	v_mov_b32_e32 v41, v72
	v_lshl_add_u64 v[40:41], s[48:49], 0, v[40:41]
	v_lshl_add_u64 v[40:41], v[40:41], 0, s[28:29]
	v_lshl_add_u64 v[50:51], v[40:41], 0, v[92:93]
	v_lshlrev_b32_e32 v40, 12, v42
	v_mov_b32_e32 v41, v72
	v_lshl_add_u64 v[40:41], s[36:37], 0, v[40:41]
	v_lshl_add_u64 v[40:41], v[40:41], 0, s[28:29]
	v_lshl_add_u64 v[70:71], v[40:41], 0, v[92:93]
	v_lshlrev_b32_e32 v40, 12, v53
	v_mov_b32_e32 v41, v72
	v_lshl_add_u64 v[40:41], s[36:37], 0, v[40:41]
	v_lshl_add_u64 v[40:41], v[40:41], 0, s[28:29]
	v_lshl_add_u64 v[186:187], v[40:41], 0, v[92:93]
	v_lshlrev_b32_e32 v40, 12, v73
	v_mov_b32_e32 v41, v72
	v_lshl_add_u64 v[40:41], s[36:37], 0, v[40:41]
	v_lshl_add_u64 v[40:41], v[40:41], 0, s[28:29]
	v_lshl_add_u64 v[188:189], v[40:41], 0, v[92:93]
	v_lshlrev_b32_e32 v40, 12, v85
	v_mov_b32_e32 v41, v72
	v_lshl_add_u64 v[40:41], s[36:37], 0, v[40:41]
	v_lshl_add_u64 v[40:41], v[40:41], 0, s[28:29]
	v_lshl_add_u64 v[44:45], v[40:41], 0, v[92:93]
	global_load_dwordx4 v[40:43], v[44:45], off
	global_load_dwordx4 v[66:69], v[188:189], off
	global_load_dwordx4 v[174:177], v[186:187], off
	global_load_dwordx4 v[178:181], v[70:71], off
	global_load_dwordx4 v[182:185], v[50:51], off
	s_waitcnt vmcnt(0)
	v_and_b32_e32 v191, 0xffff0000, v182
	global_load_dword v50, v52, s[54:55]
	v_lshlrev_b32_e32 v190, 16, v182
	v_lshlrev_b32_e32 v182, 16, v179
	s_waitcnt vmcnt(0) lgkmcnt(0)
	v_add_f32_e32 v62, v62, v50
	v_add_f32_e32 v63, v63, v50
	v_add_f32_e32 v64, v64, v50
	v_add_f32_e32 v65, v65, v50
	v_add_f32_e32 v58, v58, v50
	v_add_f32_e32 v59, v59, v50
	v_add_f32_e32 v51, v61, v50
	v_add_f32_e32 v50, v60, v50
	v_and_b32_e32 v61, 0xffff0000, v185
	v_lshlrev_b32_e32 v60, 16, v185
	v_mul_f32_e32 v62, v62, v190
	v_mul_f32_e32 v63, v63, v191
	v_and_b32_e32 v191, 0xffff0000, v178
	v_lshlrev_b32_e32 v190, 16, v178
	v_mul_f32_e32 v50, v50, v60
	v_mul_f32_e32 v51, v51, v61
	v_and_b32_e32 v61, 0xffff0000, v181
	v_lshlrev_b32_e32 v60, 16, v181
	v_mul_f32_e32 v62, v62, v190
	v_mul_f32_e32 v63, v63, v191
	v_and_b32_e32 v191, 0xffff0000, v183
	v_lshlrev_b32_e32 v190, 16, v183
	v_and_b32_e32 v183, 0xffff0000, v179
	v_and_b32_e32 v179, 0xffff0000, v184
	v_lshlrev_b32_e32 v178, 16, v184
	v_mul_f32_e32 v50, v50, v60
	v_mul_f32_e32 v51, v51, v61
	v_mul_f32_e32 v64, v64, v190
	v_mul_f32_e32 v65, v65, v191
	v_mul_f32_e32 v58, v58, v178
	v_mul_f32_e32 v59, v59, v179
	v_and_b32_e32 v179, 0xffff0000, v180
	v_lshlrev_b32_e32 v178, 16, v180
	v_mul_f32_e32 v64, v64, v182
	v_mul_f32_e32 v65, v65, v183
	v_mul_f32_e32 v58, v58, v178
	v_mul_f32_e32 v59, v59, v179
	v_bfe_u32 v87, v59, 16, 1
	v_bfe_u32 v89, v58, 16, 1
	v_bfe_u32 v91, v65, 16, 1
	v_bfe_u32 v173, v64, 16, 1
	v_cvt_pk_bf16_f32 v61, v50, v51
	v_lshlrev_b32_e32 v50, 11, v53
	v_mov_b32_e32 v51, v72
	v_add3_u32 v64, v64, v173, s84
	v_add3_u32 v65, v65, v91, s84
	v_add3_u32 v58, v58, v89, s84
	v_add3_u32 v59, v59, v87, s84
	v_lshl_add_u64 v[50:51], s[48:49], 0, v[50:51]
	v_perm_b32 v60, v59, v58, s85
	v_perm_b32 v59, v65, v64, s85
	v_cvt_pk_bf16_f32 v58, v62, v63
	v_lshl_add_u64 v[50:51], v[50:51], 0, s[28:29]
	global_store_dwordx4 v[70:71], v[58:61], off
	v_lshl_add_u64 v[50:51], v[50:51], 0, v[92:93]
	global_load_dwordx4 v[58:61], v[50:51], off
	v_and_b32_e32 v63, 0xffff0000, v174
	global_load_dword v50, v52, s[54:55] offset:16
	v_lshlrev_b32_e32 v62, 16, v174
	v_and_b32_e32 v65, 0xffff0000, v175
	v_lshlrev_b32_e32 v64, 16, v175
	v_and_b32_e32 v71, 0xffff0000, v176
	v_lshlrev_b32_e32 v70, 16, v176
	v_add_lshl_u32 v87, s8, v74, 2
	s_waitcnt vmcnt(1)
	v_and_b32_e32 v175, 0xffff0000, v58
	v_lshlrev_b32_e32 v174, 16, v58
	s_waitcnt vmcnt(0)
	v_add_f32_e32 v54, v54, v50
	v_add_f32_e32 v55, v55, v50
	v_add_f32_e32 v56, v56, v50
	v_add_f32_e32 v57, v57, v50
	v_mul_f32_e32 v54, v54, v174
	v_mul_f32_e32 v55, v55, v175
	v_and_b32_e32 v179, 0xffff0000, v59
	v_lshlrev_b32_e32 v178, 16, v59
	v_add_f32_e32 v58, v98, v50
	v_add_f32_e32 v59, v99, v50
	v_mul_f32_e32 v54, v54, v62
	v_mul_f32_e32 v55, v55, v63
	v_add_f32_e32 v51, v101, v50
	v_add_f32_e32 v50, v100, v50
	v_and_b32_e32 v63, 0xffff0000, v61
	v_lshlrev_b32_e32 v62, 16, v61
	v_and_b32_e32 v99, 0xffff0000, v60
	v_lshlrev_b32_e32 v98, 16, v60
	v_mul_f32_e32 v50, v50, v62
	v_mul_f32_e32 v51, v51, v63
	v_and_b32_e32 v61, 0xffff0000, v177
	v_lshlrev_b32_e32 v60, 16, v177
	v_mul_f32_e32 v56, v56, v178
	v_mul_f32_e32 v57, v57, v179
	v_mul_f32_e32 v50, v50, v60
	v_mul_f32_e32 v51, v51, v61
	v_mul_f32_e32 v58, v58, v98
	v_mul_f32_e32 v59, v59, v99
	v_mul_f32_e32 v56, v56, v64
	v_mul_f32_e32 v57, v57, v65
	v_mul_f32_e32 v58, v58, v70
	v_mul_f32_e32 v59, v59, v71
	v_bfe_u32 v63, v57, 16, 1
	v_bfe_u32 v61, v59, 16, 1
	v_bfe_u32 v62, v58, 16, 1
	v_bfe_u32 v64, v56, 16, 1
	v_bfe_u32 v65, v55, 16, 1
	v_bfe_u32 v70, v54, 16, 1
	v_add3_u32 v63, v57, v63, s84
	v_cvt_pk_bf16_f32 v57, v50, v51
	v_lshlrev_b32_e32 v50, 11, v73
	v_mov_b32_e32 v51, v72
	v_add3_u32 v54, v54, v70, s84
	v_add3_u32 v65, v55, v65, s84
	v_add3_u32 v55, v56, v64, s84
	v_add3_u32 v56, v58, v62, s84
	v_add3_u32 v58, v59, v61, s84
	v_lshl_add_u64 v[50:51], s[48:49], 0, v[50:51]
	v_perm_b32 v56, v58, v56, s85
	v_perm_b32 v55, v63, v55, s85
	v_perm_b32 v54, v65, v54, s85
	v_lshl_add_u64 v[50:51], v[50:51], 0, s[28:29]
	global_store_dwordx4 v[186:187], v[54:57], off
	v_lshl_add_u64 v[50:51], v[50:51], 0, v[92:93]
	global_load_dwordx4 v[54:57], v[50:51], off
	v_and_b32_e32 v61, 0xffff0000, v66
	global_load_dword v50, v52, s[54:55] offset:32
	v_lshlrev_b32_e32 v60, 16, v66
	v_and_b32_e32 v63, 0xffff0000, v67
	v_lshlrev_b32_e32 v62, 16, v67
	v_and_b32_e32 v65, 0xffff0000, v68
	v_lshlrev_b32_e32 v64, 16, v68
	v_and_b32_e32 v67, 0xffff0000, v69
	v_lshlrev_b32_e32 v66, 16, v69
	v_mov_b32_e32 v59, v72
	v_lshlrev_b32_e32 v58, 11, v85
	v_lshl_add_u64 v[58:59], s[48:49], 0, v[58:59]
	v_lshl_add_u64 v[58:59], v[58:59], 0, s[28:29]
	v_lshl_add_u64 v[58:59], v[58:59], 0, v[92:93]
	v_add_u32_e32 v73, s9, v113
	v_add_u32_e32 v85, s9, v114
	s_waitcnt vmcnt(1)
	v_and_b32_e32 v69, 0xffff0000, v54
	v_lshlrev_b32_e32 v68, 16, v54
	s_waitcnt vmcnt(0)
	v_add_f32_e32 v46, v46, v50
	v_add_f32_e32 v47, v47, v50
	v_add_f32_e32 v48, v48, v50
	v_add_f32_e32 v49, v49, v50
	v_and_b32_e32 v71, 0xffff0000, v55
	v_lshlrev_b32_e32 v70, 16, v55
	v_add_f32_e32 v54, v94, v50
	v_add_f32_e32 v55, v95, v50
	v_and_b32_e32 v95, 0xffff0000, v56
	v_lshlrev_b32_e32 v94, 16, v56
	v_add_f32_e32 v51, v97, v50
	v_add_f32_e32 v50, v96, v50
	v_and_b32_e32 v97, 0xffff0000, v57
	v_lshlrev_b32_e32 v96, 16, v57
	v_mul_f32_e32 v46, v46, v68
	v_mul_f32_e32 v47, v47, v69
	v_mul_f32_e32 v48, v48, v70
	v_mul_f32_e32 v49, v49, v71
	v_mul_f32_e32 v54, v54, v94
	v_mul_f32_e32 v55, v55, v95
	v_mul_f32_e32 v50, v50, v96
	v_mul_f32_e32 v51, v51, v97
	v_mul_f32_e32 v46, v46, v60
	v_mul_f32_e32 v47, v47, v61
	v_mul_f32_e32 v48, v48, v62
	v_mul_f32_e32 v49, v49, v63
	v_mul_f32_e32 v54, v54, v64
	v_mul_f32_e32 v55, v55, v65
	v_mul_f32_e32 v50, v50, v66
	v_mul_f32_e32 v51, v51, v67
	v_bfe_u32 v57, v55, 16, 1
	v_bfe_u32 v53, v51, 16, 1
	v_bfe_u32 v56, v50, 16, 1
	v_bfe_u32 v60, v54, 16, 1
	v_bfe_u32 v61, v49, 16, 1
	v_bfe_u32 v62, v48, 16, 1
	v_bfe_u32 v63, v47, 16, 1
	v_bfe_u32 v64, v46, 16, 1
	v_add3_u32 v46, v46, v64, s84
	v_add3_u32 v63, v47, v63, s84
	v_add3_u32 v47, v48, v62, s84
	v_add3_u32 v61, v49, v61, s84
	v_add3_u32 v48, v54, v60, s84
	v_add3_u32 v54, v55, v57, s84
	v_add3_u32 v49, v50, v56, s84
	v_add3_u32 v50, v51, v53, s84
	v_perm_b32 v49, v50, v49, s85
	v_perm_b32 v48, v54, v48, s85
	v_perm_b32 v47, v61, v47, s85
	v_perm_b32 v46, v63, v46, s85
	global_store_dwordx4 v[188:189], v[46:49], off
	global_load_dwordx4 v[54:57], v[58:59], off
	v_and_b32_e32 v63, 0xffff0000, v41
	global_load_dword v58, v52, s[54:55] offset:48
	v_add_u32_e32 v48, s9, v74
	v_mov_b32_e32 v47, v72
	v_mov_b32_e32 v49, v72
	v_lshlrev_b32_e32 v46, 11, v48
	v_lshlrev_b32_e32 v48, 12, v48
	v_lshl_add_u64 v[46:47], s[48:49], 0, v[46:47]
	v_lshl_add_u64 v[48:49], s[36:37], 0, v[48:49]
	v_lshl_add_u64 v[46:47], v[46:47], 0, s[28:29]
	v_lshl_add_u64 v[60:61], v[48:49], 0, s[28:29]
	v_lshl_add_u64 v[48:49], v[46:47], 0, v[92:93]
	v_lshl_add_u64 v[46:47], v[60:61], 0, v[92:93]
	v_and_b32_e32 v61, 0xffff0000, v40
	v_lshlrev_b32_e32 v60, 16, v40
	v_lshlrev_b32_e32 v62, 16, v41
	v_and_b32_e32 v41, 0xffff0000, v42
	v_lshlrev_b32_e32 v40, 16, v42
	v_and_b32_e32 v65, 0xffff0000, v43
	v_lshlrev_b32_e32 v64, 16, v43
	v_add_u32_e32 v53, s9, v112
	v_mov_b32_e32 v51, v72
	v_lshlrev_b32_e32 v50, 12, v53
	s_waitcnt vmcnt(1)
	v_and_b32_e32 v43, 0xffff0000, v54
	v_lshlrev_b32_e32 v42, 16, v54
	s_waitcnt vmcnt(0)
	v_add_f32_e32 v36, v36, v58
	v_add_f32_e32 v37, v37, v58
	v_add_f32_e32 v38, v38, v58
	v_add_f32_e32 v39, v39, v58
	v_and_b32_e32 v67, 0xffff0000, v55
	v_lshlrev_b32_e32 v66, 16, v55
	v_add_f32_e32 v32, v32, v58
	v_add_f32_e32 v33, v33, v58
	v_and_b32_e32 v55, 0xffff0000, v56
	v_lshlrev_b32_e32 v54, 16, v56
	v_add_f32_e32 v34, v34, v58
	v_add_f32_e32 v35, v35, v58
	v_and_b32_e32 v59, 0xffff0000, v57
	v_lshlrev_b32_e32 v58, 16, v57
	v_mul_f32_e32 v36, v36, v42
	v_mul_f32_e32 v37, v37, v43
	v_mul_f32_e32 v38, v38, v66
	v_mul_f32_e32 v39, v39, v67
	v_mul_f32_e32 v32, v32, v54
	v_mul_f32_e32 v33, v33, v55
	v_mul_f32_e32 v34, v34, v58
	v_mul_f32_e32 v35, v35, v59
	v_mul_f32_e32 v36, v36, v60
	v_mul_f32_e32 v37, v37, v61
	v_mul_f32_e32 v38, v38, v62
	v_mul_f32_e32 v39, v39, v63
	v_mul_f32_e32 v32, v32, v40
	v_mul_f32_e32 v33, v33, v41
	v_mul_f32_e32 v34, v34, v64
	v_mul_f32_e32 v35, v35, v65
	v_cvt_pk_bf16_f32 v35, v34, v35
	v_cvt_pk_bf16_f32 v34, v32, v33
	v_cvt_pk_bf16_f32 v33, v38, v39
	v_cvt_pk_bf16_f32 v32, v36, v37
	global_store_dwordx4 v[44:45], v[32:35], off
	ds_write2_b32 v171, v23, v31 offset0:192 offset1:208
	ds_write2_b32 v171, v22, v30 offset0:64 offset1:80
	ds_write2_b32 v102, v21, v29 offset0:192 offset1:208
	ds_write2_b32 v171, v11, v15 offset0:160 offset1:176
	ds_write2_b32 v171, v10, v14 offset0:32 offset1:48
	ds_write2_b32 v171, v3, v7 offset0:128 offset1:144
	ds_write2_b32 v171, v2, v6 offset1:16
	ds_write2st64_b32 v103, v18, v19 offset0:4 offset1:6
	ds_write2st64_b32 v104, v26, v27 offset0:4 offset1:6
	ds_write2_b32 v102, v20, v28 offset0:64 offset1:80
	ds_write2_b32 v102, v9, v13 offset0:160 offset1:176
	ds_write2_b32 v102, v8, v12 offset0:32 offset1:48
	v_lshl_add_u64 v[8:9], s[36:37], 0, v[50:51]
	v_lshl_add_u64 v[8:9], v[8:9], 0, s[28:29]
	v_lshl_add_u64 v[58:59], v[8:9], 0, v[92:93]
	v_lshlrev_b32_e32 v8, 12, v73
	v_mov_b32_e32 v9, v72
	v_lshl_add_u64 v[8:9], s[36:37], 0, v[8:9]
	v_lshl_add_u64 v[8:9], v[8:9], 0, s[28:29]
	v_lshl_add_u64 v[60:61], v[8:9], 0, v[92:93]
	v_lshlrev_b32_e32 v8, 12, v85
	v_mov_b32_e32 v9, v72
	v_lshl_add_u64 v[8:9], s[36:37], 0, v[8:9]
	ds_write2_b32 v102, v1, v5 offset0:128 offset1:144
	ds_write2_b32 v102, v0, v4 offset1:16
	ds_write2st64_b32 v103, v16, v17 offset1:2
	ds_write2st64_b32 v104, v24, v25 offset1:2
	v_lshl_add_u64 v[8:9], v[8:9], 0, s[28:29]
	v_lshl_add_u64 v[8:9], v[8:9], 0, v[92:93]
	ds_read_b128 v[0:3], v110 offset:16
	ds_read_b128 v[4:7], v110
	ds_read_b128 v[10:13], v108 offset:16
	ds_read_b128 v[14:17], v108
	ds_read_b128 v[18:21], v106 offset:16
	ds_read_b128 v[22:25], v106
	ds_read_b128 v[26:29], v77 offset:16
	ds_read_b128 v[30:33], v77
	global_load_dwordx4 v[34:37], v[8:9], off
	global_load_dwordx4 v[38:41], v[60:61], off
	global_load_dwordx4 v[42:45], v[58:59], off
	global_load_dwordx4 v[54:57], v[46:47], off
	v_lshlrev_b32_e32 v62, 11, v53
	global_load_dwordx4 v[48:51], v[48:49], off
	v_mov_b32_e32 v63, v72
	global_load_dword v52, v52, s[54:55] offset:64
	v_lshl_add_u64 v[62:63], s[48:49], 0, v[62:63]
	v_lshl_add_u64 v[62:63], v[62:63], 0, s[28:29]
	v_lshl_add_u64 v[62:63], v[62:63], 0, v[92:93]
	s_waitcnt vmcnt(2)
	v_and_b32_e32 v67, 0xffff0000, v54
	v_lshlrev_b32_e32 v66, 16, v54
	s_waitcnt vmcnt(1)
	v_and_b32_e32 v65, 0xffff0000, v48
	v_lshlrev_b32_e32 v64, 16, v48
	s_waitcnt vmcnt(0) lgkmcnt(0)
	v_add_f32_e32 v30, v30, v52
	v_add_f32_e32 v31, v31, v52
	v_add_f32_e32 v32, v32, v52
	v_add_f32_e32 v33, v33, v52
	v_and_b32_e32 v69, 0xffff0000, v49
	v_lshlrev_b32_e32 v68, 16, v49
	v_and_b32_e32 v49, 0xffff0000, v55
	v_lshlrev_b32_e32 v48, 16, v55
	v_add_f32_e32 v26, v26, v52
	v_add_f32_e32 v27, v27, v52
	v_and_b32_e32 v55, 0xffff0000, v50
	v_lshlrev_b32_e32 v54, 16, v50
	v_add_f32_e32 v28, v28, v52
	v_add_f32_e32 v29, v29, v52
	v_and_b32_e32 v53, 0xffff0000, v51
	v_lshlrev_b32_e32 v52, 16, v51
	v_and_b32_e32 v71, 0xffff0000, v56
	v_lshlrev_b32_e32 v70, 16, v56
	v_and_b32_e32 v51, 0xffff0000, v57
	v_lshlrev_b32_e32 v50, 16, v57
	v_mul_f32_e32 v30, v30, v64
	v_mul_f32_e32 v31, v31, v65
	v_mul_f32_e32 v32, v32, v68
	v_mul_f32_e32 v33, v33, v69
	v_mul_f32_e32 v26, v26, v54
	v_mul_f32_e32 v27, v27, v55
	v_mul_f32_e32 v28, v28, v52
	v_mul_f32_e32 v29, v29, v53
	v_mul_f32_e32 v30, v30, v66
	v_mul_f32_e32 v31, v31, v67
	v_mul_f32_e32 v32, v32, v48
	v_mul_f32_e32 v33, v33, v49
	v_mul_f32_e32 v26, v26, v70
	v_mul_f32_e32 v27, v27, v71
	v_mul_f32_e32 v28, v28, v50
	v_mul_f32_e32 v29, v29, v51
	v_bfe_u32 v54, v31, 16, 1
	v_bfe_u32 v55, v30, 16, 1
	v_add3_u32 v30, v30, v55, s84
	v_add3_u32 v31, v31, v54, s84
	v_cvt_pk_bf16_f32 v29, v28, v29
	v_cvt_pk_bf16_f32 v28, v26, v27
	v_cvt_pk_bf16_f32 v27, v32, v33
	v_perm_b32 v26, v31, v30, s85
	global_store_dwordx4 v[46:47], v[26:29], off
	global_load_dword v30, v87, s[54:55] offset:16
	v_and_b32_e32 v47, 0xffff0000, v42
	global_load_dwordx4 v[26:29], v[62:63], off
	v_lshlrev_b32_e32 v46, 16, v42
	v_and_b32_e32 v49, 0xffff0000, v43
	v_lshlrev_b32_e32 v48, 16, v43
	v_and_b32_e32 v43, 0xffff0000, v44
	v_lshlrev_b32_e32 v42, 16, v44
	v_and_b32_e32 v51, 0xffff0000, v45
	v_lshlrev_b32_e32 v50, 16, v45
	v_mov_b32_e32 v33, v72
	v_lshlrev_b32_e32 v32, 11, v73
	v_lshl_add_u64 v[32:33], s[48:49], 0, v[32:33]
	v_lshl_add_u64 v[32:33], v[32:33], 0, s[28:29]
	v_lshl_add_u64 v[32:33], v[32:33], 0, v[92:93]
	s_waitcnt vmcnt(1)
	v_add_f32_e32 v22, v22, v30
	v_add_f32_e32 v23, v23, v30
	v_add_f32_e32 v24, v24, v30
	v_add_f32_e32 v25, v25, v30
	s_waitcnt vmcnt(0)
	v_and_b32_e32 v45, 0xffff0000, v26
	v_lshlrev_b32_e32 v44, 16, v26
	v_and_b32_e32 v53, 0xffff0000, v27
	v_lshlrev_b32_e32 v52, 16, v27
	v_add_f32_e32 v18, v18, v30
	v_add_f32_e32 v19, v19, v30
	v_and_b32_e32 v27, 0xffff0000, v28
	v_lshlrev_b32_e32 v26, 16, v28
	v_add_f32_e32 v20, v20, v30
	v_add_f32_e32 v21, v21, v30
	v_and_b32_e32 v31, 0xffff0000, v29
	v_lshlrev_b32_e32 v30, 16, v29
	v_mul_f32_e32 v22, v22, v44
	v_mul_f32_e32 v23, v23, v45
	v_mul_f32_e32 v24, v24, v52
	v_mul_f32_e32 v25, v25, v53
	v_mul_f32_e32 v18, v18, v26
	v_mul_f32_e32 v19, v19, v27
	v_mul_f32_e32 v20, v20, v30
	v_mul_f32_e32 v21, v21, v31
	v_mul_f32_e32 v22, v22, v46
	v_mul_f32_e32 v23, v23, v47
	v_mul_f32_e32 v24, v24, v48
	v_mul_f32_e32 v25, v25, v49
	v_mul_f32_e32 v18, v18, v42
	v_mul_f32_e32 v19, v19, v43
	v_mul_f32_e32 v20, v20, v50
	v_mul_f32_e32 v21, v21, v51
	v_bfe_u32 v42, v23, 16, 1
	v_bfe_u32 v43, v22, 16, 1
	v_add3_u32 v22, v22, v43, s84
	v_add3_u32 v23, v23, v42, s84
	v_cvt_pk_bf16_f32 v21, v20, v21
	v_cvt_pk_bf16_f32 v20, v18, v19
	v_cvt_pk_bf16_f32 v19, v24, v25
	v_perm_b32 v18, v23, v22, s85
	global_store_dwordx4 v[58:59], v[18:21], off
	global_load_dwordx4 v[18:21], v[32:33], off
	v_and_b32_e32 v27, 0xffff0000, v38
	global_load_dword v22, v87, s[54:55] offset:32
	v_lshlrev_b32_e32 v26, 16, v38
	v_and_b32_e32 v29, 0xffff0000, v39
	v_lshlrev_b32_e32 v28, 16, v39
	v_and_b32_e32 v31, 0xffff0000, v40
	v_lshlrev_b32_e32 v30, 16, v40
	v_and_b32_e32 v33, 0xffff0000, v41
	v_lshlrev_b32_e32 v32, 16, v41
	v_mov_b32_e32 v25, v72
	v_lshlrev_b32_e32 v24, 11, v85
	v_lshl_add_u64 v[24:25], s[48:49], 0, v[24:25]
	v_lshl_add_u64 v[24:25], v[24:25], 0, s[28:29]
	v_lshl_add_u64 v[24:25], v[24:25], 0, v[92:93]
	s_waitcnt vmcnt(1)
	v_and_b32_e32 v39, 0xffff0000, v18
	v_lshlrev_b32_e32 v38, 16, v18
	s_waitcnt vmcnt(0)
	v_add_f32_e32 v14, v14, v22
	v_add_f32_e32 v15, v15, v22
	v_add_f32_e32 v16, v16, v22
	v_add_f32_e32 v17, v17, v22
	v_and_b32_e32 v41, 0xffff0000, v19
	v_lshlrev_b32_e32 v40, 16, v19
	v_add_f32_e32 v10, v10, v22
	v_add_f32_e32 v11, v11, v22
	v_and_b32_e32 v19, 0xffff0000, v20
	v_lshlrev_b32_e32 v18, 16, v20
	v_add_f32_e32 v12, v12, v22
	v_add_f32_e32 v13, v13, v22
	v_and_b32_e32 v23, 0xffff0000, v21
	v_lshlrev_b32_e32 v22, 16, v21
	v_mul_f32_e32 v14, v14, v38
	v_mul_f32_e32 v15, v15, v39
	v_mul_f32_e32 v16, v16, v40
	v_mul_f32_e32 v17, v17, v41
	v_mul_f32_e32 v10, v10, v18
	v_mul_f32_e32 v11, v11, v19
	v_mul_f32_e32 v12, v12, v22
	v_mul_f32_e32 v13, v13, v23
	v_mul_f32_e32 v14, v14, v26
	v_mul_f32_e32 v15, v15, v27
	v_mul_f32_e32 v16, v16, v28
	v_mul_f32_e32 v17, v17, v29
	v_mul_f32_e32 v10, v10, v30
	v_mul_f32_e32 v11, v11, v31
	v_mul_f32_e32 v12, v12, v32
	v_mul_f32_e32 v13, v13, v33
	v_bfe_u32 v26, v15, 16, 1
	v_bfe_u32 v27, v14, 16, 1
	v_add3_u32 v14, v14, v27, s84
	v_add3_u32 v15, v15, v26, s84
	v_cvt_pk_bf16_f32 v13, v12, v13
	v_cvt_pk_bf16_f32 v12, v10, v11
	v_cvt_pk_bf16_f32 v11, v16, v17
	v_perm_b32 v10, v15, v14, s85
	global_store_dwordx4 v[60:61], v[10:13], off
	global_load_dword v14, v87, s[54:55] offset:48
	v_and_b32_e32 v17, 0xffff0000, v34
	global_load_dwordx4 v[10:13], v[24:25], off
	v_lshlrev_b32_e32 v16, 16, v34
	v_and_b32_e32 v19, 0xffff0000, v35
	v_lshlrev_b32_e32 v18, 16, v35
	v_and_b32_e32 v21, 0xffff0000, v36
	v_lshlrev_b32_e32 v20, 16, v36
	v_and_b32_e32 v23, 0xffff0000, v37
	v_lshlrev_b32_e32 v22, 16, v37
	s_waitcnt vmcnt(1)
	v_add_f32_e32 v4, v4, v14
	v_add_f32_e32 v5, v5, v14
	v_add_f32_e32 v6, v6, v14
	v_add_f32_e32 v7, v7, v14
	s_waitcnt vmcnt(0)
	v_and_b32_e32 v25, 0xffff0000, v10
	v_lshlrev_b32_e32 v24, 16, v10
	v_and_b32_e32 v27, 0xffff0000, v11
	v_lshlrev_b32_e32 v26, 16, v11
	v_add_f32_e32 v0, v0, v14
	v_add_f32_e32 v1, v1, v14
	v_and_b32_e32 v11, 0xffff0000, v12
	v_lshlrev_b32_e32 v10, 16, v12
	v_add_f32_e32 v2, v2, v14
	v_add_f32_e32 v3, v3, v14
	v_and_b32_e32 v15, 0xffff0000, v13
	v_lshlrev_b32_e32 v14, 16, v13
	v_mul_f32_e32 v4, v4, v24
	v_mul_f32_e32 v5, v5, v25
	v_mul_f32_e32 v6, v6, v26
	v_mul_f32_e32 v7, v7, v27
	v_mul_f32_e32 v0, v0, v10
	v_mul_f32_e32 v1, v1, v11
	v_mul_f32_e32 v2, v2, v14
	v_mul_f32_e32 v3, v3, v15
	v_mul_f32_e32 v4, v4, v16
	v_mul_f32_e32 v5, v5, v17
	v_mul_f32_e32 v6, v6, v18
	v_mul_f32_e32 v7, v7, v19
	v_mul_f32_e32 v0, v0, v20
	v_mul_f32_e32 v1, v1, v21
	v_mul_f32_e32 v2, v2, v22
	v_mul_f32_e32 v3, v3, v23
	v_cvt_pk_bf16_f32 v3, v2, v3
	v_cvt_pk_bf16_f32 v2, v0, v1
	v_cvt_pk_bf16_f32 v1, v6, v7
	v_cvt_pk_bf16_f32 v0, v4, v5
	global_store_dwordx4 v[8:9], v[0:3], off
	s_cbranch_execnz .LBB0_251

.LBB0_259:
	v_add_u32_e32 v68, s92, v116
	v_add_u32_e32 v70, v68, v120
	ds_read_b128 v[48:51], v70
	ds_read_b128 v[52:55], v70 offset:4096
	ds_read_b128 v[56:59], v70 offset:8192
	ds_read_b128 v[94:97], v70 offset:12288
	v_add_u32_e32 v70, v68, v121
	v_add_u32_e32 v71, v68, v122
	ds_read_b128 v[174:177], v71 offset:12288
	v_add_u32_e32 v68, v68, v123
	ds_read_b128 v[178:181], v68 offset:12288
	s_waitcnt lgkmcnt(0)
	v_mfma_f32_16x16x32_bf16 v[52:55], v[52:55], v[0:3], 0
	v_mfma_f32_16x16x32_bf16 v[98:101], v[56:59], v[0:3], 0
	ds_read_b128 v[56:59], v70 offset:12288
	v_mfma_f32_16x16x32_bf16 v[94:97], v[94:97], v[0:3], 0
	s_waitcnt lgkmcnt(0)
	v_mfma_f32_16x16x32_bf16 v[56:59], v[56:59], v[4:7], v[94:97]
	s_nop 5
	ds_read_b128 v[94:97], v70 offset:8192
	ds_read_b128 v[182:185], v71 offset:8192
	ds_read_b128 v[186:189], v68 offset:8192
	v_mfma_f32_16x16x32_bf16 v[56:59], v[174:177], v[8:11], v[56:59]
	ds_read_b128 v[174:177], v70
	ds_read_b128 v[190:193], v70 offset:4096
	ds_read_b128 v[194:197], v71
	ds_read_b128 v[198:201], v71 offset:4096
	v_mfma_f32_16x16x32_bf16 v[56:59], v[178:181], v[12:15], v[56:59]
	ds_read_b128 v[178:181], v68
	ds_read_b128 v[202:205], v68 offset:4096
	s_waitcnt lgkmcnt(0)
	v_mfma_f32_16x16x32_bf16 v[94:97], v[94:97], v[4:7], v[98:101]
	s_nop 3
	v_exp_f32_e64 v70, -|v56|
	v_exp_f32_e64 v73, -|v57|
	v_max_f32_e32 v68, v56, v56
	v_mfma_f32_16x16x32_bf16 v[48:51], v[48:51], v[0:3], 0
	v_add_f32_e32 v70, 1.0, v70
	v_log_f32_e32 v70, v70
	v_max_f32_e32 v68, 0, v68
	v_mfma_f32_16x16x32_bf16 v[94:97], v[182:185], v[8:11], v[94:97]
	v_add_f32_e32 v68, v68, v70
	v_max_f32_e32 v70, v57, v57
	v_mfma_f32_16x16x32_bf16 v[52:55], v[190:193], v[4:7], v[52:55]
	v_max_f32_e32 v71, 0, v70
	v_add_f32_e32 v70, 1.0, v73
	v_max_f32_e32 v73, v58, v58
	v_mfma_f32_16x16x32_bf16 v[48:51], v[174:177], v[4:7], v[48:51]
	v_max_f32_e32 v193, 0, v73
	v_max_f32_e32 v73, v59, v59
	v_max_f32_e32 v183, 0, v73
	v_mfma_f32_16x16x32_bf16 v[174:177], v[186:189], v[12:15], v[94:97]
	v_log_f32_e32 v191, v70
	v_exp_f32_e64 v70, -|v58|
	v_mfma_f32_16x16x32_bf16 v[52:55], v[198:201], v[8:11], v[52:55]
	v_add_u32_e32 v198, s90, v159
	s_nop 3
	v_exp_f32_e64 v73, -|v174|
	v_exp_f32_e64 v94, -|v175|
	v_mfma_f32_16x16x32_bf16 v[52:55], v[202:205], v[12:15], v[52:55]
	v_exp_f32_e64 v96, -|v177|
	v_add_f32_e32 v73, 1.0, v73
	v_log_f32_e32 v190, v73
	v_max_f32_e32 v73, v175, v175
	v_max_f32_e32 v192, 0, v73
	v_add_f32_e32 v73, 1.0, v94
	v_exp_f32_e64 v94, -|v176|
	s_nop 0
	v_exp_f32_e64 v97, -|v52|
	v_add_f32_e32 v96, 1.0, v96
	v_mfma_f32_16x16x32_bf16 v[48:51], v[194:197], v[8:11], v[48:51]
	v_log_f32_e32 v194, v73
	v_max_f32_e32 v73, v176, v176
	v_log_f32_e32 v96, v96
	v_max_f32_e32 v182, 0, v73
	v_add_f32_e32 v73, 1.0, v94
	v_add_f32_e32 v97, 1.0, v97
	v_log_f32_e32 v94, v73
	v_max_f32_e32 v73, v177, v177
	v_log_f32_e32 v97, v97
	v_max_f32_e32 v73, 0, v73
	v_add_f32_e32 v185, v73, v96
	v_max_f32_e32 v73, v52, v52
	v_exp_f32_e64 v96, -|v54|
	v_max_f32_e32 v73, 0, v73
	v_add_f32_e32 v97, v73, v97
	v_exp_f32_e64 v73, -|v53|
	v_add_f32_e32 v96, 1.0, v96
	v_mfma_f32_16x16x32_bf16 v[48:51], v[178:181], v[12:15], v[48:51]
	v_log_f32_e32 v96, v96
	v_add_f32_e32 v73, 1.0, v73
	v_log_f32_e32 v181, v73
	v_max_f32_e32 v73, v54, v54
	v_max_f32_e32 v73, 0, v73
	v_add_f32_e32 v196, v73, v96
	s_nop 1
	v_exp_f32_e64 v96, -|v48|
	v_exp_f32_e64 v73, -|v55|
	v_exp_f32_e64 v100, -|v50|
	v_add_f32_e32 v70, 1.0, v70
	v_add_f32_e32 v96, 1.0, v96
	v_log_f32_e32 v96, v96
	v_add_f32_e32 v73, 1.0, v73
	v_log_f32_e32 v180, v73
	v_max_f32_e32 v73, v48, v48
	v_max_f32_e32 v73, 0, v73
	v_add_f32_e32 v73, v73, v96
	v_exp_f32_e64 v96, -|v49|
	v_max_f32_e32 v98, v53, v53
	v_log_f32_e32 v195, v70
	v_exp_f32_e64 v70, -|v59|
	v_add_f32_e32 v96, 1.0, v96
	v_log_f32_e32 v101, v96
	v_add_f32_e32 v96, 1.0, v100
	v_max_f32_e32 v179, 0, v98
	v_max_f32_e32 v98, v55, v55
	v_log_f32_e32 v96, v96
	v_max_f32_e32 v178, 0, v98
	v_max_f32_e32 v98, v49, v49
	v_exp_f32_e64 v100, -|v51|
	v_max_f32_e32 v99, 0, v98
	v_max_f32_e32 v98, v50, v50
	v_max_f32_e32 v98, 0, v98
	v_add_f32_e32 v70, 1.0, v70
	v_add_f32_e32 v197, v98, v96
	v_max_f32_e32 v96, v51, v51
	v_log_f32_e32 v95, v70
	v_max_f32_e32 v98, 0, v96
	v_add_f32_e32 v96, 1.0, v100
	v_cmp_lt_u32_e64 s[12:13], v198, v60
	v_max_f32_e32 v70, v174, v174
	v_log_f32_e32 v100, v96
	v_cndmask_b32_e64 v96, 0, -v73, s[12:13]
	v_or_b32_e32 v73, 48, v198
	v_max_f32_e32 v70, 0, v70
	v_or_b32_e32 v188, 33, v198
	v_or_b32_e32 v189, 32, v198
	v_or_b32_e32 v201, 49, v198
	v_cmp_lt_u32_e64 s[14:15], v73, v60
	v_or_b32_e32 v204, 50, v198
	v_add_f32_e32 v70, v70, v190
	v_add_f32_e32 v71, v71, v191
	v_cndmask_b32_e64 v184, 0, -v68, s[14:15]
	v_add_f32_e32 v186, v192, v194
	v_add_f32_e32 v187, v193, v195
	v_cmp_lt_u32_e64 s[16:17], v204, v60
	v_cmp_lt_u32_e32 vcc, v188, v61
	v_cmp_lt_u32_e64 s[18:19], v201, v61
	v_cmp_lt_u32_e64 s[8:9], v189, v60
	v_add_f32_e32 v73, 0, v184
	v_or_b32_e32 v202, 34, v198
	v_or_b32_e32 v203, 51, v198
	v_add_f32_e32 v94, v182, v94
	v_add_f32_e32 v95, v183, v95
	v_cndmask_b32_e64 v183, 0, -v187, s[16:17]
	v_cndmask_b32_e64 v182, 0, -v186, vcc
	v_cndmask_b32_e64 v187, 0, -v71, s[18:19]
	v_cndmask_b32_e64 v186, 0, -v70, s[8:9]
	v_add_f32_e32 v70, v186, v72
	v_add_f32_e32 v71, v187, v73
	v_cmp_lt_u32_e64 s[24:25], v203, v61
	v_cmp_lt_u32_e64 s[20:21], v202, v60
	v_add_f32_e32 v70, v182, v70
	v_add_f32_e32 v71, v183, v71
	v_cndmask_b32_e64 v189, 0, -v95, s[24:25]
	v_cndmask_b32_e64 v188, 0, -v94, s[20:21]
	v_add_f32_e32 v70, v188, v70
	v_add_f32_e32 v71, v189, v71
	ds_bpermute_b32 v95, v85, v71
	v_or_b32_e32 v68, 35, v198
	v_cmp_lt_u32_e64 s[10:11], v68, v61
	ds_bpermute_b32 v191, v87, v71
	v_add_f32_e32 v201, v176, v188
	v_cndmask_b32_e64 v94, 0, -v185, s[10:11]
	s_waitcnt lgkmcnt(0)
	v_add_f32_e32 v70, v94, v70
	v_add_f32_e32 v71, v95, v71
	ds_bpermute_b32 v190, v85, v70
	ds_bpermute_b32 v193, v87, v95
	ds_bpermute_b32 v192, v87, v70
	v_add_f32_e32 v185, v58, v183
	v_cndmask_b32_e64 v58, 0, v95, s[0:1]
	s_waitcnt lgkmcnt(0)
	ds_bpermute_b32 v68, v87, v190
	v_add_f32_e32 v70, v70, v190
	v_add_f32_e32 v71, v71, v191
	v_cndmask_b32_e64 v73, 0, v190, s[0:1]
	v_cndmask_b32_e64 v95, 0, v192, s[22:23]
	v_add_f32_e32 v70, v70, v192
	v_add_f32_e32 v71, v71, v193
	v_add_f32_e32 v73, v73, v95
	s_waitcnt lgkmcnt(0)
	v_cndmask_b32_e64 v95, 0, v68, s[4:5]
	v_add_f32_e32 v194, v70, v68
	v_add_f32_e32 v195, v71, v69
	v_cndmask_b32_e64 v68, 0, v191, s[22:23]
	v_add_f32_e32 v58, v58, v68
	v_cndmask_b32_e64 v68, 0, v193, s[4:5]
	v_mov_b32_e32 v70, v188
	v_add_f32_e32 v188, v58, v68
	v_mov_b32_e32 v58, v69
	v_add_f32_e32 v58, v58, v188
	v_add_f32_e32 v59, v59, v189
	v_add_f32_e32 v202, v177, v94
	v_add_f32_e32 v176, v72, v94
	v_add_f32_e32 v177, v73, v95
	v_mov_b32_e32 v71, v195
	v_add_f32_e32 v68, v58, v59
	v_add_f32_e32 v70, v70, v176
	v_add_f32_e32 v71, v71, v177
	v_add_f32_e32 v68, 0, v68
	v_add_f32_e32 v204, v175, v182
	v_mov_b32_e32 v94, v182
	v_mov_b32_e32 v95, v174
	v_mov_b32_e32 v174, v70
	v_mov_b32_e32 v175, v186
	v_exp_f32_e32 v177, v68
	v_mov_b32_e32 v68, v189
	v_mov_b32_e32 v69, v57
	v_mov_b32_e32 v73, v187
	v_add_f32_e32 v94, v94, v174
	v_add_f32_e32 v95, v95, v175
	v_add_f32_e32 v68, v68, v72
	v_add_f32_e32 v69, v69, v73
	v_pk_mov_b32 v[174:175], v[182:183], v[58:59] op_sel:[1,0]
	v_add_f32_e32 v186, v58, v185
	v_add_f32_e32 v174, v174, v68
	v_add_f32_e32 v175, v175, v69
	v_mov_b32_e32 v57, v187
	v_mov_b32_e32 v185, v174
	v_add_f32_e32 v56, v56, v184
	v_add_f32_e32 v57, v57, v185
	v_add_f32_e32 v59, v68, v186
	v_add_f32_e32 v56, v58, v56
	v_add_f32_e32 v56, v56, v57
	v_exp_f32_e32 v56, v56
	v_exp_f32_e32 v59, v59
	v_add_f32_e32 v68, v174, v175
	v_exp_f32_e32 v68, v68
	v_cndmask_b32_e64 v187, 0, v56, s[14:15]
	v_add_f32_e32 v56, v201, v71
	v_add_f32_e32 v56, v176, v56
	v_exp_f32_e32 v56, v56
	v_add_f32_e32 v57, v202, v71
	v_add_f32_e32 v57, 0, v57
	v_or_b32_e32 v58, 2, v198
	v_cndmask_b32_e64 v189, 0, v56, s[20:21]
	v_or_b32_e32 v56, 16, v198
	v_cndmask_b32_e64 v185, 0, v59, s[16:17]
	v_exp_f32_e32 v188, v57
	v_or_b32_e32 v57, 17, v198
	v_cmp_lt_u32_e64 s[16:17], v56, v60
	v_cmp_lt_u32_e64 s[14:15], v58, v60
	v_cndmask_b32_e64 v186, 0, v68, s[18:19]
	v_cndmask_b32_e64 v56, 0, -v97, s[16:17]
	v_cndmask_b32_e64 v58, 0, -v197, s[14:15]
	v_or_b32_e32 v68, 18, v198
	v_add_f32_e32 v174, v178, v180
	v_add_f32_e32 v175, v179, v181
	v_cmp_lt_u32_e64 s[20:21], v57, v61
	v_add_f32_e32 v59, 0, v56
	v_add_f32_e32 v191, v50, v58
	v_or_b32_e32 v50, 19, v198
	v_cmp_lt_u32_e64 s[18:19], v68, v60
	v_cndmask_b32_e64 v175, 0, -v175, s[20:21]
	v_cndmask_b32_e64 v184, 0, v177, s[24:25]
	v_cndmask_b32_e64 v68, 0, -v196, s[18:19]
	v_cmp_lt_u32_e64 s[24:25], v50, v61
	v_add_f32_e32 v50, v175, v59
	v_add_f32_e32 v50, v68, v50
	v_cndmask_b32_e64 v174, 0, -v174, s[24:25]
	v_add_f32_e32 v50, v174, v50
	ds_bpermute_b32 v57, v85, v50
	ds_bpermute_b32 v176, v87, v50
	v_mov_b32_e32 v73, v53
	v_mov_b32_e32 v181, v194
	v_mov_b32_e32 v183, v195
	s_waitcnt lgkmcnt(0)
	ds_bpermute_b32 v177, v87, v57
	v_add_f32_e32 v50, v50, v57
	v_add_f32_e32 v179, v50, v176
	v_cndmask_b32_e64 v50, 0, v57, s[0:1]
	v_cndmask_b32_e64 v53, 0, v176, s[22:23]
	v_add_f32_e32 v180, v50, v53
	s_waitcnt lgkmcnt(0)
	v_cndmask_b32_e64 v182, 0, v177, s[4:5]
	v_add_f32_e32 v180, v180, v182
	v_add_f32_e32 v181, v181, v183
	v_add_f32_e32 v69, v54, v68
	v_mov_b32_e32 v53, v180
	v_mov_b32_e32 v57, v181
	v_add_f32_e32 v59, v55, v174
	v_add_f32_e32 v52, v52, v56
	v_add_f32_e32 v53, v53, v57
	v_add_f32_e32 v54, v72, v174
	v_add_f32_e32 v55, v73, v175
	v_add_f32_e32 v50, v59, v53
	v_add_f32_e32 v56, v69, v53
	v_add_f32_e32 v50, 0, v50
	v_add_f32_e32 v56, v54, v56
	v_exp_f32_e32 v56, v56
	v_exp_f32_e32 v50, v50
	v_mov_b32_e32 v69, v53
	v_add_u32_e32 v199, 1, v198
	v_add_f32_e32 v54, v68, v54
	v_add_f32_e32 v55, v69, v55
	v_or_b32_e32 v97, 3, v198
	v_cndmask_b32_e64 v68, 0, v56, s[18:19]
	v_cndmask_b32_e64 v69, 0, v50, s[24:25]
	v_add_f32_e32 v50, v54, v55
	v_add_f32_e32 v55, v52, v53
	v_add_f32_e32 v52, v98, v100
	v_add_f32_e32 v53, v99, v101
	v_cmp_lt_u32_e64 s[18:19], v199, v61
	v_add_f32_e32 v200, 0, v96
	v_cmp_lt_u32_e64 s[24:25], v97, v61
	v_cndmask_b32_e64 v57, 0, -v53, s[18:19]
	v_exp_f32_e32 v50, v50
	v_cndmask_b32_e64 v56, 0, -v52, s[24:25]
	v_add_f32_e32 v52, v57, v200
	v_add_f32_e32 v52, v58, v52
	v_add_f32_e32 v182, v56, v52
	ds_bpermute_b32 v183, v85, v182
	v_add_f32_e32 v52, v175, v54
	ds_bpermute_b32 v192, v87, v182
	v_add_f32_e32 v52, v52, v55
	v_exp_f32_e32 v52, v52
	s_waitcnt lgkmcnt(0)
	ds_bpermute_b32 v193, v87, v183
	v_cndmask_b32_e64 v178, 0, v183, s[0:1]
	v_cndmask_b32_e64 v176, 0, v192, s[22:23]
	v_cndmask_b32_e64 v99, 0, v52, s[16:17]
	v_add_f32_e32 v52, v178, v176
	v_add_f32_e32 v53, v179, v177
	s_waitcnt lgkmcnt(0)
	v_cndmask_b32_e64 v180, 0, v193, s[4:5]
	v_add_f32_e32 v52, v52, v180
	v_add_f32_e32 v53, v53, v181
	v_mov_b32_e32 v73, v49
	v_mov_b32_e32 v49, v52
	v_mov_b32_e32 v97, v53
	v_add_f32_e32 v48, v48, v96
	v_add_f32_e32 v49, v49, v97
	v_cndmask_b32_e64 v98, 0, v50, s[20:21]
	v_add_f32_e32 v100, v51, v56
	v_add_f32_e32 v50, v72, v56
	v_add_f32_e32 v51, v73, v57
	v_mov_b32_e32 v59, v49
	v_add_f32_e32 v54, v58, v50
	v_add_f32_e32 v55, v59, v51
	v_add_f32_e32 v51, v100, v49
	v_add_f32_e32 v52, v191, v49
	v_add_f32_e32 v48, v48, v49
	v_add_f32_e32 v49, v57, v54
	v_add_f32_e32 v51, 0, v51
	v_add_f32_e32 v50, v50, v52
	v_add_f32_e32 v52, v54, v55
	v_add_f32_e32 v48, v49, v48
	v_exp_f32_e32 v51, v51
	v_exp_f32_e32 v50, v50
	v_exp_f32_e32 v52, v52
	v_exp_f32_e32 v48, v48
	v_bfe_u32 v59, v68, 16, 1
	v_cndmask_b32_e64 v49, 0, v50, s[14:15]
	v_cndmask_b32_e64 v50, 0, v51, s[24:25]
	v_cndmask_b32_e64 v51, 0, v52, s[18:19]
	v_cndmask_b32_e64 v48, 0, v48, s[12:13]
	v_add_u32_e32 v52, s92, v75
	v_bfe_u32 v56, v48, 16, 1
	v_bfe_u32 v57, v51, 16, 1
	v_bfe_u32 v73, v50, 16, 1
	v_bfe_u32 v96, v49, 16, 1
	v_add3_u32 v59, v68, v59, s84
	v_add3_u32 v68, v52, v124, v117
	v_add3_u32 v191, v52, v125, v117
	v_add3_u32 v97, v51, v57, s84
	v_add3_u32 v100, v48, v56, s84
	v_add3_u32 v101, v49, v96, s84
	v_add3_u32 v73, v50, v73, s84
	ds_read2st64_b64 v[48:51], v68 offset0:32 offset1:36
	ds_read2st64_b64 v[54:57], v191 offset0:32 offset1:36
	v_bfe_u32 v58, v69, 16, 1
	v_add3_u32 v58, v69, v58, s84
	v_cvt_pk_bf16_f32 v98, v99, v98
	s_waitcnt lgkmcnt(0)
	v_mov_b32_e32 v174, v48
	v_mov_b32_e32 v175, v49
	v_mov_b32_e32 v176, v54
	v_mov_b32_e32 v177, v55
	v_perm_b32 v96, v97, v100, s85
	v_perm_b32 v99, v58, v59, s85
	v_perm_b32 v97, v73, v101, s85
	ds_read2st64_b64 v[178:181], v68 offset0:40 offset1:44
	v_mov_b32_e32 v54, v50
	v_mfma_f32_16x16x32_bf16 v[16:19], v[174:177], v[96:99], v[16:19]
	ds_read2st64_b64 v[174:177], v191 offset0:40 offset1:44
	v_mov_b32_e32 v55, v51
	s_waitcnt lgkmcnt(0)
	v_mov_b32_e32 v48, v178
	v_mov_b32_e32 v49, v179
	v_add_f32_e32 v190, v204, v71
	v_mov_b32_e32 v50, v174
	v_mov_b32_e32 v51, v175
	v_mfma_f32_16x16x32_bf16 v[20:23], v[54:57], v[96:99], v[20:23]
	v_add_f32_e32 v54, v70, v190
	v_exp_f32_e32 v58, v54
	ds_read2st64_b64 v[54:57], v68 offset0:48 offset1:52
	v_mfma_f32_16x16x32_bf16 v[24:27], v[48:51], v[96:99], v[24:27]
	ds_read2st64_b64 v[48:51], v191 offset0:48 offset1:52
	v_mov_b32_e32 v174, v180
	v_mov_b32_e32 v175, v181
	s_waitcnt lgkmcnt(0)
	v_mov_b32_e32 v178, v54
	v_mov_b32_e32 v179, v55
	v_mov_b32_e32 v180, v48
	v_add_f32_e32 v48, v95, v71
	v_mov_b32_e32 v181, v49
	v_mfma_f32_16x16x32_bf16 v[32:35], v[174:177], v[96:99], v[32:35]
	v_add_f32_e32 v59, v94, v48
	ds_read2st64_b64 v[68:71], v68 offset0:56 offset1:60
	ds_read2st64_b64 v[174:177], v191 offset0:56 offset1:60
	v_mov_b32_e32 v48, v56
	v_mov_b32_e32 v49, v57
	v_mfma_f32_16x16x32_bf16 v[28:31], v[178:181], v[96:99], v[28:31]
	s_waitcnt lgkmcnt(0)
	v_mov_b32_e32 v54, v68
	v_mov_b32_e32 v55, v69
	v_mov_b32_e32 v56, v174
	v_mov_b32_e32 v57, v175
	v_mfma_f32_16x16x32_bf16 v[36:39], v[48:51], v[96:99], v[36:39]
	v_exp_f32_e32 v48, v59
	v_mov_b32_e32 v174, v70
	v_mov_b32_e32 v175, v71
	v_cndmask_b32_e64 v49, 0, v188, s[10:11]
	v_cndmask_b32_e32 v50, 0, v58, vcc
	v_cndmask_b32_e64 v48, 0, v48, s[8:9]
	v_mfma_f32_16x16x32_bf16 v[40:43], v[54:57], v[96:99], v[40:43]
	v_bfe_u32 v51, v48, 16, 1
	v_bfe_u32 v54, v50, 16, 1
	v_bfe_u32 v55, v49, 16, 1
	v_mfma_f32_16x16x32_bf16 v[44:47], v[174:177], v[96:99], v[44:47]
	v_bfe_u32 v56, v189, 16, 1
	v_add3_u32 v174, v52, v126, v117
	v_add3_u32 v52, v52, v127, v117
	v_add3_u32 v69, v50, v54, s84
	v_add3_u32 v70, v48, v51, s84
	v_add3_u32 v73, v189, v56, s84
	v_add3_u32 v95, v49, v55, s84
	ds_read2st64_b64 v[48:51], v174 offset0:32 offset1:36
	ds_read2st64_b64 v[54:57], v52 offset0:32 offset1:36
	v_perm_b32 v94, v69, v70, s85
	s_waitcnt lgkmcnt(0)
	v_mov_b32_e32 v68, v48
	v_mov_b32_e32 v69, v49
	v_mov_b32_e32 v70, v54
	v_mov_b32_e32 v71, v55
	v_perm_b32 v95, v95, v73, s85
	v_cvt_pk_bf16_f32 v96, v187, v186
	v_cvt_pk_bf16_f32 v97, v185, v184
	ds_read2st64_b64 v[98:101], v174 offset0:40 offset1:44
	v_mov_b32_e32 v54, v50
	v_mfma_f32_16x16x32_bf16 v[16:19], v[68:71], v[94:97], v[16:19]
	ds_read2st64_b64 v[68:71], v52 offset0:40 offset1:44
	v_mov_b32_e32 v55, v51
	s_waitcnt lgkmcnt(0)
	v_mov_b32_e32 v48, v98
	v_mov_b32_e32 v49, v99
	v_mfma_f32_16x16x32_bf16 v[20:23], v[54:57], v[94:97], v[20:23]
	v_mov_b32_e32 v50, v68
	v_mov_b32_e32 v51, v69
	v_add_f32_e32 v54, v182, v183
	v_add_f32_e32 v58, v54, v192
	ds_read2st64_b64 v[54:57], v174 offset0:48 offset1:52
	v_mov_b32_e32 v68, v100
	v_mov_b32_e32 v69, v101
	v_mfma_f32_16x16x32_bf16 v[24:27], v[48:51], v[94:97], v[24:27]
	ds_read2st64_b64 v[48:51], v52 offset0:48 offset1:52
	s_waitcnt lgkmcnt(0)
	v_mov_b32_e32 v98, v54
	v_add_f32_e32 v54, v58, v193
	v_mfma_f32_16x16x32_bf16 v[32:35], v[68:71], v[94:97], v[32:35]
	v_add_f32_e32 v69, v54, v53
	v_mov_b32_e32 v100, v48
	v_mov_b32_e32 v48, v56
	ds_bpermute_b32 v56, v89, v69
	v_mov_b32_e32 v101, v49
	v_mov_b32_e32 v49, v57
	v_mov_b32_e32 v99, v55
	s_waitcnt lgkmcnt(0)
	v_max_f32_e32 v56, v56, v56
	v_max_f32_e32 v68, v69, v56
	ds_bpermute_b32 v70, v91, v68
	v_mfma_f32_16x16x32_bf16 v[36:39], v[48:51], v[94:97], v[36:39]
	ds_read2st64_b64 v[48:51], v174 offset0:56 offset1:60
	ds_read2st64_b64 v[52:55], v52 offset0:56 offset1:60
	s_waitcnt lgkmcnt(0)
	v_mov_b32_e32 v56, v48
	v_max_f32_e32 v48, v70, v70
	v_max_f32_e32 v48, v68, v48
	v_mov_b32_e32 v57, v49
	ds_bpermute_b32 v49, v93, v48
	v_mov_b32_e32 v58, v52
	v_mov_b32_e32 v59, v53
	v_mov_b32_e32 v52, v50
	v_mov_b32_e32 v53, v51
	s_waitcnt lgkmcnt(0)
	v_max_f32_e32 v49, v49, v49
	v_max_f32_e32 v48, v48, v49
	ds_bpermute_b32 v49, v173, v48
	v_mfma_f32_16x16x32_bf16 v[28:31], v[98:101], v[94:97], v[28:31]
	v_mfma_f32_16x16x32_bf16 v[40:43], v[56:59], v[94:97], v[40:43]
	v_mfma_f32_16x16x32_bf16 v[44:47], v[52:55], v[94:97], v[44:47]
	s_and_saveexec_b64 s[8:9], s[6:7]
	s_cbranch_execz .LBB0_256
	s_waitcnt lgkmcnt(0)
	v_max_f32_e32 v49, v49, v49
	v_max_f32_e32 v48, v48, v48
	v_max_f32_e32 v48, v48, v49
	ds_write_b32 v119, v48
	s_branch .LBB0_256

.LBB0_316:
	s_and_b32 s55, s0, 0x8000
	s_add_i32 s56, s0, 0xffff8000
	v_or_b32_e32 v126, s55, v129
	v_lshl_add_u64 v[68:69], v[66:67], 0, s[38:39]
	s_and_b32 s56, s56, 0x8000
	v_readfirstlane_b32 s57, v126
	v_add_u32_e32 v127, 0x1000, v126
	v_lshl_add_u64 v[72:73], v[68:69], 0, s[10:11]
	v_add_u32_e32 v141, 0x2000, v126
	v_or_b32_e32 v146, s56, v109
	v_or_b32_e32 v147, s56, v111
	v_readfirstlane_b32 s56, v127
	s_mov_b32 m0, s57
	s_waitcnt vmcnt(0)
	s_barrier
	v_lshl_add_u64 v[74:75], v[68:69], 0, s[12:13]
	v_add_u32_e32 v142, 0x3000, v126
	v_readfirstlane_b32 s58, v141
	global_load_lds_dwordx4 v[72:73], off
	s_mov_b32 m0, s56
	v_lshl_add_u64 v[76:77], v[68:69], 0, s[14:15]
	v_or_b32_e32 v143, 0x4000, v126
	v_readfirstlane_b32 s59, v142
	global_load_lds_dwordx4 v[74:75], off
	s_mov_b32 m0, s58
	v_lshl_add_u64 v[70:71], v[64:65], 0, s[38:39]
	v_lshl_add_u64 v[68:69], v[68:69], 0, s[18:19]
	v_add_u32_e32 v144, 0x5000, v126
	v_readfirstlane_b32 s60, v143
	global_load_lds_dwordx4 v[76:77], off
	s_mov_b32 m0, s59
	v_lshl_add_u64 v[78:79], v[70:71], 0, s[20:21]
	v_add_u32_e32 v145, 0x6000, v126
	v_readfirstlane_b32 s61, v144
	global_load_lds_dwordx4 v[68:69], off
	s_mov_b32 m0, s60
	v_lshl_add_u64 v[80:81], v[70:71], 0, s[22:23]
	v_add_u32_e32 v126, 0x7000, v126
	v_readfirstlane_b32 s64, v145
	global_load_lds_dwordx4 v[78:79], off
	s_mov_b32 m0, s61
	v_lshl_add_u64 v[82:83], v[70:71], 0, s[24:25]
	v_readfirstlane_b32 s65, v126
	global_load_lds_dwordx4 v[80:81], off
	s_mov_b32 m0, s64
	v_lshl_add_u64 v[70:71], v[70:71], 0, s[28:29]
	global_load_lds_dwordx4 v[82:83], off
	s_mov_b32 m0, s65
	v_add_u32_e32 v126, v146, v110
	global_load_lds_dwordx4 v[70:71], off
	v_add_u32_e32 v127, v146, v108
	ds_read_b128 v[68:71], v126
	ds_read_b128 v[72:75], v127 offset:16384
	ds_read_b128 v[76:79], v127 offset:18432
	ds_read_b128 v[80:83], v127 offset:20480
	ds_read_b128 v[142:145], v126 offset:2048
	v_add_u32_e32 v141, v147, v110
	ds_read_b128 v[160:163], v127 offset:22528
	ds_read_b128 v[164:167], v127 offset:24576
	ds_read_b128 v[168:171], v127 offset:26624
	ds_read_b128 v[172:175], v127 offset:28672
	ds_read_b128 v[176:179], v127 offset:30720
	ds_read_b128 v[180:183], v141
	ds_read_b128 v[184:187], v141 offset:2048
	v_add_u32_e32 v146, v147, v108
	ds_read_b128 v[188:191], v146 offset:16384
	ds_read_b128 v[192:195], v146 offset:18432
	ds_read_b128 v[196:199], v146 offset:20480
	ds_read_b128 v[200:203], v146 offset:22528
	ds_read_b128 v[204:207], v146 offset:24576
	ds_read_b128 v[208:211], v146 offset:26624
	ds_read_b128 v[212:215], v146 offset:28672
	ds_read_b128 v[216:219], v146 offset:30720
	s_waitcnt lgkmcnt(0)
	v_mfma_f32_16x16x32_bf16 v[40:43], v[68:71], v[72:75], v[40:43]
	s_add_u32 s38, s38, 0x80
	s_addc_u32 s39, s39, 0
	s_add_i32 s0, s0, 0x8000
	v_mfma_f32_16x16x32_bf16 v[28:31], v[68:71], v[76:79], v[28:31]
	s_cmpk_eq_i32 s38, 0xf80
	v_mfma_f32_16x16x32_bf16 v[60:63], v[68:71], v[80:83], v[60:63]
	v_mfma_f32_16x16x32_bf16 v[20:23], v[68:71], v[160:163], v[20:23]
	v_mfma_f32_16x16x32_bf16 v[44:47], v[68:71], v[164:167], v[44:47]
	v_mfma_f32_16x16x32_bf16 v[24:27], v[68:71], v[168:171], v[24:27]
	v_mfma_f32_16x16x32_bf16 v[56:59], v[68:71], v[172:175], v[56:59]
	v_mfma_f32_16x16x32_bf16 v[12:15], v[68:71], v[176:179], v[12:15]
	v_mfma_f32_16x16x32_bf16 v[52:55], v[142:145], v[72:75], v[52:55]
	v_mfma_f32_16x16x32_bf16 v[16:19], v[142:145], v[76:79], v[16:19]
	v_mfma_f32_16x16x32_bf16 v[48:51], v[142:145], v[80:83], v[48:51]
	v_mfma_f32_16x16x32_bf16 v[0:3], v[142:145], v[160:163], v[0:3]
	v_mfma_f32_16x16x32_bf16 v[36:39], v[142:145], v[164:167], v[36:39]
	v_mfma_f32_16x16x32_bf16 v[8:11], v[142:145], v[168:171], v[8:11]
	v_mfma_f32_16x16x32_bf16 v[32:35], v[142:145], v[172:175], v[32:35]
	v_mfma_f32_16x16x32_bf16 v[4:7], v[142:145], v[176:179], v[4:7]
	v_mfma_f32_16x16x32_bf16 v[40:43], v[180:183], v[188:191], v[40:43]
	v_mfma_f32_16x16x32_bf16 v[28:31], v[180:183], v[192:195], v[28:31]
	v_mfma_f32_16x16x32_bf16 v[60:63], v[180:183], v[196:199], v[60:63]
	v_mfma_f32_16x16x32_bf16 v[20:23], v[180:183], v[200:203], v[20:23]
	v_mfma_f32_16x16x32_bf16 v[44:47], v[180:183], v[204:207], v[44:47]
	v_mfma_f32_16x16x32_bf16 v[24:27], v[180:183], v[208:211], v[24:27]
	v_mfma_f32_16x16x32_bf16 v[56:59], v[180:183], v[212:215], v[56:59]
	v_mfma_f32_16x16x32_bf16 v[12:15], v[180:183], v[216:219], v[12:15]
	v_mfma_f32_16x16x32_bf16 v[52:55], v[184:187], v[188:191], v[52:55]
	v_mfma_f32_16x16x32_bf16 v[16:19], v[184:187], v[192:195], v[16:19]
	v_mfma_f32_16x16x32_bf16 v[48:51], v[184:187], v[196:199], v[48:51]
	v_mfma_f32_16x16x32_bf16 v[0:3], v[184:187], v[200:203], v[0:3]
	v_mfma_f32_16x16x32_bf16 v[36:39], v[184:187], v[204:207], v[36:39]
	v_mfma_f32_16x16x32_bf16 v[8:11], v[184:187], v[208:211], v[8:11]
	v_mfma_f32_16x16x32_bf16 v[32:35], v[184:187], v[212:215], v[32:35]
	v_mfma_f32_16x16x32_bf16 v[4:7], v[184:187], v[216:219], v[4:7]
	s_cbranch_scc0 .LBB0_316
	v_add_u32_e32 v68, s55, v109
	v_add_u32_e32 v72, v68, v110
	s_waitcnt vmcnt(0)
	s_barrier
	ds_read_b128 v[64:67], v72
	v_add_u32_e32 v126, v68, v108
	ds_read_b128 v[68:71], v126 offset:16384
	ds_read_b128 v[80:83], v126 offset:20480
	ds_read_b128 v[142:145], v126 offset:24576
	s_ashr_i32 s54, s54, 5
	s_lshl_b32 s0, s53, 7
	s_waitcnt lgkmcnt(0)
	v_mfma_f32_16x16x32_bf16 v[160:163], v[64:67], v[68:71], v[40:43]
	s_mul_hi_i32 s38, s54, 0x3000
	s_nop 1
	ds_read_b128 v[40:43], v72 offset:2048
	v_add_u32_e32 v141, 0x400, v113
	v_mfma_f32_16x16x32_bf16 v[164:167], v[64:67], v[80:83], v[60:63]
	ds_read_b128 v[72:75], v126 offset:18432
	v_mfma_f32_16x16x32_bf16 v[168:171], v[64:67], v[142:145], v[44:47]
	s_nop 2
	ds_read_b128 v[44:47], v126 offset:22528
	s_waitcnt lgkmcnt(0)
	v_mfma_f32_16x16x32_bf16 v[52:55], v[40:43], v[68:71], v[52:55]
	ds_read_b128 v[76:79], v126 offset:26624
	v_mfma_f32_16x16x32_bf16 v[80:83], v[40:43], v[80:83], v[48:51]
	ds_read_b128 v[68:71], v126 offset:28672
	s_waitcnt lgkmcnt(0)
	v_mfma_f32_16x16x32_bf16 v[56:59], v[64:67], v[68:71], v[56:59]
	ds_read_b128 v[48:51], v126 offset:30720
	v_mfma_f32_16x16x32_bf16 v[142:145], v[40:43], v[142:145], v[36:39]
	s_nop 2
	v_add_u32_e32 v36, s55, v111
	v_add_u32_e32 v37, v36, v110
	ds_read_b128 v[60:63], v37
	v_mfma_f32_16x16x32_bf16 v[172:175], v[40:43], v[68:71], v[32:35]
	v_add_u32_e32 v126, v36, v108
	s_mul_i32 s55, s54, 0x3000
	s_add_u32 s39, s50, s55
	ds_read_b128 v[32:35], v37 offset:2048
	v_mfma_f32_16x16x32_bf16 v[176:179], v[64:67], v[72:75], v[28:31]
	s_addc_u32 s56, s51, s38
	s_lshl_b32 s53, s53, 9
	s_add_u32 s38, s39, s53
	ds_read_b128 v[28:31], v126 offset:16384
	s_waitcnt lgkmcnt(0)
	v_mfma_f32_16x16x32_bf16 v[160:163], v[60:63], v[28:31], v[160:163]
	ds_read_b128 v[180:183], v126 offset:18432
	s_addc_u32 s39, s56, 0
	v_mfma_f32_16x16x32_bf16 v[28:31], v[32:35], v[28:31], v[52:55]
	ds_read_b128 v[36:39], v126 offset:20480
	s_waitcnt lgkmcnt(0)
	v_mfma_f32_16x16x32_bf16 v[164:167], v[60:63], v[36:39], v[164:167]
	ds_read_b128 v[68:71], v126 offset:22528
	v_mfma_f32_16x16x32_bf16 v[36:39], v[32:35], v[36:39], v[80:83]
	ds_read_b128 v[52:55], v126 offset:24576
	s_waitcnt lgkmcnt(0)
	v_mfma_f32_16x16x32_bf16 v[168:171], v[60:63], v[52:55], v[168:171]
	ds_read_b128 v[184:187], v126 offset:26624
	v_mfma_f32_16x16x32_bf16 v[52:55], v[32:35], v[52:55], v[142:145]
	s_nop 2
	ds_read_b128 v[142:145], v126 offset:28672
	s_waitcnt lgkmcnt(0)
	v_mfma_f32_16x16x32_bf16 v[188:191], v[60:63], v[142:145], v[56:59]
	ds_read_b128 v[80:83], v126 offset:30720
	s_barrier
	v_mfma_f32_16x16x32_bf16 v[56:59], v[32:35], v[142:145], v[172:175]
	v_mfma_f32_16x16x32_bf16 v[24:27], v[64:67], v[76:79], v[24:27]
	v_mfma_f32_16x16x32_bf16 v[16:19], v[40:43], v[72:75], v[16:19]
	v_mfma_f32_16x16x32_bf16 v[8:11], v[40:43], v[76:79], v[8:11]
	v_mfma_f32_16x16x32_bf16 v[72:75], v[60:63], v[180:183], v[176:179]
	v_mfma_f32_16x16x32_bf16 v[24:27], v[60:63], v[184:187], v[24:27]
	v_mfma_f32_16x16x32_bf16 v[16:19], v[32:35], v[180:183], v[16:19]
	v_mfma_f32_16x16x32_bf16 v[8:11], v[32:35], v[184:187], v[8:11]
	v_mfma_f32_16x16x32_bf16 v[20:23], v[64:67], v[44:47], v[20:23]
	v_mfma_f32_16x16x32_bf16 v[12:15], v[64:67], v[48:51], v[12:15]
	v_lshl_add_u64 v[64:65], s[38:39], 0, v[84:85]
	s_add_i32 s38, s54, 4
	s_add_i32 s39, s55, 0xc000
	s_mul_hi_i32 s38, s38, 0x3000
	s_add_u32 s39, s50, s39
	s_addc_u32 s56, s51, s38
	v_lshl_add_u64 v[66:67], v[64:65], 0, s[30:31]
	v_add_co_u32_e32 v64, vcc, s47, v64
	s_add_u32 s38, s39, s53
	s_nop 0
	v_addc_co_u32_e32 v65, vcc, 0, v65, vcc
	s_addc_u32 s39, s56, 0
	v_mfma_f32_16x16x32_bf16 v[20:23], v[60:63], v[68:71], v[20:23]
	s_waitcnt lgkmcnt(0)
	v_mfma_f32_16x16x32_bf16 v[12:15], v[60:63], v[80:83], v[12:15]
	ds_write2_b32 v113, v160, v72 offset1:16
	global_load_dwordx4 v[60:63], v[64:65], off
	ds_write2_b32 v113, v161, v73 offset0:128 offset1:144
	v_lshl_add_u64 v[72:73], s[38:39], 0, v[84:85]
	s_add_i32 s38, s54, 8
	s_add_i32 s39, s55, 0x18000
	s_mul_hi_i32 s38, s38, 0x3000
	s_add_u32 s39, s50, s39
	s_addc_u32 s56, s51, s38
	v_lshl_add_u64 v[126:127], v[72:73], 0, s[30:31]
	v_add_co_u32_e32 v72, vcc, s47, v72
	s_add_u32 s38, s39, s53
	s_nop 0
	v_addc_co_u32_e32 v73, vcc, 0, v73, vcc
	s_addc_u32 s39, s56, 0
	global_load_dwordx4 v[64:67], v[66:67], off offset:16
	ds_write2_b32 v141, v162, v74 offset1:16
	global_load_dwordx4 v[76:79], v[72:73], off
	ds_write2_b32 v141, v163, v75 offset0:128 offset1:144
	global_load_dwordx4 v[72:75], v[126:127], off offset:16
	v_lshl_add_u64 v[126:127], s[38:39], 0, v[84:85]
	s_add_i32 s38, s54, 12
	s_add_i32 s39, s55, 0x24000
	s_mul_hi_i32 s38, s38, 0x3000
	s_add_u32 s39, s50, s39
	s_addc_u32 s56, s51, s38
	v_lshl_add_u64 v[146:147], v[126:127], 0, s[30:31]
	v_add_co_u32_e32 v126, vcc, s47, v126
	s_add_u32 s38, s39, s53
	s_nop 0
	v_addc_co_u32_e32 v127, vcc, 0, v127, vcc
	s_addc_u32 s39, s56, 0
	ds_write2_b32 v113, v164, v20 offset0:32 offset1:48
	global_load_dwordx4 v[142:145], v[126:127], off
	ds_write2_b32 v113, v165, v21 offset0:160 offset1:176
	v_lshl_add_u64 v[20:21], s[38:39], 0, v[84:85]
	s_add_i32 s38, s54, 16
	s_add_i32 s39, s55, 0x30000
	s_mul_hi_i32 s38, s38, 0x3000
	s_add_u32 s39, s50, s39
	s_addc_u32 s56, s51, s38
	v_lshl_add_u64 v[126:127], v[20:21], 0, s[30:31]
	v_add_co_u32_e32 v20, vcc, s47, v20
	s_add_u32 s38, s39, s53
	s_nop 0
	v_addc_co_u32_e32 v21, vcc, 0, v21, vcc
	s_addc_u32 s39, s56, 0
	global_load_dwordx4 v[160:163], v[146:147], off offset:16
	ds_write2_b32 v141, v166, v22 offset0:32 offset1:48
	global_load_dwordx4 v[172:175], v[20:21], off
	ds_write2_b32 v141, v167, v23 offset0:160 offset1:176
	global_load_dwordx4 v[20:23], v[126:127], off offset:16
	v_lshl_add_u64 v[126:127], s[38:39], 0, v[84:85]
	s_add_i32 s38, s54, 20
	s_add_i32 s39, s55, 0x3c000
	s_mul_hi_i32 s38, s38, 0x3000
	s_add_u32 s39, s50, s39
	s_addc_u32 s56, s51, s38
	v_lshl_add_u64 v[146:147], v[126:127], 0, s[30:31]
	v_add_co_u32_e32 v126, vcc, s47, v126
	s_add_u32 s38, s39, s53
	s_nop 0
	v_addc_co_u32_e32 v127, vcc, 0, v127, vcc
	s_addc_u32 s39, s56, 0
	ds_write2_b32 v113, v168, v24 offset0:64 offset1:80
	global_load_dwordx4 v[164:167], v[126:127], off
	ds_write2_b32 v113, v169, v25 offset0:192 offset1:208
	v_lshl_add_u64 v[24:25], s[38:39], 0, v[84:85]
	s_add_i32 s38, s54, 24
	s_add_i32 s39, s55, 0x48000
	s_mul_hi_i32 s38, s38, 0x3000
	s_add_u32 s39, s50, s39
	s_addc_u32 s56, s51, s38
	v_lshl_add_u64 v[126:127], v[24:25], 0, s[30:31]
	v_add_co_u32_e32 v24, vcc, s47, v24
	s_add_u32 s38, s39, s53
	s_nop 0
	v_addc_co_u32_e32 v25, vcc, 0, v25, vcc
	s_addc_u32 s39, s56, 0
	s_add_i32 s54, s54, 28
	s_add_i32 s55, s55, 0x54000
	global_load_dwordx4 v[176:179], v[146:147], off offset:16
	ds_write2_b32 v141, v170, v26 offset0:64 offset1:80
	global_load_dwordx4 v[180:183], v[24:25], off
	ds_write2_b32 v141, v171, v27 offset0:192 offset1:208
	global_load_dwordx4 v[24:27], v[126:127], off offset:16
	v_lshl_add_u64 v[126:127], s[38:39], 0, v[84:85]
	s_mul_hi_i32 s38, s54, 0x3000
	s_add_u32 s39, s50, s55
	s_addc_u32 s54, s51, s38
	v_lshl_add_u64 v[146:147], v[126:127], 0, s[30:31]
	v_add_co_u32_e32 v126, vcc, s47, v126
	s_add_u32 s38, s39, s53
	s_nop 0
	v_addc_co_u32_e32 v127, vcc, 0, v127, vcc
	s_addc_u32 s39, s54, 0
	ds_write2st64_b32 v114, v188, v189 offset1:2
	global_load_dwordx4 v[168:171], v[126:127], off
	v_lshl_add_u64 v[126:127], s[38:39], 0, v[84:85]
	ds_write2st64_b32 v114, v190, v191 offset0:4 offset1:6
	global_load_dwordx4 v[184:187], v[146:147], off offset:16
	v_lshl_add_u64 v[146:147], v[126:127], 0, s[30:31]
	v_add_co_u32_e32 v126, vcc, s47, v126
	ds_write2st64_b32 v115, v12, v13 offset1:2
	s_nop 0
	v_addc_co_u32_e32 v127, vcc, 0, v127, vcc
	global_load_dwordx4 v[188:191], v[126:127], off
	ds_write2st64_b32 v115, v14, v15 offset0:4 offset1:6
	global_load_dwordx4 v[12:15], v[146:147], off offset:16
	v_mfma_f32_16x16x32_bf16 v[0:3], v[40:43], v[44:47], v[0:3]
	s_lshl_b64 s[34:35], s[34:35], 17
	s_add_i32 s52, s52, s3
	v_mfma_f32_16x16x32_bf16 v[4:7], v[40:43], v[48:51], v[4:7]
	s_add_i32 s33, s33, s46
	s_cmpk_gt_i32 s52, 0x3ff
	v_mfma_f32_16x16x32_bf16 v[68:71], v[32:35], v[68:71], v[0:3]
	s_nop 2
	v_lshl_add_u64 v[0:1], s[34:35], 0, v[90:91]
	v_or_b32_e32 v0, s0, v0
	v_lshlrev_b64 v[126:127], 2, v[0:1]
	v_lshl_add_u64 v[0:1], s[68:69], 0, v[126:127]
	v_mfma_f32_16x16x32_bf16 v[32:35], v[32:35], v[80:83], v[4:7]
	ds_read_b128 v[80:83], v112
	ds_read_b128 v[204:207], v112 offset:16
	ds_read_b128 v[200:203], v116
	ds_read_b128 v[192:195], v118 offset:16
	ds_read_b128 v[196:199], v118
	ds_read_b128 v[44:47], v117 offset:16
	ds_read_b128 v[40:43], v117
	ds_read_b128 v[48:51], v116 offset:16
	global_load_dwordx4 v[208:211], v[0:1], off offset:16 nt
	global_load_dwordx4 v[212:215], v[0:1], off nt
	s_waitcnt vmcnt(0)
	v_add_f32_e32 v0, 0, v62
	v_add_f32_e32 v1, 0, v63
	v_add_f32_e32 v2, 0, v60
	v_add_f32_e32 v3, 0, v61
	v_add_f32_e32 v4, 0, v66
	v_add_f32_e32 v5, 0, v67
	v_add_f32_e32 v6, 0, v64
	v_add_f32_e32 v7, 0, v65
	v_add_f32_e32 v0, v0, v78
	v_add_f32_e32 v1, v1, v79
	v_add_f32_e32 v2, v2, v76
	v_add_f32_e32 v3, v3, v77
	v_add_f32_e32 v4, v4, v74
	v_add_f32_e32 v5, v5, v75
	v_add_f32_e32 v6, v6, v72
	v_add_f32_e32 v7, v7, v73
	v_add_f32_e32 v0, v0, v144
	v_add_f32_e32 v1, v1, v145
	v_add_f32_e32 v2, v2, v142
	v_add_f32_e32 v3, v3, v143
	v_add_f32_e32 v4, v4, v162
	v_add_f32_e32 v5, v5, v163
	v_add_f32_e32 v6, v6, v160
	v_add_f32_e32 v7, v7, v161
	v_add_f32_e32 v0, v0, v174
	v_add_f32_e32 v1, v1, v175
	v_add_f32_e32 v2, v2, v172
	v_add_f32_e32 v3, v3, v173
	v_add_f32_e32 v4, v4, v22
	v_add_f32_e32 v5, v5, v23
	v_add_f32_e32 v6, v6, v20
	v_add_f32_e32 v7, v7, v21
	v_add_f32_e32 v0, v0, v166
	v_add_f32_e32 v1, v1, v167
	v_add_f32_e32 v2, v2, v164
	v_add_f32_e32 v3, v3, v165
	v_add_f32_e32 v4, v4, v178
	v_add_f32_e32 v5, v5, v179
	v_add_f32_e32 v6, v6, v176
	v_add_f32_e32 v7, v7, v177
	v_add_f32_e32 v0, v0, v182
	v_add_f32_e32 v1, v1, v183
	v_add_f32_e32 v2, v2, v180
	v_add_f32_e32 v3, v3, v181
	v_add_f32_e32 v4, v4, v26
	v_add_f32_e32 v5, v5, v27
	v_add_f32_e32 v6, v6, v24
	v_add_f32_e32 v7, v7, v25
	v_lshl_add_u64 v[24:25], s[48:49], 0, v[126:127]
	v_lshl_add_u64 v[26:27], s[34:35], 0, v[96:97]
	v_or_b32_e32 v26, s0, v26
	v_lshlrev_b64 v[26:27], 2, v[26:27]
	v_add_f32_e32 v0, v0, v170
	v_add_f32_e32 v1, v1, v171
	v_add_f32_e32 v2, v2, v168
	v_add_f32_e32 v3, v3, v169
	v_add_f32_e32 v4, v4, v186
	v_add_f32_e32 v5, v5, v187
	v_add_f32_e32 v6, v6, v184
	v_add_f32_e32 v7, v7, v185
	v_add_f32_e32 v0, v0, v190
	v_add_f32_e32 v1, v1, v191
	v_add_f32_e32 v2, v2, v188
	v_add_f32_e32 v3, v3, v189
	v_add_f32_e32 v4, v4, v14
	v_add_f32_e32 v5, v5, v15
	v_add_f32_e32 v6, v6, v12
	v_add_f32_e32 v7, v7, v13
	s_waitcnt lgkmcnt(6)
	v_fma_f32 v22, v4, v206, v210
	v_fma_f32 v23, v5, v207, v211
	v_fma_f32 v14, v0, v82, v214
	v_fma_f32 v15, v1, v83, v215
	v_fma_f32 v12, v2, v80, v212
	v_fma_f32 v13, v3, v81, v213
	global_store_dwordx4 v[24:25], v[12:15], off
	v_fma_f32 v20, v6, v204, v208
	v_fma_f32 v21, v7, v205, v209
	global_store_dwordx4 v[24:25], v[20:23], off offset:16
	v_lshl_add_u64 v[12:13], s[34:35], 0, v[92:93]
	v_or_b32_e32 v12, s0, v12
	v_lshlrev_b64 v[24:25], 2, v[12:13]
	v_lshl_add_u64 v[20:21], s[68:69], 0, v[24:25]
	global_load_dwordx4 v[12:15], v[20:21], off offset:16 nt
	v_lshl_add_u64 v[24:25], s[48:49], 0, v[24:25]
	global_load_dwordx4 v[20:23], v[20:21], off nt
	s_waitcnt vmcnt(1) lgkmcnt(0)
	v_fma_f32 v14, v4, v50, v14
	v_fma_f32 v15, v5, v51, v15
	v_fma_f32 v12, v6, v48, v12
	v_fma_f32 v13, v7, v49, v13
	global_store_dwordx4 v[24:25], v[12:15], off offset:16
	s_waitcnt vmcnt(1)
	v_fma_f32 v22, v0, v202, v22
	v_fma_f32 v23, v1, v203, v23
	v_fma_f32 v20, v2, v200, v20
	v_fma_f32 v21, v3, v201, v21
	v_lshl_add_u64 v[12:13], s[34:35], 0, v[94:95]
	v_or_b32_e32 v12, s0, v12
	global_store_dwordx4 v[24:25], v[20:23], off
	v_lshlrev_b64 v[24:25], 2, v[12:13]
	v_lshl_add_u64 v[48:49], s[68:69], 0, v[26:27]
	v_lshl_add_u64 v[20:21], s[68:69], 0, v[24:25]
	global_load_dwordx4 v[12:15], v[20:21], off offset:16 nt
	v_lshl_add_u64 v[24:25], s[48:49], 0, v[24:25]
	global_load_dwordx4 v[20:23], v[20:21], off nt
	v_lshl_add_u64 v[50:51], s[34:35], 0, v[100:101]
	v_or_b32_e32 v50, s0, v50
	v_lshlrev_b64 v[50:51], 2, v[50:51]
	s_waitcnt vmcnt(1)
	v_fma_f32 v14, v4, v46, v14
	v_fma_f32 v15, v5, v47, v15
	v_fma_f32 v12, v6, v44, v12
	v_fma_f32 v13, v7, v45, v13
	s_waitcnt vmcnt(0)
	v_fma_f32 v22, v0, v42, v22
	v_fma_f32 v23, v1, v43, v23
	v_fma_f32 v20, v2, v40, v20
	v_fma_f32 v21, v3, v41, v21
	global_store_dwordx4 v[24:25], v[20:23], off
	global_store_dwordx4 v[24:25], v[12:15], off offset:16
	global_load_dwordx4 v[12:15], v[48:49], off offset:16 nt
	v_lshl_add_u64 v[24:25], s[34:35], 0, v[98:99]
	global_load_dwordx4 v[20:23], v[48:49], off nt
	v_or_b32_e32 v24, s0, v24
	v_lshlrev_b64 v[48:49], 2, v[24:25]
	v_lshl_add_u64 v[24:25], s[48:49], 0, v[26:27]
	v_lshl_add_u64 v[44:45], s[68:69], 0, v[48:49]
	v_lshl_add_u64 v[48:49], s[48:49], 0, v[48:49]
	s_waitcnt vmcnt(1)
	v_fma_f32 v14, v4, v194, v14
	v_fma_f32 v15, v5, v195, v15
	v_fma_f32 v12, v6, v192, v12
	v_fma_f32 v13, v7, v193, v13
	s_waitcnt vmcnt(0)
	v_fma_f32 v22, v0, v198, v22
	v_fma_f32 v23, v1, v199, v23
	v_fma_f32 v20, v2, v196, v20
	v_fma_f32 v21, v3, v197, v21
	global_store_dwordx4 v[24:25], v[20:23], off
	global_store_dwordx4 v[24:25], v[12:15], off offset:16
	ds_write2_b32 v113, v28, v16 offset1:16
	ds_write2_b32 v113, v29, v17 offset0:128 offset1:144
	ds_write2_b32 v141, v30, v18 offset1:16
	ds_write2_b32 v141, v31, v19 offset0:128 offset1:144
	ds_write2_b32 v113, v36, v68 offset0:32 offset1:48
	ds_write2_b32 v113, v37, v69 offset0:160 offset1:176
	ds_write2_b32 v141, v38, v70 offset0:32 offset1:48
	ds_write2_b32 v141, v39, v71 offset0:160 offset1:176
	ds_write2_b32 v113, v52, v8 offset0:64 offset1:80
	ds_write2_b32 v113, v53, v9 offset0:192 offset1:208
	ds_write2_b32 v141, v54, v10 offset0:64 offset1:80
	ds_write2_b32 v141, v55, v11 offset0:192 offset1:208
	ds_write2st64_b32 v114, v56, v57 offset1:2
	ds_write2st64_b32 v114, v58, v59 offset0:4 offset1:6
	ds_write2st64_b32 v115, v32, v33 offset1:2
	ds_write2st64_b32 v115, v34, v35 offset0:4 offset1:6
	ds_read_b128 v[36:39], v112
	ds_read_b128 v[32:35], v112 offset:16
	ds_read_b128 v[28:31], v116
	ds_read_b128 v[24:27], v116 offset:16
	ds_read_b128 v[20:23], v117
	ds_read_b128 v[16:19], v117 offset:16
	ds_read_b128 v[12:15], v118
	ds_read_b128 v[8:11], v118 offset:16
	global_load_dwordx4 v[40:43], v[44:45], off offset:16 nt
	v_lshl_add_u64 v[52:53], s[68:69], 0, v[50:51]
	global_load_dwordx4 v[44:47], v[44:45], off nt
	s_waitcnt vmcnt(1) lgkmcnt(6)
	v_fma_f32 v34, v4, v34, v42
	v_fma_f32 v35, v5, v35, v43
	v_fma_f32 v32, v6, v32, v40
	v_fma_f32 v33, v7, v33, v41
	s_waitcnt vmcnt(0)
	v_fma_f32 v38, v0, v38, v46
	v_fma_f32 v39, v1, v39, v47
	v_fma_f32 v36, v2, v36, v44
	v_fma_f32 v37, v3, v37, v45
	global_store_dwordx4 v[48:49], v[36:39], off
	global_store_dwordx4 v[48:49], v[32:35], off offset:16
	global_load_dwordx4 v[32:35], v[52:53], off offset:16 nt
	v_lshl_add_u64 v[40:41], s[34:35], 0, v[102:103]
	global_load_dwordx4 v[36:39], v[52:53], off nt
	v_or_b32_e32 v40, s0, v40
	v_lshlrev_b64 v[40:41], 2, v[40:41]
	v_lshl_add_u64 v[42:43], s[48:49], 0, v[50:51]
	v_lshl_add_u64 v[44:45], s[68:69], 0, v[40:41]
	s_waitcnt vmcnt(1) lgkmcnt(4)
	v_fma_f32 v26, v4, v26, v34
	v_fma_f32 v27, v5, v27, v35
	v_fma_f32 v24, v6, v24, v32
	v_fma_f32 v25, v7, v25, v33
	s_waitcnt vmcnt(0)
	v_fma_f32 v30, v0, v30, v38
	v_fma_f32 v31, v1, v31, v39
	v_fma_f32 v28, v2, v28, v36
	v_fma_f32 v29, v3, v29, v37
	global_store_dwordx4 v[42:43], v[28:31], off
	global_store_dwordx4 v[42:43], v[24:27], off offset:16
	global_load_dwordx4 v[24:27], v[44:45], off offset:16 nt
	v_lshl_add_u64 v[32:33], s[34:35], 0, v[104:105]
	global_load_dwordx4 v[28:31], v[44:45], off nt
	v_or_b32_e32 v32, s0, v32
	v_lshlrev_b64 v[32:33], 2, v[32:33]
	v_lshl_add_u64 v[34:35], s[48:49], 0, v[40:41]
	v_lshl_add_u64 v[36:37], s[68:69], 0, v[32:33]
	s_waitcnt vmcnt(1) lgkmcnt(2)
	v_fma_f32 v18, v4, v18, v26
	v_fma_f32 v19, v5, v19, v27
	v_fma_f32 v16, v6, v16, v24
	v_fma_f32 v17, v7, v17, v25
	s_waitcnt vmcnt(0)
	v_fma_f32 v22, v0, v22, v30
	v_fma_f32 v23, v1, v23, v31
	v_fma_f32 v20, v2, v20, v28
	v_fma_f32 v21, v3, v21, v29
	global_store_dwordx4 v[34:35], v[20:23], off
	global_store_dwordx4 v[34:35], v[16:19], off offset:16
	global_load_dwordx4 v[16:19], v[36:37], off offset:16 nt
	v_lshl_add_u64 v[24:25], s[48:49], 0, v[32:33]
	global_load_dwordx4 v[20:23], v[36:37], off nt
	s_waitcnt vmcnt(0) lgkmcnt(1)
	v_fma_f32 v14, v0, v14, v22
	v_fma_f32 v15, v1, v15, v23
	v_fma_f32 v12, v2, v12, v20
	v_fma_f32 v13, v3, v13, v21
	s_waitcnt lgkmcnt(0)
	v_fma_f32 v2, v4, v10, v18
	v_fma_f32 v3, v5, v11, v19
	v_fma_f32 v0, v6, v8, v16
	v_fma_f32 v1, v7, v9, v17
	global_store_dwordx4 v[24:25], v[12:15], off
	global_store_dwordx4 v[24:25], v[0:3], off offset:16
	s_cbranch_scc0 .LBB0_315

.LBB0_511:
	v_mov_b32_e32 v99, s18
	v_cmp_lt_u32_e64 s[8:9], s18, v93
	v_cmp_lt_u32_e64 s[14:15], s18, v91
	s_add_i32 s6, s18, 1
	s_add_i32 s7, s18, 2
	s_add_i32 s10, s18, 3
	v_cndmask_b32_e64 v101, 0, v99, s[14:15]
	v_cndmask_b32_e64 v99, 0, v99, s[8:9]
	s_cmp_eq_u32 s18, 0
	v_cndmask_b32_e64 v184, 0, v97, s[8:9]
	v_mad_u64_u32 v[182:183], s[8:9], v101, s55, v[116:117]
	v_mad_u64_u32 v[186:187], s[8:9], v99, s55, v[118:119]
	v_mov_b32_e32 v103, s6
	v_cmp_lt_u32_e64 s[0:1], s6, v91
	v_mov_b32_e32 v105, s7
	v_cmp_lt_u32_e64 s[12:13], s7, v91
	v_mov_b32_e32 v107, s10
	v_cmp_lt_u32_e64 s[4:5], s10, v91
	v_cmp_lt_u32_e32 vcc, s6, v93
	v_cmp_lt_u32_e64 s[6:7], s7, v93
	v_cmp_lt_u32_e64 s[10:11], s10, v93
	s_cselect_b64 s[8:9], -1, 0
	v_cndmask_b32_e64 v109, 0, v95, s[14:15]
	v_cndmask_b32_e64 v192, 0, v103, s[0:1]
	v_cndmask_b32_e64 v193, 0, v105, s[12:13]
	v_cndmask_b32_e64 v196, 0, v107, s[4:5]
	v_cndmask_b32_e32 v103, 0, v103, vcc
	v_cndmask_b32_e64 v105, 0, v105, s[6:7]
	v_cndmask_b32_e64 v107, 0, v107, s[10:11]
	v_cndmask_b32_e64 v185, 0, 1.0, s[8:9]
	v_sub_u32_e32 v183, v183, v101
	v_sub_u32_e32 v187, v187, v99
	v_cndmask_b32_e64 v214, 0, v95, s[0:1]
	v_mad_u64_u32 v[190:191], s[0:1], v192, s55, v[116:117]
	v_mad_u64_u32 v[194:195], s[0:1], v193, s55, v[116:117]
	v_mad_u64_u32 v[198:199], s[0:1], v196, s55, v[116:117]
	v_mad_u64_u32 v[202:203], s[0:1], v103, s55, v[118:119]
	v_mad_u64_u32 v[206:207], s[0:1], v105, s55, v[118:119]
	v_mad_u64_u32 v[210:211], s[0:1], v107, s55, v[118:119]
	v_sub_f32_e32 v226, v109, v185
	v_sub_f32_e32 v228, v184, v185
	global_load_dwordx4 v[182:185], v[182:183], off
	s_nop 0
	global_load_dwordx4 v[186:189], v[186:187], off
	v_sub_u32_e32 v191, v191, v192
	v_sub_u32_e32 v195, v195, v193
	v_sub_u32_e32 v199, v199, v196
	v_sub_u32_e32 v203, v203, v103
	v_sub_u32_e32 v207, v207, v105
	v_sub_u32_e32 v211, v211, v107
	global_load_dwordx4 v[190:193], v[190:191], off
	s_nop 0
	global_load_dwordx4 v[194:197], v[194:195], off
	s_nop 0
	global_load_dwordx4 v[198:201], v[198:199], off
	s_nop 0
	global_load_dwordx4 v[202:205], v[202:203], off
	s_nop 0
	global_load_dwordx4 v[206:209], v[206:207], off
	s_nop 0
	global_load_dwordx4 v[210:213], v[210:211], off
	v_cndmask_b32_e32 v220, 0, v97, vcc
	v_cndmask_b32_e64 v216, 0, v95, s[12:13]
	v_cndmask_b32_e64 v222, 0, v97, s[6:7]
	v_cndmask_b32_e64 v218, 0, v95, s[4:5]
	v_cndmask_b32_e64 v224, 0, v97, s[10:11]
	s_add_i32 s18, s18, 4
	s_cmp_ge_u32 s18, s57
	s_waitcnt vmcnt(0)
	v_and_b32_e32 v231, 0xffff0000, v182
	v_lshlrev_b32_e32 v230, 16, v182
	v_and_b32_e32 v233, 0xffff0000, v183
	v_lshlrev_b32_e32 v232, 16, v183
	v_and_b32_e32 v183, 0xffff0000, v184
	v_lshlrev_b32_e32 v182, 16, v184
	v_and_b32_e32 v235, 0xffff0000, v185
	v_lshlrev_b32_e32 v234, 16, v185
	v_and_b32_e32 v185, 0xffff0000, v186
	v_lshlrev_b32_e32 v184, 16, v186
	v_and_b32_e32 v237, 0xffff0000, v187
	v_lshlrev_b32_e32 v236, 16, v187
	v_and_b32_e32 v187, 0xffff0000, v188
	v_lshlrev_b32_e32 v186, 16, v188
	v_and_b32_e32 v239, 0xffff0000, v189
	v_lshlrev_b32_e32 v238, 16, v189
	v_fma_f32 v146, v226, v230, v146
	v_fma_f32 v147, v226, v231, v147
	v_and_b32_e32 v189, 0xffff0000, v190
	v_lshlrev_b32_e32 v188, 16, v190
	v_fma_f32 v144, v226, v232, v144
	v_fma_f32 v145, v226, v233, v145
	v_and_b32_e32 v233, 0xffff0000, v191
	v_lshlrev_b32_e32 v232, 16, v191
	v_fma_f32 v142, v226, v182, v142
	v_fma_f32 v143, v226, v183, v143
	v_and_b32_e32 v183, 0xffff0000, v192
	v_lshlrev_b32_e32 v182, 16, v192
	v_fma_f32 v140, v226, v234, v140
	v_fma_f32 v141, v226, v235, v141
	v_and_b32_e32 v227, 0xffff0000, v193
	v_lshlrev_b32_e32 v226, 16, v193
	v_fma_f32 v126, v228, v184, v126
	v_fma_f32 v127, v228, v185, v127
	v_and_b32_e32 v185, 0xffff0000, v202
	v_lshlrev_b32_e32 v184, 16, v202
	v_fma_f32 v124, v228, v236, v124
	v_fma_f32 v125, v228, v237, v125
	v_and_b32_e32 v237, 0xffff0000, v203
	v_lshlrev_b32_e32 v236, 16, v203
	v_fma_f32 v122, v228, v186, v122
	v_fma_f32 v123, v228, v187, v123
	v_and_b32_e32 v187, 0xffff0000, v204
	v_lshlrev_b32_e32 v186, 16, v204
	v_fma_f32 v120, v228, v238, v120
	v_fma_f32 v121, v228, v239, v121
	v_and_b32_e32 v229, 0xffff0000, v205
	v_lshlrev_b32_e32 v228, 16, v205
	v_and_b32_e32 v231, 0xffff0000, v194
	v_lshlrev_b32_e32 v230, 16, v194
	v_and_b32_e32 v241, 0xffff0000, v198
	v_lshlrev_b32_e32 v240, 16, v198
	v_and_b32_e32 v191, 0xffff0000, v195
	v_lshlrev_b32_e32 v190, 16, v195
	v_and_b32_e32 v195, 0xffff0000, v199
	v_lshlrev_b32_e32 v194, 16, v199
	v_and_b32_e32 v199, 0xffff0000, v196
	v_lshlrev_b32_e32 v198, 16, v196
	v_and_b32_e32 v243, 0xffff0000, v200
	v_lshlrev_b32_e32 v242, 16, v200
	v_and_b32_e32 v193, 0xffff0000, v197
	v_lshlrev_b32_e32 v192, 16, v197
	v_and_b32_e32 v197, 0xffff0000, v201
	v_lshlrev_b32_e32 v196, 16, v201
	v_and_b32_e32 v201, 0xffff0000, v206
	v_lshlrev_b32_e32 v200, 16, v206
	v_and_b32_e32 v235, 0xffff0000, v210
	v_lshlrev_b32_e32 v234, 16, v210
	v_and_b32_e32 v203, 0xffff0000, v207
	v_lshlrev_b32_e32 v202, 16, v207
	v_and_b32_e32 v207, 0xffff0000, v211
	v_lshlrev_b32_e32 v206, 16, v211
	v_and_b32_e32 v211, 0xffff0000, v208
	v_lshlrev_b32_e32 v210, 16, v208
	v_and_b32_e32 v205, 0xffff0000, v209
	v_lshlrev_b32_e32 v204, 16, v209
	v_fma_f32 v146, v214, v188, v146
	v_fma_f32 v147, v214, v189, v147
	v_fma_f32 v144, v214, v232, v144
	v_fma_f32 v145, v214, v233, v145
	v_fma_f32 v142, v214, v182, v142
	v_fma_f32 v143, v214, v183, v143
	v_fma_f32 v140, v214, v226, v140
	v_fma_f32 v141, v214, v227, v141
	v_fma_f32 v126, v220, v184, v126
	v_fma_f32 v127, v220, v185, v127
	v_fma_f32 v124, v220, v236, v124
	v_fma_f32 v125, v220, v237, v125
	v_fma_f32 v122, v220, v186, v122
	v_fma_f32 v123, v220, v187, v123
	v_fma_f32 v120, v220, v228, v120
	v_fma_f32 v121, v220, v229, v121
	v_and_b32_e32 v245, 0xffff0000, v212
	v_lshlrev_b32_e32 v244, 16, v212
	v_and_b32_e32 v209, 0xffff0000, v213
	v_lshlrev_b32_e32 v208, 16, v213
	v_fma_f32 v146, v216, v230, v146
	v_fma_f32 v147, v216, v231, v147
	v_fma_f32 v144, v216, v190, v144
	v_fma_f32 v145, v216, v191, v145
	v_fma_f32 v142, v216, v198, v142
	v_fma_f32 v143, v216, v199, v143
	v_fma_f32 v140, v216, v192, v140
	v_fma_f32 v141, v216, v193, v141
	v_fma_f32 v126, v222, v200, v126
	v_fma_f32 v127, v222, v201, v127
	v_fma_f32 v124, v222, v202, v124
	v_fma_f32 v125, v222, v203, v125
	v_fma_f32 v122, v222, v210, v122
	v_fma_f32 v123, v222, v211, v123
	v_fma_f32 v120, v222, v204, v120
	v_fma_f32 v121, v222, v205, v121
	v_fma_f32 v146, v218, v240, v146
	v_fma_f32 v147, v218, v241, v147
	v_fma_f32 v144, v218, v194, v144
	v_fma_f32 v145, v218, v195, v145
	v_fma_f32 v142, v218, v242, v142
	v_fma_f32 v143, v218, v243, v143
	v_fma_f32 v140, v218, v196, v140
	v_fma_f32 v141, v218, v197, v141
	v_fma_f32 v126, v224, v234, v126
	v_fma_f32 v127, v224, v235, v127
	v_fma_f32 v124, v224, v206, v124
	v_fma_f32 v125, v224, v207, v125
	v_fma_f32 v122, v224, v244, v122
	v_fma_f32 v123, v224, v245, v123
	v_fma_f32 v120, v224, v208, v120
	v_fma_f32 v121, v224, v209, v121
	s_cbranch_scc0 .LBB0_511
	v_cvt_pk_bf16_f32 v119, v140, v141
	v_cvt_pk_bf16_f32 v118, v142, v143
	v_cvt_pk_bf16_f32 v117, v144, v145
	v_cvt_pk_bf16_f32 v116, v146, v147
	v_lshl_or_b32 v64, v64, 7, v162
	ds_write_b128 v64, v[116:119]
	v_cvt_pk_bf16_f32 v119, v120, v121
	v_cvt_pk_bf16_f32 v118, v122, v123
	v_cvt_pk_bf16_f32 v117, v124, v125
	v_cvt_pk_bf16_f32 v116, v126, v127
	s_mov_b32 s4, 64
	s_mov_b64 s[0:1], 0
	s_and_b64 vcc, exec, s[42:43]
	ds_write_b128 v64, v[116:119] offset:4096
	s_cbranch_vccz .LBB0_510
	s_waitcnt vmcnt(0)
	s_waitcnt lgkmcnt(0)
	s_barrier
	ds_read_b128 v[114:117], v175
	ds_read_b128 v[118:121], v176 offset:16384
	ds_read_b128 v[122:125], v176 offset:18432
	ds_read_b128 v[140:143], v176 offset:20480
	s_add_i32 s59, s59, 1
	s_waitcnt lgkmcnt(2)
	v_mfma_f32_16x16x32_bf16 v[32:35], v[114:117], v[118:121], v[32:35]
	ds_read_b128 v[144:147], v175 offset:2048
	s_cmp_lg_u32 s59, 4
	s_waitcnt lgkmcnt(2)
	v_mfma_f32_16x16x32_bf16 v[44:47], v[114:117], v[122:125], v[44:47]
	ds_read_b128 v[182:185], v176 offset:22528
	s_waitcnt lgkmcnt(2)
	v_mfma_f32_16x16x32_bf16 v[40:43], v[114:117], v[140:143], v[40:43]
	ds_read_b128 v[186:189], v176 offset:24576
	s_waitcnt lgkmcnt(1)
	v_mfma_f32_16x16x32_bf16 v[52:55], v[114:117], v[182:185], v[52:55]
	ds_read_b128 v[190:193], v176 offset:26624
	s_waitcnt lgkmcnt(1)
	v_mfma_f32_16x16x32_bf16 v[48:51], v[114:117], v[186:189], v[48:51]
	ds_read_b128 v[194:197], v176 offset:28672
	s_waitcnt lgkmcnt(1)
	v_mfma_f32_16x16x32_bf16 v[56:59], v[114:117], v[190:193], v[56:59]
	ds_read_b128 v[198:201], v176 offset:30720
	s_waitcnt lgkmcnt(1)
	v_mfma_f32_16x16x32_bf16 v[60:63], v[114:117], v[194:197], v[60:63]
	ds_read_b128 v[202:205], v177
	s_waitcnt lgkmcnt(1)
	v_mfma_f32_16x16x32_bf16 v[36:39], v[114:117], v[198:201], v[36:39]
	ds_read_b128 v[114:117], v177 offset:2048
	v_mfma_f32_16x16x32_bf16 v[0:3], v[144:147], v[118:121], v[0:3]
	ds_read_b128 v[118:121], v178 offset:16384
	v_mfma_f32_16x16x32_bf16 v[8:11], v[144:147], v[122:125], v[8:11]
	ds_read_b128 v[122:125], v178 offset:18432
	v_mfma_f32_16x16x32_bf16 v[4:7], v[144:147], v[140:143], v[4:7]
	ds_read_b128 v[140:143], v178 offset:20480
	v_mfma_f32_16x16x32_bf16 v[16:19], v[144:147], v[182:185], v[16:19]
	ds_read_b128 v[182:185], v178 offset:22528
	v_mfma_f32_16x16x32_bf16 v[12:15], v[144:147], v[186:189], v[12:15]
	ds_read_b128 v[186:189], v178 offset:24576
	v_mfma_f32_16x16x32_bf16 v[20:23], v[144:147], v[190:193], v[20:23]
	ds_read_b128 v[190:193], v178 offset:26624
	v_mfma_f32_16x16x32_bf16 v[24:27], v[144:147], v[194:197], v[24:27]
	ds_read_b128 v[194:197], v178 offset:28672
	v_mfma_f32_16x16x32_bf16 v[28:31], v[144:147], v[198:201], v[28:31]
	ds_read_b128 v[144:147], v178 offset:30720
	s_waitcnt lgkmcnt(0)
	s_barrier
	v_mfma_f32_16x16x32_bf16 v[32:35], v[202:205], v[118:121], v[32:35]
	v_mfma_f32_16x16x32_bf16 v[44:47], v[202:205], v[122:125], v[44:47]
	v_mfma_f32_16x16x32_bf16 v[40:43], v[202:205], v[140:143], v[40:43]
	v_mfma_f32_16x16x32_bf16 v[52:55], v[202:205], v[182:185], v[52:55]
	v_mfma_f32_16x16x32_bf16 v[48:51], v[202:205], v[186:189], v[48:51]
	v_mfma_f32_16x16x32_bf16 v[56:59], v[202:205], v[190:193], v[56:59]
	v_mfma_f32_16x16x32_bf16 v[60:63], v[202:205], v[194:197], v[60:63]
	v_mfma_f32_16x16x32_bf16 v[36:39], v[202:205], v[144:147], v[36:39]
	v_mfma_f32_16x16x32_bf16 v[0:3], v[114:117], v[118:121], v[0:3]
	v_mfma_f32_16x16x32_bf16 v[8:11], v[114:117], v[122:125], v[8:11]
	v_mfma_f32_16x16x32_bf16 v[4:7], v[114:117], v[140:143], v[4:7]
	v_mfma_f32_16x16x32_bf16 v[16:19], v[114:117], v[182:185], v[16:19]
	v_mfma_f32_16x16x32_bf16 v[12:15], v[114:117], v[186:189], v[12:15]
	v_mfma_f32_16x16x32_bf16 v[20:23], v[114:117], v[190:193], v[20:23]
	v_mfma_f32_16x16x32_bf16 v[24:27], v[114:117], v[194:197], v[24:27]
	v_mfma_f32_16x16x32_bf16 v[28:31], v[114:117], v[144:147], v[28:31]
	s_cbranch_scc1 .LBB0_509
	ds_write2_b32 v148, v32, v44 offset1:16
	ds_write2_b32 v148, v33, v45 offset0:128 offset1:144
	v_or_b32_e32 v44, s39, v66
	s_ashr_i32 s39, s38, 31
	s_lshl_b64 s[0:1], s[38:39], 19
	s_add_u32 s0, s36, s0
	v_add_u32_e32 v33, 0x400, v148
	s_addc_u32 s1, s37, s1
	ds_write2_b32 v33, v34, v46 offset1:16
	ds_write2_b32 v33, v35, v47 offset0:128 offset1:144
	ds_write2_b32 v148, v40, v52 offset0:32 offset1:48
	ds_write2_b32 v148, v41, v53 offset0:160 offset1:176
	ds_write2_b32 v33, v42, v54 offset0:32 offset1:48
	ds_write2_b32 v33, v43, v55 offset0:160 offset1:176
	ds_write2_b32 v148, v48, v56 offset0:64 offset1:80
	ds_write2_b32 v148, v49, v57 offset0:192 offset1:208
	ds_write2_b32 v33, v50, v58 offset0:64 offset1:80
	ds_write2_b32 v33, v51, v59 offset0:192 offset1:208
	ds_write2st64_b32 v149, v60, v61 offset1:2
	ds_write2st64_b32 v149, v62, v63 offset0:4 offset1:6
	ds_write2st64_b32 v150, v36, v37 offset1:2
	ds_write2st64_b32 v150, v38, v39 offset0:4 offset1:6
	v_lshl_add_u64 v[42:43], s[0:1], 0, v[68:69]
	v_lshlrev_b32_e32 v64, 1, v44
	v_lshlrev_b32_e32 v32, 2, v44
	v_lshl_add_u64 v[58:59], v[42:43], 0, v[64:65]
	global_load_dwordx4 v[34:37], v32, s[40:41] offset:16
	global_load_dwordx4 v[38:41], v32, s[40:41]
	global_load_dwordx4 v[42:45], v[58:59], off
	ds_read_b128 v[46:49], v67
	ds_read_b128 v[50:53], v67 offset:16
	v_lshl_add_u64 v[54:55], s[0:1], 0, v[70:71]
	v_lshl_add_u64 v[60:61], v[54:55], 0, v[64:65]
	global_load_dwordx4 v[54:57], v[60:61], off
	s_waitcnt vmcnt(3) lgkmcnt(0)
	v_mul_f32_e32 v36, v52, v36
	v_mul_f32_e32 v37, v53, v37
	s_waitcnt vmcnt(2)
	v_mul_f32_e32 v40, v48, v40
	v_mul_f32_e32 v41, v49, v41
	v_mul_f32_e32 v38, v46, v38
	v_mul_f32_e32 v39, v47, v39
	v_mul_f32_e32 v34, v50, v34
	v_mul_f32_e32 v35, v51, v35
	s_waitcnt vmcnt(1)
	v_and_b32_e32 v47, 0xffff0000, v42
	v_lshlrev_b32_e32 v46, 16, v42
	v_and_b32_e32 v49, 0xffff0000, v44
	v_lshlrev_b32_e32 v48, 16, v44
	v_and_b32_e32 v51, 0xffff0000, v43
	v_lshlrev_b32_e32 v50, 16, v43
	v_and_b32_e32 v43, 0xffff0000, v45
	v_lshlrev_b32_e32 v42, 16, v45
	v_mul_f32_e32 v38, v38, v46
	v_mul_f32_e32 v39, v39, v47
	v_mul_f32_e32 v34, v34, v48
	v_mul_f32_e32 v35, v35, v49
	v_mul_f32_e32 v40, v40, v50
	v_mul_f32_e32 v41, v41, v51
	v_mul_f32_e32 v36, v36, v42
	v_mul_f32_e32 v37, v37, v43
	v_cvt_pk_bf16_f32 v37, v36, v37
	v_cvt_pk_bf16_f32 v36, v34, v35
	v_cvt_pk_bf16_f32 v35, v40, v41
	v_cvt_pk_bf16_f32 v34, v38, v39
	global_store_dwordx4 v[58:59], v[34:37], off
	global_load_dwordx4 v[34:37], v32, s[40:41]
	s_nop 0
	global_load_dwordx4 v[38:41], v32, s[40:41] offset:16
	ds_read_b128 v[42:45], v151
	ds_read_b128 v[46:49], v151 offset:16
	s_waitcnt vmcnt(3)
	v_and_b32_e32 v63, 0xffff0000, v54
	v_lshlrev_b32_e32 v62, 16, v54
	v_and_b32_e32 v111, 0xffff0000, v56
	v_lshlrev_b32_e32 v110, 16, v56
	v_and_b32_e32 v113, 0xffff0000, v55
	v_lshlrev_b32_e32 v112, 16, v55
	v_and_b32_e32 v55, 0xffff0000, v57
	v_lshlrev_b32_e32 v54, 16, v57
	v_lshl_add_u64 v[50:51], s[0:1], 0, v[72:73]
	v_lshl_add_u64 v[58:59], v[50:51], 0, v[64:65]
	global_load_dwordx4 v[50:53], v[58:59], off
	s_waitcnt vmcnt(2) lgkmcnt(1)
	v_mul_f32_e32 v36, v44, v36
	v_mul_f32_e32 v37, v45, v37
	v_mul_f32_e32 v34, v42, v34
	v_mul_f32_e32 v35, v43, v35
	s_waitcnt vmcnt(1) lgkmcnt(0)
	v_mul_f32_e32 v40, v48, v40
	v_mul_f32_e32 v41, v49, v41
	v_mul_f32_e32 v38, v46, v38
	v_mul_f32_e32 v39, v47, v39
	v_mul_f32_e32 v34, v34, v62
	v_mul_f32_e32 v35, v35, v63
	v_mul_f32_e32 v38, v38, v110
	v_mul_f32_e32 v39, v39, v111
	v_mul_f32_e32 v36, v36, v112
	v_mul_f32_e32 v37, v37, v113
	v_mul_f32_e32 v40, v40, v54
	v_mul_f32_e32 v41, v41, v55
	v_bfe_u32 v42, v39, 16, 1
	v_bfe_u32 v43, v38, 16, 1
	v_bfe_u32 v46, v41, 16, 1
	v_bfe_u32 v47, v40, 16, 1
	v_bfe_u32 v48, v37, 16, 1
	v_bfe_u32 v49, v36, 16, 1
	v_add3_u32 v49, v36, v49, s53
	v_add3_u32 v48, v37, v48, s53
	v_add3_u32 v37, v40, v47, s53
	v_add3_u32 v40, v41, v46, s53
	v_add3_u32 v36, v38, v43, s53
	v_add3_u32 v38, v39, v42, s53
	v_perm_b32 v36, v38, v36, s54
	v_cvt_pk_bf16_f32 v34, v34, v35
	v_perm_b32 v37, v40, v37, s54
	v_perm_b32 v35, v48, v49, s54
	global_store_dwordx4 v[60:61], v[34:37], off
	global_load_dwordx4 v[34:37], v32, s[40:41]
	s_nop 0
	global_load_dwordx4 v[38:41], v32, s[40:41] offset:16
	ds_read_b128 v[42:45], v160
	ds_read_b128 v[46:49], v160 offset:16
	s_waitcnt vmcnt(3)
	v_and_b32_e32 v63, 0xffff0000, v50
	v_lshlrev_b32_e32 v62, 16, v50
	v_and_b32_e32 v111, 0xffff0000, v52
	v_lshlrev_b32_e32 v110, 16, v52
	v_and_b32_e32 v113, 0xffff0000, v51
	v_lshlrev_b32_e32 v112, 16, v51
	v_and_b32_e32 v51, 0xffff0000, v53
	v_lshlrev_b32_e32 v50, 16, v53
	v_lshl_add_u64 v[54:55], s[0:1], 0, v[74:75]
	v_lshl_add_u64 v[60:61], v[54:55], 0, v[64:65]
	global_load_dwordx4 v[54:57], v[60:61], off
	s_waitcnt vmcnt(2) lgkmcnt(1)
	v_mul_f32_e32 v36, v44, v36
	v_mul_f32_e32 v37, v45, v37
	v_mul_f32_e32 v34, v42, v34
	v_mul_f32_e32 v35, v43, v35
	s_waitcnt vmcnt(1) lgkmcnt(0)
	v_mul_f32_e32 v40, v48, v40
	v_mul_f32_e32 v41, v49, v41
	v_mul_f32_e32 v38, v46, v38
	v_mul_f32_e32 v39, v47, v39
	v_mul_f32_e32 v34, v34, v62
	v_mul_f32_e32 v35, v35, v63
	v_mul_f32_e32 v38, v38, v110
	v_mul_f32_e32 v39, v39, v111
	v_mul_f32_e32 v36, v36, v112
	v_mul_f32_e32 v37, v37, v113
	v_mul_f32_e32 v40, v40, v50
	v_mul_f32_e32 v41, v41, v51
	v_bfe_u32 v42, v39, 16, 1
	v_bfe_u32 v43, v38, 16, 1
	v_bfe_u32 v46, v41, 16, 1
	v_bfe_u32 v47, v40, 16, 1
	v_bfe_u32 v48, v37, 16, 1
	v_bfe_u32 v49, v36, 16, 1
	v_add3_u32 v49, v36, v49, s53
	v_add3_u32 v48, v37, v48, s53
	v_add3_u32 v37, v40, v47, s53
	v_add3_u32 v40, v41, v46, s53
	v_add3_u32 v36, v38, v43, s53
	v_add3_u32 v38, v39, v42, s53
	v_perm_b32 v36, v38, v36, s54
	v_cvt_pk_bf16_f32 v34, v34, v35
	v_perm_b32 v37, v40, v37, s54
	v_perm_b32 v35, v48, v49, s54
	global_store_dwordx4 v[58:59], v[34:37], off
	global_load_dwordx4 v[34:37], v32, s[40:41]
	s_nop 0
	global_load_dwordx4 v[38:41], v32, s[40:41] offset:16
	ds_read_b128 v[42:45], v161
	ds_read_b128 v[46:49], v161 offset:16
	s_waitcnt vmcnt(3)
	v_and_b32_e32 v53, 0xffff0000, v54
	v_lshlrev_b32_e32 v52, 16, v54
	v_and_b32_e32 v59, 0xffff0000, v56
	v_lshlrev_b32_e32 v58, 16, v56
	v_and_b32_e32 v63, 0xffff0000, v55
	v_lshlrev_b32_e32 v62, 16, v55
	v_and_b32_e32 v55, 0xffff0000, v57
	v_lshlrev_b32_e32 v54, 16, v57
	v_lshl_add_u64 v[50:51], s[0:1], 0, v[76:77]
	s_waitcnt vmcnt(1) lgkmcnt(1)
	v_mul_f32_e32 v36, v44, v36
	v_mul_f32_e32 v37, v45, v37
	v_mul_f32_e32 v34, v42, v34
	v_mul_f32_e32 v35, v43, v35
	s_waitcnt vmcnt(0) lgkmcnt(0)
	v_mul_f32_e32 v40, v48, v40
	v_mul_f32_e32 v41, v49, v41
	v_mul_f32_e32 v38, v46, v38
	v_mul_f32_e32 v39, v47, v39
	v_mul_f32_e32 v34, v34, v52
	v_mul_f32_e32 v35, v35, v53
	v_mul_f32_e32 v38, v38, v58
	v_mul_f32_e32 v39, v39, v59
	v_mul_f32_e32 v36, v36, v62
	v_mul_f32_e32 v37, v37, v63
	v_mul_f32_e32 v40, v40, v54
	v_mul_f32_e32 v41, v41, v55
	v_bfe_u32 v44, v39, 16, 1
	v_bfe_u32 v45, v38, 16, 1
	v_bfe_u32 v46, v37, 16, 1
	v_bfe_u32 v47, v36, 16, 1
	v_bfe_u32 v48, v35, 16, 1
	v_bfe_u32 v49, v34, 16, 1
	v_add3_u32 v34, v34, v49, s53
	v_add3_u32 v48, v35, v48, s53
	v_add3_u32 v35, v36, v47, s53
	v_add3_u32 v46, v37, v46, s53
	v_add3_u32 v36, v38, v45, s53
	v_add3_u32 v38, v39, v44, s53
	v_cvt_pk_bf16_f32 v37, v40, v41
	v_perm_b32 v36, v38, v36, s54
	v_perm_b32 v35, v46, v35, s54
	v_perm_b32 v34, v48, v34, s54
	global_store_dwordx4 v[60:61], v[34:37], off
	ds_write2_b32 v148, v0, v8 offset1:16
	ds_write2_b32 v148, v1, v9 offset0:128 offset1:144
	ds_write2_b32 v33, v2, v10 offset1:16
	ds_write2_b32 v33, v3, v11 offset0:128 offset1:144
	ds_write2_b32 v148, v4, v16 offset0:32 offset1:48
	ds_write2_b32 v148, v5, v17 offset0:160 offset1:176
	ds_write2_b32 v33, v6, v18 offset0:32 offset1:48
	ds_write2_b32 v33, v7, v19 offset0:160 offset1:176
	ds_write2_b32 v148, v12, v20 offset0:64 offset1:80
	ds_write2_b32 v148, v13, v21 offset0:192 offset1:208
	ds_write2_b32 v33, v14, v22 offset0:64 offset1:80
	ds_write2_b32 v33, v15, v23 offset0:192 offset1:208
	ds_write2st64_b32 v149, v24, v25 offset1:2
	ds_write2st64_b32 v149, v26, v27 offset0:4 offset1:6
	ds_write2st64_b32 v150, v28, v29 offset1:2
	ds_write2st64_b32 v150, v30, v31 offset0:4 offset1:6
	v_lshl_add_u64 v[24:25], v[50:51], 0, v[64:65]
	global_load_dwordx4 v[0:3], v32, s[40:41]
	global_load_dwordx4 v[4:7], v[24:25], off
	global_load_dwordx4 v[8:11], v32, s[40:41] offset:16
	v_lshl_add_u64 v[16:17], s[0:1], 0, v[78:79]
	ds_read_b128 v[12:15], v67
	v_lshl_add_u64 v[26:27], v[16:17], 0, v[64:65]
	ds_read_b128 v[16:19], v67 offset:16
	global_load_dwordx4 v[20:23], v[26:27], off
	s_waitcnt vmcnt(3) lgkmcnt(1)
	v_mul_f32_e32 v2, v14, v2
	v_mul_f32_e32 v3, v15, v3
	v_mul_f32_e32 v0, v12, v0
	v_mul_f32_e32 v1, v13, v1
	s_waitcnt vmcnt(2)
	v_and_b32_e32 v13, 0xffff0000, v4
	v_lshlrev_b32_e32 v12, 16, v4
	s_waitcnt vmcnt(1) lgkmcnt(0)
	v_mul_f32_e32 v10, v18, v10
	v_mul_f32_e32 v11, v19, v11
	v_mul_f32_e32 v8, v16, v8
	v_mul_f32_e32 v9, v17, v9
	v_and_b32_e32 v15, 0xffff0000, v6
	v_lshlrev_b32_e32 v14, 16, v6
	v_and_b32_e32 v17, 0xffff0000, v5
	v_lshlrev_b32_e32 v16, 16, v5
	v_and_b32_e32 v5, 0xffff0000, v7
	v_lshlrev_b32_e32 v4, 16, v7
	v_mul_f32_e32 v0, v0, v12
	v_mul_f32_e32 v1, v1, v13
	v_mul_f32_e32 v6, v8, v14
	v_mul_f32_e32 v7, v9, v15
	v_mul_f32_e32 v2, v2, v16
	v_mul_f32_e32 v3, v3, v17
	v_mul_f32_e32 v4, v10, v4
	v_mul_f32_e32 v5, v11, v5
	v_bfe_u32 v10, v7, 16, 1
	v_bfe_u32 v8, v5, 16, 1
	v_bfe_u32 v9, v4, 16, 1
	v_bfe_u32 v11, v6, 16, 1
	v_bfe_u32 v12, v3, 16, 1
	v_bfe_u32 v13, v2, 16, 1
	v_bfe_u32 v14, v1, 16, 1
	v_bfe_u32 v15, v0, 16, 1
	v_add3_u32 v0, v0, v15, s53
	v_add3_u32 v14, v1, v14, s53
	v_add3_u32 v1, v2, v13, s53
	v_add3_u32 v12, v3, v12, s53
	v_add3_u32 v2, v6, v11, s53
	v_add3_u32 v6, v7, v10, s53
	v_add3_u32 v3, v4, v9, s53
	v_add3_u32 v4, v5, v8, s53
	v_perm_b32 v3, v4, v3, s54
	v_perm_b32 v2, v6, v2, s54
	v_perm_b32 v1, v12, v1, s54
	v_perm_b32 v0, v14, v0, s54
	global_store_dwordx4 v[24:25], v[0:3], off
	global_load_dwordx4 v[0:3], v32, s[40:41]
	s_nop 0
	global_load_dwordx4 v[4:7], v32, s[40:41] offset:16
	v_lshl_add_u64 v[8:9], s[0:1], 0, v[80:81]
	v_lshl_add_u64 v[24:25], v[8:9], 0, v[64:65]
	ds_read_b128 v[8:11], v151
	ds_read_b128 v[12:15], v151 offset:16
	s_waitcnt vmcnt(3)
	v_and_b32_e32 v29, 0xffff0000, v20
	v_lshlrev_b32_e32 v28, 16, v20
	v_and_b32_e32 v31, 0xffff0000, v22
	v_lshlrev_b32_e32 v30, 16, v22
	v_and_b32_e32 v35, 0xffff0000, v21
	v_lshlrev_b32_e32 v34, 16, v21
	v_and_b32_e32 v21, 0xffff0000, v23
	v_lshlrev_b32_e32 v20, 16, v23
	global_load_dwordx4 v[16:19], v[24:25], off
	s_waitcnt vmcnt(2) lgkmcnt(1)
	v_mul_f32_e32 v2, v10, v2
	v_mul_f32_e32 v3, v11, v3
	v_mul_f32_e32 v0, v8, v0
	v_mul_f32_e32 v1, v9, v1
	s_waitcnt vmcnt(1) lgkmcnt(0)
	v_mul_f32_e32 v6, v14, v6
	v_mul_f32_e32 v7, v15, v7
	v_mul_f32_e32 v4, v12, v4
	v_mul_f32_e32 v5, v13, v5
	v_mul_f32_e32 v0, v0, v28
	v_mul_f32_e32 v1, v1, v29
	v_mul_f32_e32 v4, v4, v30
	v_mul_f32_e32 v5, v5, v31
	v_mul_f32_e32 v2, v2, v34
	v_mul_f32_e32 v3, v3, v35
	v_mul_f32_e32 v6, v6, v20
	v_mul_f32_e32 v7, v7, v21
	v_bfe_u32 v8, v5, 16, 1
	v_bfe_u32 v9, v4, 16, 1
	v_bfe_u32 v12, v7, 16, 1
	v_bfe_u32 v13, v6, 16, 1
	v_bfe_u32 v14, v3, 16, 1
	v_bfe_u32 v15, v2, 16, 1
	v_add3_u32 v15, v2, v15, s53
	v_add3_u32 v14, v3, v14, s53
	v_add3_u32 v3, v6, v13, s53
	v_add3_u32 v6, v7, v12, s53
	v_add3_u32 v2, v4, v9, s53
	v_add3_u32 v4, v5, v8, s53
	v_perm_b32 v2, v4, v2, s54
	v_cvt_pk_bf16_f32 v0, v0, v1
	v_perm_b32 v3, v6, v3, s54
	v_perm_b32 v1, v14, v15, s54
	global_store_dwordx4 v[26:27], v[0:3], off
	global_load_dwordx4 v[0:3], v32, s[40:41]
	s_nop 0
	global_load_dwordx4 v[4:7], v32, s[40:41] offset:16
	v_lshl_add_u64 v[8:9], s[0:1], 0, v[82:83]
	v_lshl_add_u64 v[26:27], v[8:9], 0, v[64:65]
	ds_read_b128 v[8:11], v160
	ds_read_b128 v[12:15], v160 offset:16
	s_waitcnt vmcnt(3)
	v_and_b32_e32 v29, 0xffff0000, v16
	v_lshlrev_b32_e32 v28, 16, v16
	v_and_b32_e32 v31, 0xffff0000, v18
	v_lshlrev_b32_e32 v30, 16, v18
	v_and_b32_e32 v35, 0xffff0000, v17
	v_lshlrev_b32_e32 v34, 16, v17
	v_and_b32_e32 v17, 0xffff0000, v19
	v_lshlrev_b32_e32 v16, 16, v19
	global_load_dwordx4 v[20:23], v[26:27], off
	s_waitcnt vmcnt(2) lgkmcnt(1)
	v_mul_f32_e32 v2, v10, v2
	v_mul_f32_e32 v3, v11, v3
	v_mul_f32_e32 v0, v8, v0
	v_mul_f32_e32 v1, v9, v1
	s_waitcnt vmcnt(1) lgkmcnt(0)
	v_mul_f32_e32 v6, v14, v6
	v_mul_f32_e32 v7, v15, v7
	v_mul_f32_e32 v4, v12, v4
	v_mul_f32_e32 v5, v13, v5
	v_mul_f32_e32 v0, v0, v28
	v_mul_f32_e32 v1, v1, v29
	v_mul_f32_e32 v4, v4, v30
	v_mul_f32_e32 v5, v5, v31
	v_mul_f32_e32 v2, v2, v34
	v_mul_f32_e32 v3, v3, v35
	v_mul_f32_e32 v6, v6, v16
	v_mul_f32_e32 v7, v7, v17
	v_bfe_u32 v8, v5, 16, 1
	v_bfe_u32 v9, v4, 16, 1
	v_bfe_u32 v12, v7, 16, 1
	v_bfe_u32 v13, v6, 16, 1
	v_bfe_u32 v14, v3, 16, 1
	v_bfe_u32 v15, v2, 16, 1
	v_add3_u32 v15, v2, v15, s53
	v_add3_u32 v14, v3, v14, s53
	v_add3_u32 v3, v6, v13, s53
	v_add3_u32 v6, v7, v12, s53
	v_add3_u32 v2, v4, v9, s53
	v_add3_u32 v4, v5, v8, s53
	v_perm_b32 v2, v4, v2, s54
	v_cvt_pk_bf16_f32 v0, v0, v1
	v_perm_b32 v3, v6, v3, s54
	v_perm_b32 v1, v14, v15, s54
	global_store_dwordx4 v[24:25], v[0:3], off
	global_load_dwordx4 v[0:3], v32, s[40:41]
	s_nop 0
	global_load_dwordx4 v[4:7], v32, s[40:41] offset:16
	ds_read_b128 v[8:11], v161
	ds_read_b128 v[12:15], v161 offset:16
	s_waitcnt vmcnt(3)
	v_and_b32_e32 v17, 0xffff0000, v20
	v_lshlrev_b32_e32 v16, 16, v20
	v_and_b32_e32 v19, 0xffff0000, v22
	v_lshlrev_b32_e32 v18, 16, v22
	v_and_b32_e32 v25, 0xffff0000, v21
	v_lshlrev_b32_e32 v24, 16, v21
	v_and_b32_e32 v21, 0xffff0000, v23
	v_lshlrev_b32_e32 v20, 16, v23
	s_waitcnt vmcnt(1) lgkmcnt(1)
	v_mul_f32_e32 v2, v10, v2
	v_mul_f32_e32 v3, v11, v3
	v_mul_f32_e32 v0, v8, v0
	v_mul_f32_e32 v1, v9, v1
	s_waitcnt vmcnt(0) lgkmcnt(0)
	v_mul_f32_e32 v6, v14, v6
	v_mul_f32_e32 v7, v15, v7
	v_mul_f32_e32 v4, v12, v4
	v_mul_f32_e32 v5, v13, v5
	v_mul_f32_e32 v0, v0, v16
	v_mul_f32_e32 v1, v1, v17
	v_mul_f32_e32 v4, v4, v18
	v_mul_f32_e32 v5, v5, v19
	v_mul_f32_e32 v2, v2, v24
	v_mul_f32_e32 v3, v3, v25
	v_mul_f32_e32 v6, v6, v20
	v_mul_f32_e32 v7, v7, v21
	v_bfe_u32 v10, v5, 16, 1
	v_bfe_u32 v11, v4, 16, 1
	v_bfe_u32 v12, v3, 16, 1
	v_bfe_u32 v13, v2, 16, 1
	v_bfe_u32 v14, v1, 16, 1
	v_bfe_u32 v15, v0, 16, 1
	v_add3_u32 v0, v0, v15, s53
	v_add3_u32 v14, v1, v14, s53
	v_add3_u32 v1, v2, v13, s53
	v_add3_u32 v12, v3, v12, s53
	v_add3_u32 v2, v4, v11, s53
	v_add3_u32 v4, v5, v10, s53
	v_cvt_pk_bf16_f32 v3, v6, v7
	v_perm_b32 v2, v4, v2, s54
	v_perm_b32 v1, v12, v1, s54
	v_perm_b32 v0, v14, v0, s54
	global_store_dwordx4 v[26:27], v[0:3], off
	s_branch .LBB0_502

.LBB0_625:
	s_lshl_b64 s[56:57], s[56:57], 1
	v_readfirstlane_b32 s31, v129
	v_lshl_add_u64 v[98:99], v[60:61], 0, s[56:57]
	s_mov_b32 m0, s31
	v_readfirstlane_b32 s31, v162
	global_load_lds_dwordx4 v[98:99], off
	v_lshl_add_u64 v[100:101], v[98:99], 0, s[40:41]
	s_mov_b32 m0, s31
	v_readfirstlane_b32 s31, v163
	global_load_lds_dwordx4 v[100:101], off
	v_lshl_add_u64 v[100:101], v[98:99], 0, s[42:43]
	s_mov_b32 m0, s31
	v_readfirstlane_b32 s31, v164
	global_load_lds_dwordx4 v[100:101], off
	v_lshl_add_u64 v[98:99], v[98:99], 0, s[44:45]
	s_mov_b32 m0, s31
	v_readfirstlane_b32 s31, v165
	global_load_lds_dwordx4 v[98:99], off
	v_lshl_add_u64 v[98:99], v[92:93], 0, s[56:57]
	s_mov_b32 m0, s31
	v_readfirstlane_b32 s31, v166
	global_load_lds_dwordx4 v[98:99], off
	v_lshl_add_u64 v[100:101], v[98:99], 0, s[40:41]
	s_mov_b32 m0, s31
	v_readfirstlane_b32 s31, v167
	global_load_lds_dwordx4 v[100:101], off
	v_lshl_add_u64 v[100:101], v[98:99], 0, s[42:43]
	s_mov_b32 m0, s31
	v_readfirstlane_b32 s31, v168
	global_load_lds_dwordx4 v[100:101], off
	v_lshl_add_u64 v[98:99], v[98:99], 0, s[44:45]
	s_mov_b32 m0, s31
	s_mov_b64 s[56:57], 64
	global_load_lds_dwordx4 v[98:99], off
	s_waitcnt vmcnt(0)
	s_waitcnt vmcnt(0) lgkmcnt(0)
	s_barrier
	ds_read_b128 v[98:101], v169
	ds_read_b128 v[180:183], v170 offset:16384
	ds_read_b128 v[184:187], v170 offset:18432
	ds_read_b128 v[188:191], v170 offset:20480
	ds_read_b128 v[102:105], v169 offset:2048
	ds_read_b128 v[192:195], v170 offset:22528
	ds_read_b128 v[196:199], v170 offset:24576
	ds_read_b128 v[200:203], v170 offset:26624
	ds_read_b128 v[204:207], v170 offset:28672
	ds_read_b128 v[208:211], v170 offset:30720
	s_waitcnt lgkmcnt(8)
	v_mfma_f32_16x16x32_bf16 v[56:59], v[98:101], v[180:183], v[56:59]
	s_andn2_b64 vcc, exec, s[54:55]
	s_mov_b64 s[54:55], 0
	s_waitcnt lgkmcnt(7)
	v_mfma_f32_16x16x32_bf16 v[52:55], v[98:101], v[184:187], v[52:55]
	s_waitcnt lgkmcnt(6)
	v_mfma_f32_16x16x32_bf16 v[48:51], v[98:101], v[188:191], v[48:51]
	s_waitcnt lgkmcnt(4)
	v_mfma_f32_16x16x32_bf16 v[44:47], v[98:101], v[192:195], v[44:47]
	s_waitcnt lgkmcnt(3)
	v_mfma_f32_16x16x32_bf16 v[40:43], v[98:101], v[196:199], v[40:43]
	s_waitcnt lgkmcnt(2)
	v_mfma_f32_16x16x32_bf16 v[36:39], v[98:101], v[200:203], v[36:39]
	s_waitcnt lgkmcnt(1)
	v_mfma_f32_16x16x32_bf16 v[32:35], v[98:101], v[204:207], v[32:35]
	s_waitcnt lgkmcnt(0)
	v_mfma_f32_16x16x32_bf16 v[28:31], v[98:101], v[208:211], v[28:31]
	ds_read_b128 v[98:101], v171
	v_mfma_f32_16x16x32_bf16 v[24:27], v[102:105], v[184:187], v[24:27]
	v_mfma_f32_16x16x32_bf16 v[20:23], v[102:105], v[188:191], v[20:23]
	v_mfma_f32_16x16x32_bf16 v[16:19], v[102:105], v[192:195], v[16:19]
	v_mfma_f32_16x16x32_bf16 v[12:15], v[102:105], v[196:199], v[12:15]
	v_mfma_f32_16x16x32_bf16 v[8:11], v[102:105], v[200:203], v[8:11]
	v_mfma_f32_16x16x32_bf16 v[4:7], v[102:105], v[204:207], v[4:7]
	v_mfma_f32_16x16x32_bf16 v[0:3], v[102:105], v[208:211], v[0:3]
	ds_read_b128 v[102:105], v171 offset:2048
	ds_read_b128 v[180:183], v172 offset:16384
	ds_read_b128 v[184:187], v172 offset:18432
	ds_read_b128 v[188:191], v172 offset:20480
	ds_read_b128 v[192:195], v172 offset:22528
	ds_read_b128 v[196:199], v172 offset:24576
	ds_read_b128 v[200:203], v172 offset:26624
	ds_read_b128 v[204:207], v172 offset:28672
	ds_read_b128 v[208:211], v172 offset:30720
	s_waitcnt lgkmcnt(7)
	v_mfma_f32_16x16x32_bf16 v[56:59], v[98:101], v[180:183], v[56:59]
	s_waitcnt lgkmcnt(0)
	s_barrier
	v_mfma_f32_16x16x32_bf16 v[52:55], v[98:101], v[184:187], v[52:55]
	v_mfma_f32_16x16x32_bf16 v[48:51], v[98:101], v[188:191], v[48:51]
	v_mfma_f32_16x16x32_bf16 v[44:47], v[98:101], v[192:195], v[44:47]
	v_mfma_f32_16x16x32_bf16 v[40:43], v[98:101], v[196:199], v[40:43]
	v_mfma_f32_16x16x32_bf16 v[36:39], v[98:101], v[200:203], v[36:39]
	v_mfma_f32_16x16x32_bf16 v[32:35], v[98:101], v[204:207], v[32:35]
	v_mfma_f32_16x16x32_bf16 v[28:31], v[98:101], v[208:211], v[28:31]
	v_mfma_f32_16x16x32_bf16 v[24:27], v[102:105], v[184:187], v[24:27]
	v_mfma_f32_16x16x32_bf16 v[20:23], v[102:105], v[188:191], v[20:23]
	v_mfma_f32_16x16x32_bf16 v[16:19], v[102:105], v[192:195], v[16:19]
	v_mfma_f32_16x16x32_bf16 v[12:15], v[102:105], v[196:199], v[12:15]
	v_mfma_f32_16x16x32_bf16 v[8:11], v[102:105], v[200:203], v[8:11]
	v_mfma_f32_16x16x32_bf16 v[4:7], v[102:105], v[204:207], v[4:7]
	v_mfma_f32_16x16x32_bf16 v[0:3], v[102:105], v[208:211], v[0:3]
	s_cbranch_vccz .LBB0_625
	v_mul_f32_e32 v63, v63, v87
	v_mul_f32_e32 v63, v63, v91
	v_add_f32_e32 v87, v97, v63
	v_sub_f32_e32 v91, v87, v97
	v_sub_f32_e32 v63, v63, v91
	v_add_f32_e32 v63, v96, v63
	v_add_f32_e32 v91, v87, v63
	v_add_f32_e32 v60, v94, v95
	v_sub_f32_e32 v87, v91, v87
	v_sub_f32_e32 v63, v63, v87
	v_add_f32_e32 v87, v60, v91
	v_sub_f32_e32 v61, v60, v94
	v_sub_f32_e32 v94, v87, v60
	v_sub_f32_e32 v61, v95, v61
	v_sub_f32_e32 v95, v87, v94
	v_sub_f32_e32 v60, v60, v95
	v_sub_f32_e32 v91, v91, v94
	v_add_f32_e32 v60, v91, v60
	v_add_f32_e32 v91, v61, v63
	v_sub_f32_e32 v94, v91, v61
	v_sub_f32_e32 v95, v91, v94
	v_sub_f32_e32 v61, v61, v95
	v_sub_f32_e32 v63, v63, v94
	v_add_f32_e32 v60, v91, v60
	v_add_f32_e32 v61, v63, v61
	v_add_f32_e32 v63, v87, v60
	v_sub_f32_e32 v87, v63, v87
	v_sub_f32_e32 v60, v60, v87
	v_add_f32_e32 v60, v61, v60
	v_add_f32_e32 v60, v63, v60
	v_cmp_nlt_f32_e32 vcc, 1.0, v62
	s_mov_b32 s31, 0x33800000
	s_mov_b64 s[56:57], 0
	v_cndmask_b32_e32 v60, v173, v60, vcc
	v_cmp_neq_f32_e32 vcc, 1.0, v62
	s_nop 1
	v_cndmask_b32_e32 v60, v174, v60, vcc
	v_cmp_gt_f32_e32 vcc, s31, v62
	s_ashr_i32 s31, s30, 31
	s_lshl_b64 s[54:55], s[30:31], 15
	v_cndmask_b32_e64 v87, v60, -v62, vcc
	v_mul_f32_e32 v60, v87, v110
	v_mul_f32_e32 v60, 0x3fb8aa3b, v60
	v_mul_f32_e64 v61, v118, -v87
	v_mul_f32_e64 v63, v119, -v87
	v_mul_f32_e64 v91, v120, -v87
	v_exp_f32_e32 v176, v60
	v_mul_f32_e32 v61, 0x3fb8aa3b, v61
	v_mul_f32_e32 v63, 0x3fb8aa3b, v63
	v_mul_f32_e32 v91, 0x3fb8aa3b, v91
	v_exp_f32_e32 v61, v61
	v_exp_f32_e32 v63, v63
	v_exp_f32_e32 v180, v91
	v_mul_f32_e64 v91, v121, -v87
	v_mul_f32_e32 v91, 0x3fb8aa3b, v91
	v_exp_f32_e32 v181, v91
	v_lshl_add_u64 v[94:95], v[66:67], 0, s[54:55]
	v_mul_f32_e32 v56, v176, v56
	v_mul_f32_e32 v57, v176, v57
	v_readlane_b32 s54, v247, 13
	v_mul_f32_e32 v56, v61, v56
	v_mul_f32_e32 v57, v63, v57
	v_readlane_b32 s55, v247, 14
	v_mul_f32_e32 v60, v87, v111
	v_cndmask_b32_e64 v91, v56, 0, s[6:7]
	v_cndmask_b32_e64 v97, 0, v57, s[54:55]
	v_mul_f32_e32 v56, v176, v58
	v_mul_f32_e32 v57, v176, v59
	v_readlane_b32 s54, v247, 17
	v_mul_f32_e32 v60, 0x3fb8aa3b, v60
	v_mul_f32_e32 v56, v180, v56
	v_mul_f32_e32 v57, v181, v57
	v_readlane_b32 s55, v247, 18
	v_exp_f32_e32 v104, v60
	s_nop 0
	v_cndmask_b32_e64 v56, v56, 0, s[54:55]
	v_readlane_b32 s54, v247, 15
	v_readlane_b32 s55, v247, 16
	v_bfe_u32 v101, v56, 16, 1
	s_nop 0
	v_cndmask_b32_e64 v57, v57, 0, s[54:55]
	v_bfe_u32 v99, v57, 16, 1
	v_add3_u32 v101, v56, v101, s47
	v_add3_u32 v57, v57, v99, s47
	v_mul_f32_e32 v52, v104, v52
	v_readlane_b32 s54, v247, 21
	v_cvt_pk_bf16_f32 v56, v91, v97
	v_perm_b32 v57, v57, v101, s33
	v_add_u32_e32 v58, v122, v108
	v_mul_f32_e32 v52, v61, v52
	v_readlane_b32 s55, v247, 22
	ds_write_b64 v58, v[56:57] offset:32768
	v_mul_f32_e32 v53, v104, v53
	v_cndmask_b32_e64 v56, v52, 0, s[54:55]
	v_readlane_b32 s54, v247, 19
	v_mul_f32_e32 v53, v63, v53
	v_readlane_b32 s55, v247, 20
	v_mul_f32_e32 v60, v87, v112
	v_mul_f32_e32 v60, 0x3fb8aa3b, v60
	v_cndmask_b32_e64 v57, 0, v53, s[54:55]
	v_mul_f32_e32 v52, v104, v54
	v_mul_f32_e32 v53, v104, v55
	v_readlane_b32 s54, v247, 25
	v_mul_f32_e32 v52, v180, v52
	v_mul_f32_e32 v53, v181, v53
	v_readlane_b32 s55, v247, 26
	v_exp_f32_e32 v102, v60
	s_nop 0
	v_cndmask_b32_e64 v52, v52, 0, s[54:55]
	v_readlane_b32 s54, v247, 23
	v_readlane_b32 s55, v247, 24
	v_bfe_u32 v59, v52, 16, 1
	s_nop 0
	v_cndmask_b32_e64 v53, v53, 0, s[54:55]
	v_bfe_u32 v58, v53, 16, 1
	v_add3_u32 v59, v52, v59, s47
	v_add3_u32 v53, v53, v58, s47
	v_mul_f32_e32 v48, v102, v48
	v_readlane_b32 s54, v247, 29
	v_cvt_pk_bf16_f32 v52, v56, v57
	v_perm_b32 v53, v53, v59, s33
	v_add_u32_e32 v54, v122, v123
	v_mul_f32_e32 v48, v61, v48
	v_readlane_b32 s55, v247, 30
	ds_write_b64 v54, v[52:53] offset:32768
	v_mul_f32_e32 v49, v102, v49
	v_cndmask_b32_e64 v52, v48, 0, s[54:55]
	v_readlane_b32 s54, v247, 27
	v_mul_f32_e32 v49, v63, v49
	v_readlane_b32 s55, v247, 28
	v_mul_f32_e32 v60, v87, v113
	v_mul_f32_e32 v60, 0x3fb8aa3b, v60
	v_cndmask_b32_e64 v53, 0, v49, s[54:55]
	v_mul_f32_e32 v48, v102, v50
	v_mul_f32_e32 v49, v102, v51
	v_readlane_b32 s54, v247, 33
	v_mul_f32_e32 v48, v180, v48
	v_mul_f32_e32 v49, v181, v49
	v_readlane_b32 s55, v247, 34
	v_exp_f32_e32 v100, v60
	s_nop 0
	v_cndmask_b32_e64 v48, v48, 0, s[54:55]
	v_readlane_b32 s54, v247, 31
	v_readlane_b32 s55, v247, 32
	v_bfe_u32 v55, v48, 16, 1
	s_nop 0
	v_cndmask_b32_e64 v49, v49, 0, s[54:55]
	v_bfe_u32 v54, v49, 16, 1
	v_add3_u32 v55, v48, v55, s47
	v_add3_u32 v49, v49, v54, s47
	v_mul_f32_e32 v44, v100, v44
	v_readlane_b32 s54, v247, 37
	v_cvt_pk_bf16_f32 v48, v52, v53
	v_perm_b32 v49, v49, v55, s33
	v_add_u32_e32 v50, v122, v124
	v_mul_f32_e32 v44, v61, v44
	v_readlane_b32 s55, v247, 38
	ds_write_b64 v50, v[48:49] offset:32768
	v_mul_f32_e32 v45, v100, v45
	v_cndmask_b32_e64 v48, v44, 0, s[54:55]
	v_readlane_b32 s54, v247, 35
	v_mul_f32_e32 v45, v63, v45
	v_readlane_b32 s55, v247, 36
	v_mul_f32_e32 v60, v87, v114
	v_mul_f32_e32 v60, 0x3fb8aa3b, v60
	v_cndmask_b32_e64 v49, 0, v45, s[54:55]
	v_mul_f32_e32 v44, v100, v46
	v_mul_f32_e32 v45, v100, v47
	v_readlane_b32 s54, v247, 41
	v_mul_f32_e32 v44, v180, v44
	v_mul_f32_e32 v45, v181, v45
	v_readlane_b32 s55, v247, 42
	v_exp_f32_e32 v98, v60
	s_nop 0
	v_cndmask_b32_e64 v44, v44, 0, s[54:55]
	v_readlane_b32 s54, v247, 39
	v_readlane_b32 s55, v247, 40
	v_bfe_u32 v51, v44, 16, 1
	s_nop 0
	v_cndmask_b32_e64 v45, v45, 0, s[54:55]
	v_bfe_u32 v50, v45, 16, 1
	v_add3_u32 v51, v44, v51, s47
	v_add3_u32 v45, v45, v50, s47
	v_mul_f32_e32 v40, v98, v40
	v_readlane_b32 s54, v247, 45
	v_cvt_pk_bf16_f32 v44, v48, v49
	v_perm_b32 v45, v45, v51, s33
	v_add_u32_e32 v46, v122, v125
	v_mul_f32_e32 v40, v61, v40
	v_readlane_b32 s55, v247, 46
	ds_write_b64 v46, v[44:45] offset:32768
	v_mul_f32_e32 v41, v98, v41
	v_cndmask_b32_e64 v44, v40, 0, s[54:55]
	v_readlane_b32 s54, v247, 43
	v_mul_f32_e32 v41, v63, v41
	v_readlane_b32 s55, v247, 44
	v_mul_f32_e32 v60, v87, v115
	v_mul_f32_e32 v60, 0x3fb8aa3b, v60
	v_cndmask_b32_e64 v45, 0, v41, s[54:55]
	v_mul_f32_e32 v40, v98, v42
	v_mul_f32_e32 v41, v98, v43
	v_readlane_b32 s54, v247, 49
	v_mul_f32_e32 v40, v180, v40
	v_mul_f32_e32 v41, v181, v41
	v_readlane_b32 s55, v247, 50
	v_exp_f32_e32 v96, v60
	s_nop 0
	v_cndmask_b32_e64 v40, v40, 0, s[54:55]
	v_readlane_b32 s54, v247, 47
	v_readlane_b32 s55, v247, 48
	v_bfe_u32 v47, v40, 16, 1
	s_nop 0
	v_cndmask_b32_e64 v41, v41, 0, s[54:55]
	v_bfe_u32 v46, v41, 16, 1
	v_add3_u32 v47, v40, v47, s47
	v_add3_u32 v41, v41, v46, s47
	v_mul_f32_e32 v36, v96, v36
	v_readlane_b32 s54, v247, 53
	v_cvt_pk_bf16_f32 v40, v44, v45
	v_perm_b32 v41, v41, v47, s33
	v_add_u32_e32 v42, v122, v126
	v_mul_f32_e32 v36, v61, v36
	v_readlane_b32 s55, v247, 54
	ds_write_b64 v42, v[40:41] offset:32768
	v_mul_f32_e32 v37, v96, v37
	v_cndmask_b32_e64 v40, v36, 0, s[54:55]
	v_readlane_b32 s54, v247, 51
	v_mul_f32_e32 v37, v63, v37
	v_readlane_b32 s55, v247, 52
	v_mul_f32_e32 v60, v87, v116
	v_mul_f32_e32 v60, 0x3fb8aa3b, v60
	v_cndmask_b32_e64 v41, 0, v37, s[54:55]
	v_mul_f32_e32 v36, v96, v38
	v_mul_f32_e32 v37, v96, v39
	v_readlane_b32 s54, v247, 57
	v_mul_f32_e32 v36, v180, v36
	v_mul_f32_e32 v37, v181, v37
	v_readlane_b32 s55, v247, 58
	v_exp_f32_e32 v62, v60
	s_nop 0
	v_cndmask_b32_e64 v36, v36, 0, s[54:55]
	v_readlane_b32 s54, v247, 55
	v_readlane_b32 s55, v247, 56
	v_bfe_u32 v43, v36, 16, 1
	s_nop 0
	v_cndmask_b32_e64 v37, v37, 0, s[54:55]
	v_bfe_u32 v42, v37, 16, 1
	v_add3_u32 v43, v36, v43, s47
	v_add3_u32 v37, v37, v42, s47
	v_mul_f32_e32 v32, v62, v32
	v_readlane_b32 s54, v247, 61
	v_cvt_pk_bf16_f32 v36, v40, v41
	v_perm_b32 v37, v37, v43, s33
	v_add_u32_e32 v38, v122, v127
	v_mul_f32_e32 v32, v61, v32
	v_readlane_b32 s55, v247, 62
	v_mul_f32_e32 v60, v87, v117
	ds_write_b64 v38, v[36:37] offset:32768
	v_mul_f32_e32 v33, v62, v33
	v_cndmask_b32_e64 v36, v32, 0, s[54:55]
	v_readlane_b32 s54, v247, 59
	v_mul_f32_e32 v60, 0x3fb8aa3b, v60
	v_mul_f32_e32 v33, v63, v33
	v_readlane_b32 s55, v247, 60
	v_exp_f32_e32 v60, v60
	v_mul_f32_e32 v24, v104, v24
	v_mul_f32_e32 v25, v104, v25
	v_cndmask_b32_e64 v37, 0, v33, s[54:55]
	v_mul_f32_e32 v32, v62, v34
	v_mul_f32_e32 v33, v62, v35
	v_readlane_b32 s54, v247, 63
	v_mul_f32_e32 v32, v180, v32
	v_mul_f32_e32 v33, v181, v33
	v_readlane_b32 s55, v246, 0
	v_cndmask_b32_e64 v32, v32, 0, s[60:61]
	s_nop 0
	v_cndmask_b32_e64 v33, v33, 0, s[54:55]
	v_bfe_u32 v38, v33, 16, 1
	v_bfe_u32 v39, v32, 16, 1
	v_add3_u32 v39, v32, v39, s47
	v_add3_u32 v33, v33, v38, s47
	v_mul_f32_e32 v28, v60, v28
	v_mul_f32_e32 v29, v60, v29
	v_cvt_pk_bf16_f32 v32, v36, v37
	v_perm_b32 v33, v33, v39, s33
	v_add_u32_e32 v34, v122, v140
	v_mul_f32_e32 v28, v61, v28
	v_mul_f32_e32 v29, v63, v29
	ds_write_b64 v34, v[32:33] offset:32768
	v_cndmask_b32_e64 v32, v28, 0, s[64:65]
	v_cndmask_b32_e64 v33, 0, v29, s[62:63]
	v_mul_f32_e32 v28, v60, v30
	v_mul_f32_e32 v29, v60, v31
	v_mul_f32_e32 v28, v180, v28
	v_mul_f32_e32 v29, v181, v29
	v_cndmask_b32_e64 v28, v28, 0, s[68:69]
	v_cndmask_b32_e64 v29, v29, 0, s[66:67]
	v_bfe_u32 v34, v29, 16, 1
	v_bfe_u32 v35, v28, 16, 1
	v_add3_u32 v35, v28, v35, s47
	v_add3_u32 v29, v29, v34, s47
	v_cvt_pk_bf16_f32 v28, v32, v33
	v_perm_b32 v29, v29, v35, s33
	v_add_u32_e32 v30, v122, v141
	ds_write_b64 v30, v[28:29] offset:32768
	v_mul_f32_e64 v28, v142, -v87
	v_mul_f32_e64 v29, v143, -v87
	v_mul_f32_e32 v28, 0x3fb8aa3b, v28
	v_mul_f32_e32 v29, 0x3fb8aa3b, v29
	v_exp_f32_e32 v28, v28
	v_exp_f32_e32 v29, v29
	v_mul_f32_e64 v30, v144, -v87
	v_mul_f32_e64 v31, v145, -v87
	v_mul_f32_e32 v30, 0x3fb8aa3b, v30
	v_mul_f32_e32 v31, 0x3fb8aa3b, v31
	v_exp_f32_e32 v30, v30
	v_exp_f32_e32 v31, v31
	v_add_u32_e32 v32, v146, v108
	v_mul_f32_e32 v24, v28, v24
	v_mul_f32_e32 v25, v29, v25
	ds_write_b64 v32, v[178:179] offset:32768
	v_cndmask_b32_e64 v32, v24, 0, s[6:7]
	v_cndmask_b32_e64 v33, v25, 0, s[70:71]
	v_mul_f32_e32 v24, v104, v26
	v_mul_f32_e32 v25, v104, v27
	v_mul_f32_e32 v24, v30, v24
	v_mul_f32_e32 v25, v31, v25
	v_cndmask_b32_e64 v24, v24, 0, s[74:75]
	v_cndmask_b32_e64 v25, v25, 0, s[72:73]
	v_mul_f32_e32 v20, v102, v20
	v_mul_f32_e32 v21, v102, v21
	v_cvt_pk_bf16_f32 v25, v24, v25
	v_cvt_pk_bf16_f32 v24, v32, v33
	v_add_u32_e32 v26, v146, v123
	v_mul_f32_e32 v20, v28, v20
	v_mul_f32_e32 v21, v29, v21
	ds_write_b64 v26, v[24:25] offset:32768
	v_cndmask_b32_e64 v24, v20, 0, s[78:79]
	v_cndmask_b32_e64 v25, v21, 0, s[76:77]
	v_mul_f32_e32 v20, v102, v22
	v_mul_f32_e32 v21, v102, v23
	v_mul_f32_e32 v20, v30, v20
	v_mul_f32_e32 v21, v31, v21
	v_cndmask_b32_e64 v20, v20, 0, s[82:83]
	v_cndmask_b32_e64 v21, v21, 0, s[80:81]
	v_mul_f32_e32 v16, v100, v16
	v_mul_f32_e32 v17, v100, v17
	v_cvt_pk_bf16_f32 v21, v20, v21
	v_cvt_pk_bf16_f32 v20, v24, v25
	v_add_u32_e32 v22, v146, v124
	v_mul_f32_e32 v16, v28, v16
	v_mul_f32_e32 v17, v29, v17
	ds_write_b64 v22, v[20:21] offset:32768
	v_cndmask_b32_e64 v20, v16, 0, s[86:87]
	v_cndmask_b32_e64 v21, v17, 0, s[84:85]
	v_mul_f32_e32 v16, v100, v18
	v_mul_f32_e32 v17, v100, v19
	v_mul_f32_e32 v16, v30, v16
	v_mul_f32_e32 v17, v31, v17
	v_cndmask_b32_e64 v16, v16, 0, s[90:91]
	v_cndmask_b32_e64 v17, v17, 0, s[88:89]
	v_mul_f32_e32 v12, v98, v12
	v_mul_f32_e32 v13, v98, v13
	v_cvt_pk_bf16_f32 v17, v16, v17
	v_cvt_pk_bf16_f32 v16, v20, v21
	v_add_u32_e32 v18, v146, v125
	v_mul_f32_e32 v12, v28, v12
	v_mul_f32_e32 v13, v29, v13
	ds_write_b64 v18, v[16:17] offset:32768
	v_cndmask_b32_e64 v16, v12, 0, s[94:95]
	v_cndmask_b32_e64 v17, v13, 0, s[92:93]
	v_mul_f32_e32 v12, v98, v14
	v_mul_f32_e32 v13, v98, v15
	v_mul_f32_e32 v12, v30, v12
	v_mul_f32_e32 v13, v31, v13
	v_cndmask_b32_e64 v12, v12, 0, s[0:1]
	v_cndmask_b32_e64 v13, v13, 0, s[96:97]
	v_mul_f32_e32 v8, v96, v8
	v_mul_f32_e32 v9, v96, v9
	v_cvt_pk_bf16_f32 v13, v12, v13
	v_cvt_pk_bf16_f32 v12, v16, v17
	v_add_u32_e32 v14, v146, v126
	v_mul_f32_e32 v8, v28, v8
	v_mul_f32_e32 v9, v29, v9
	ds_write_b64 v14, v[12:13] offset:32768
	v_cndmask_b32_e64 v12, v8, 0, s[4:5]
	v_cndmask_b32_e64 v13, v9, 0, s[28:29]
	v_mul_f32_e32 v8, v96, v10
	v_mul_f32_e32 v9, v96, v11
	v_mul_f32_e32 v8, v30, v8
	v_mul_f32_e32 v9, v31, v9
	v_cndmask_b32_e64 v8, v8, 0, s[10:11]
	v_cndmask_b32_e64 v9, v9, 0, s[8:9]
	v_mul_f32_e32 v4, v62, v4
	v_mul_f32_e32 v5, v62, v5
	v_cvt_pk_bf16_f32 v9, v8, v9
	v_cvt_pk_bf16_f32 v8, v12, v13
	v_add_u32_e32 v10, v146, v127
	v_mul_f32_e32 v4, v28, v4
	v_mul_f32_e32 v5, v29, v5
	ds_write_b64 v10, v[8:9] offset:32768
	v_cndmask_b32_e64 v8, v4, 0, s[14:15]
	v_cndmask_b32_e64 v9, v5, 0, s[12:13]
	v_mul_f32_e32 v4, v62, v6
	v_mul_f32_e32 v5, v62, v7
	v_mul_f32_e32 v4, v30, v4
	v_mul_f32_e32 v5, v31, v5
	v_cndmask_b32_e64 v4, v4, 0, s[18:19]
	v_cndmask_b32_e64 v5, v5, 0, s[16:17]
	v_mul_f32_e32 v0, v60, v0
	v_mul_f32_e32 v1, v60, v1
	v_cvt_pk_bf16_f32 v5, v4, v5
	v_cvt_pk_bf16_f32 v4, v8, v9
	v_add_u32_e32 v6, v146, v140
	v_mul_f32_e32 v0, v28, v0
	v_mul_f32_e32 v1, v29, v1
	ds_write_b64 v6, v[4:5] offset:32768
	v_cndmask_b32_e64 v4, v0, 0, s[22:23]
	v_cndmask_b32_e64 v5, v1, 0, s[20:21]
	v_mul_f32_e32 v0, v60, v2
	v_mul_f32_e32 v1, v60, v3
	v_mul_f32_e32 v0, v30, v0
	v_mul_f32_e32 v1, v31, v1
	v_cndmask_b32_e64 v0, v0, 0, s[26:27]
	v_cndmask_b32_e64 v1, v1, 0, s[24:25]
	v_cvt_pk_bf16_f32 v1, v0, v1
	v_cvt_pk_bf16_f32 v0, v4, v5
	v_add_u32_e32 v2, v146, v141
	v_mov_b32_e32 v32, 0
	ds_write_b64 v2, v[0:1] offset:32768
	v_mov_b32_e32 v33, v32
	v_mov_b32_e32 v34, v32
	v_mov_b32_e32 v35, v32
	v_mov_b32_e32 v36, v32
	v_mov_b32_e32 v37, v32
	v_mov_b32_e32 v38, v32
	v_mov_b32_e32 v39, v32
	v_mov_b32_e32 v40, v32
	v_mov_b32_e32 v41, v32
	v_mov_b32_e32 v42, v32
	v_mov_b32_e32 v43, v32
	v_mov_b32_e32 v44, v32
	v_mov_b32_e32 v45, v32
	v_mov_b32_e32 v46, v32
	v_mov_b32_e32 v47, v32
	v_mov_b32_e32 v48, v32
	v_mov_b32_e32 v49, v32
	v_mov_b32_e32 v50, v32
	v_mov_b32_e32 v51, v32
	v_mov_b32_e32 v52, v32
	v_mov_b32_e32 v53, v32
	v_mov_b32_e32 v54, v32
	v_mov_b32_e32 v55, v32
	v_mov_b32_e32 v56, v32
	v_mov_b32_e32 v57, v32
	v_mov_b32_e32 v58, v32
	v_mov_b32_e32 v59, v32
	v_mov_b32_e32 v60, v32
	v_mov_b32_e32 v61, v32
	v_mov_b32_e32 v62, v32
	v_mov_b32_e32 v63, v32
	v_mov_b32_e32 v0, v32
	v_mov_b32_e32 v1, v32
	v_mov_b32_e32 v2, v32
	v_mov_b32_e32 v3, v32
	v_mov_b32_e32 v8, v32
	v_mov_b32_e32 v9, v32
	v_mov_b32_e32 v10, v32
	v_mov_b32_e32 v11, v32
	v_mov_b32_e32 v12, v32
	v_mov_b32_e32 v13, v32
	v_mov_b32_e32 v14, v32
	v_mov_b32_e32 v15, v32
	v_mov_b32_e32 v16, v32
	v_mov_b32_e32 v17, v32
	v_mov_b32_e32 v18, v32
	v_mov_b32_e32 v19, v32
	v_mov_b32_e32 v20, v32
	v_mov_b32_e32 v21, v32
	v_mov_b32_e32 v22, v32
	v_mov_b32_e32 v23, v32
	v_mov_b32_e32 v24, v32
	v_mov_b32_e32 v25, v32
	v_mov_b32_e32 v26, v32
	v_mov_b32_e32 v27, v32
	v_mov_b32_e32 v28, v32
	v_mov_b32_e32 v29, v32
	v_mov_b32_e32 v30, v32
	v_mov_b32_e32 v31, v32
	v_mov_b32_e32 v4, v32
	v_mov_b32_e32 v5, v32
	v_mov_b32_e32 v6, v32
	v_mov_b32_e32 v7, v32
	s_mov_b64 s[54:55], -1
.LBB0_627:
	s_lshl_b64 s[56:57], s[56:57], 1
	v_readfirstlane_b32 s31, v129
	v_lshl_add_u64 v[96:97], v[92:93], 0, s[56:57]
	s_mov_b32 m0, s31
	v_readfirstlane_b32 s31, v162
	global_load_lds_dwordx4 v[96:97], off
	v_lshl_add_u64 v[98:99], v[96:97], 0, s[40:41]
	s_mov_b32 m0, s31
	v_readfirstlane_b32 s31, v163
	global_load_lds_dwordx4 v[98:99], off
	v_lshl_add_u64 v[98:99], v[96:97], 0, s[42:43]
	s_mov_b32 m0, s31
	v_readfirstlane_b32 s31, v164
	global_load_lds_dwordx4 v[98:99], off
	v_lshl_add_u64 v[96:97], v[96:97], 0, s[44:45]
	s_mov_b32 m0, s31
	v_readfirstlane_b32 s31, v165
	global_load_lds_dwordx4 v[96:97], off
	v_lshl_add_u64 v[96:97], v[94:95], 0, s[56:57]
	s_mov_b32 m0, s31
	s_mov_b64 s[56:57], 0x2000
	v_readfirstlane_b32 s31, v166
	global_load_lds_dwordx4 v[96:97], off
	v_lshl_add_u64 v[98:99], v[96:97], 0, s[56:57]
	s_mov_b32 m0, s31
	s_mov_b64 s[56:57], 0x4000
	v_readfirstlane_b32 s31, v167
	global_load_lds_dwordx4 v[98:99], off
	v_lshl_add_u64 v[98:99], v[96:97], 0, s[56:57]
	s_mov_b32 m0, s31
	s_mov_b64 s[56:57], 0x6000
	v_readfirstlane_b32 s31, v168
	global_load_lds_dwordx4 v[98:99], off
	v_lshl_add_u64 v[96:97], v[96:97], 0, s[56:57]
	s_mov_b32 m0, s31
	s_mov_b64 s[56:57], 64
	global_load_lds_dwordx4 v[96:97], off
	s_waitcnt vmcnt(0)
	s_waitcnt vmcnt(0) lgkmcnt(0)
	s_barrier
	ds_read_b128 v[96:99], v169
	ds_read_b128 v[180:183], v170 offset:16384
	ds_read_b128 v[184:187], v170 offset:18432
	ds_read_b128 v[188:191], v170 offset:20480
	ds_read_b128 v[100:103], v169 offset:2048
	ds_read_b128 v[192:195], v170 offset:22528
	ds_read_b128 v[196:199], v170 offset:24576
	ds_read_b128 v[200:203], v170 offset:26624
	ds_read_b128 v[204:207], v170 offset:28672
	ds_read_b128 v[208:211], v170 offset:30720
	s_waitcnt lgkmcnt(8)
	v_mfma_f32_16x16x32_bf16 v[32:35], v[96:99], v[180:183], v[32:35]
	s_andn2_b64 vcc, exec, s[54:55]
	s_mov_b64 s[54:55], 0
	s_waitcnt lgkmcnt(7)
	v_mfma_f32_16x16x32_bf16 v[36:39], v[96:99], v[184:187], v[36:39]
	s_waitcnt lgkmcnt(6)
	v_mfma_f32_16x16x32_bf16 v[40:43], v[96:99], v[188:191], v[40:43]
	s_waitcnt lgkmcnt(4)
	v_mfma_f32_16x16x32_bf16 v[44:47], v[96:99], v[192:195], v[44:47]
	s_waitcnt lgkmcnt(3)
	v_mfma_f32_16x16x32_bf16 v[48:51], v[96:99], v[196:199], v[48:51]
	s_waitcnt lgkmcnt(2)
	v_mfma_f32_16x16x32_bf16 v[52:55], v[96:99], v[200:203], v[52:55]
	s_waitcnt lgkmcnt(1)
	v_mfma_f32_16x16x32_bf16 v[56:59], v[96:99], v[204:207], v[56:59]
	s_waitcnt lgkmcnt(0)
	v_mfma_f32_16x16x32_bf16 v[60:63], v[96:99], v[208:211], v[60:63]
	ds_read_b128 v[96:99], v171
	v_mfma_f32_16x16x32_bf16 v[0:3], v[100:103], v[180:183], v[0:3]
	v_mfma_f32_16x16x32_bf16 v[8:11], v[100:103], v[184:187], v[8:11]
	v_mfma_f32_16x16x32_bf16 v[12:15], v[100:103], v[188:191], v[12:15]
	v_mfma_f32_16x16x32_bf16 v[16:19], v[100:103], v[192:195], v[16:19]
	v_mfma_f32_16x16x32_bf16 v[20:23], v[100:103], v[196:199], v[20:23]
	v_mfma_f32_16x16x32_bf16 v[24:27], v[100:103], v[200:203], v[24:27]
	v_mfma_f32_16x16x32_bf16 v[28:31], v[100:103], v[204:207], v[28:31]
	v_mfma_f32_16x16x32_bf16 v[4:7], v[100:103], v[208:211], v[4:7]
	ds_read_b128 v[100:103], v171 offset:2048
	ds_read_b128 v[180:183], v172 offset:16384
	ds_read_b128 v[184:187], v172 offset:18432
	ds_read_b128 v[188:191], v172 offset:20480
	ds_read_b128 v[192:195], v172 offset:22528
	ds_read_b128 v[196:199], v172 offset:24576
	ds_read_b128 v[200:203], v172 offset:26624
	ds_read_b128 v[204:207], v172 offset:28672
	ds_read_b128 v[208:211], v172 offset:30720
	s_waitcnt lgkmcnt(7)
	v_mfma_f32_16x16x32_bf16 v[32:35], v[96:99], v[180:183], v[32:35]
	s_waitcnt lgkmcnt(0)
	s_barrier
	v_mfma_f32_16x16x32_bf16 v[36:39], v[96:99], v[184:187], v[36:39]
	v_mfma_f32_16x16x32_bf16 v[40:43], v[96:99], v[188:191], v[40:43]
	v_mfma_f32_16x16x32_bf16 v[44:47], v[96:99], v[192:195], v[44:47]
	v_mfma_f32_16x16x32_bf16 v[48:51], v[96:99], v[196:199], v[48:51]
	v_mfma_f32_16x16x32_bf16 v[52:55], v[96:99], v[200:203], v[52:55]
	v_mfma_f32_16x16x32_bf16 v[56:59], v[96:99], v[204:207], v[56:59]
	v_mfma_f32_16x16x32_bf16 v[60:63], v[96:99], v[208:211], v[60:63]
	v_mfma_f32_16x16x32_bf16 v[0:3], v[100:103], v[180:183], v[0:3]
	v_mfma_f32_16x16x32_bf16 v[8:11], v[100:103], v[184:187], v[8:11]
	v_mfma_f32_16x16x32_bf16 v[12:15], v[100:103], v[188:191], v[12:15]
	v_mfma_f32_16x16x32_bf16 v[16:19], v[100:103], v[192:195], v[16:19]
	v_mfma_f32_16x16x32_bf16 v[20:23], v[100:103], v[196:199], v[20:23]
	v_mfma_f32_16x16x32_bf16 v[24:27], v[100:103], v[200:203], v[24:27]
	v_mfma_f32_16x16x32_bf16 v[28:31], v[100:103], v[204:207], v[28:31]
	v_mfma_f32_16x16x32_bf16 v[4:7], v[100:103], v[208:211], v[4:7]
	s_cbranch_vccz .LBB0_627
	v_mul_f32_e32 v91, v87, v119
	v_mul_f32_e32 v91, 0x3fb8aa3b, v91
	v_exp_f32_e32 v92, v91
	v_mul_f32_e32 v91, v87, v120
	v_mul_f32_e32 v91, 0x3fb8aa3b, v91
	v_exp_f32_e32 v93, v91
	v_mul_f32_e32 v91, v87, v121
	v_mul_f32_e32 v91, 0x3fb8aa3b, v91
	v_exp_f32_e32 v94, v91
	v_mul_f32_e32 v91, v87, v147
	v_mul_f32_e32 v91, 0x3fb8aa3b, v91
	v_exp_f32_e32 v95, v91
	v_mul_f32_e32 v91, v87, v143
	v_mul_f32_e32 v91, 0x3fb8aa3b, v91
	v_mul_f32_e32 v32, v92, v32
	v_mul_f32_e32 v33, v93, v33
	v_mul_f32_e32 v36, v92, v36
	v_mul_f32_e32 v37, v93, v37
	v_mul_f32_e32 v40, v92, v40
	v_mul_f32_e32 v41, v93, v41
	v_mul_f32_e32 v44, v92, v44
	v_mul_f32_e32 v45, v93, v45
	v_mul_f32_e32 v48, v92, v48
	v_mul_f32_e32 v49, v93, v49
	v_mul_f32_e32 v52, v92, v52
	v_mul_f32_e32 v53, v93, v53
	v_mul_f32_e32 v56, v92, v56
	v_mul_f32_e32 v57, v93, v57
	v_mul_f32_e32 v60, v92, v60
	v_mul_f32_e32 v61, v93, v61
	v_exp_f32_e32 v92, v91
	v_mul_f32_e32 v91, v87, v144
	v_mul_f32_e32 v91, 0x3fb8aa3b, v91
	s_ashr_i32 s53, s52, 31
	v_exp_f32_e32 v93, v91
	v_mul_f32_e32 v91, v87, v145
	v_mul_f32_e32 v87, v87, v148
	s_lshl_b64 s[52:53], s[52:53], 20
	v_readlane_b32 s31, v247, 3
	v_mul_f32_e32 v91, 0x3fb8aa3b, v91
	v_mul_f32_e32 v87, 0x3fb8aa3b, v87
	s_add_u32 s31, s31, s52
	v_readlane_b32 s52, v247, 4
	v_mul_f32_e32 v34, v94, v34
	v_mul_f32_e32 v35, v95, v35
	v_mul_f32_e32 v38, v94, v38
	v_mul_f32_e32 v39, v95, v39
	v_mul_f32_e32 v42, v94, v42
	v_mul_f32_e32 v43, v95, v43
	v_mul_f32_e32 v46, v94, v46
	v_mul_f32_e32 v47, v95, v47
	v_mul_f32_e32 v50, v94, v50
	v_mul_f32_e32 v51, v95, v51
	v_mul_f32_e32 v54, v94, v54
	v_mul_f32_e32 v55, v95, v55
	v_mul_f32_e32 v58, v94, v58
	v_mul_f32_e32 v59, v95, v59
	v_mul_f32_e32 v62, v94, v62
	v_mul_f32_e32 v63, v95, v63
	v_exp_f32_e32 v94, v91
	v_exp_f32_e32 v95, v87
	s_addc_u32 s53, s52, s53
	s_lshl_b32 s38, s38, 1
	s_add_u32 s52, s31, s38
	s_addc_u32 s53, s53, 0
	v_mov_b32_e32 v91, v65
	v_mul_f32_e32 v0, v92, v0
	v_mul_f32_e32 v1, v93, v1
	v_mul_f32_e32 v8, v92, v8
	v_mul_f32_e32 v9, v93, v9
	v_mul_f32_e32 v12, v92, v12
	v_mul_f32_e32 v13, v93, v13
	v_mul_f32_e32 v16, v92, v16
	v_mul_f32_e32 v17, v93, v17
	v_mul_f32_e32 v20, v92, v20
	v_mul_f32_e32 v21, v93, v21
	v_mul_f32_e32 v24, v92, v24
	v_mul_f32_e32 v25, v93, v25
	v_mul_f32_e32 v28, v92, v28
	v_mul_f32_e32 v29, v93, v29
	v_mul_f32_e32 v4, v92, v4
	v_mul_f32_e32 v5, v93, v5
	v_lshl_add_u64 v[92:93], s[52:53], 0, v[90:91]
	v_mov_b32_e32 v87, v65
	v_mul_f32_e32 v2, v94, v2
	v_mul_f32_e32 v3, v95, v3
	v_mul_f32_e32 v10, v94, v10
	v_mul_f32_e32 v11, v95, v11
	v_mul_f32_e32 v14, v94, v14
	v_mul_f32_e32 v15, v95, v15
	v_mul_f32_e32 v18, v94, v18
	v_mul_f32_e32 v19, v95, v19
	v_mul_f32_e32 v22, v94, v22
	v_mul_f32_e32 v23, v95, v23
	v_mul_f32_e32 v26, v94, v26
	v_mul_f32_e32 v27, v95, v27
	v_mul_f32_e32 v30, v94, v30
	v_mul_f32_e32 v31, v95, v31
	v_mul_f32_e32 v6, v94, v6
	v_mul_f32_e32 v7, v95, v7
	v_lshl_add_u64 v[92:93], v[92:93], 0, v[86:87]
	s_mov_b32 s31, 0
	s_mov_b64 s[52:53], -1
.LBB0_629:
	s_lshl_b32 s38, s31, 7
	v_lshl_add_u64 v[94:95], v[92:93], 0, s[38:39]
	v_readfirstlane_b32 s38, v165
	s_mov_b32 m0, s38
	s_mov_b64 s[54:55], 0x40000
	v_readfirstlane_b32 s38, v166
	global_load_lds_dwordx4 v[94:95], off
	v_lshl_add_u64 v[96:97], v[94:95], 0, s[54:55]
	s_mov_b32 m0, s38
	s_mov_b64 s[54:55], 0x80000
	v_readfirstlane_b32 s38, v167
	global_load_lds_dwordx4 v[96:97], off
	v_lshl_add_u64 v[96:97], v[94:95], 0, s[54:55]
	s_mov_b32 m0, s38
	s_mov_b64 s[54:55], 0xc0000
	v_readfirstlane_b32 s38, v168
	global_load_lds_dwordx4 v[96:97], off
	v_lshl_add_u64 v[94:95], v[94:95], 0, s[54:55]
	s_mov_b32 m0, s38
	s_lshl_b32 s31, s31, 14
	global_load_lds_dwordx4 v[94:95], off
	v_or_b32_e32 v87, s31, v106
	v_add_u32_e32 v87, v87, v109
	s_waitcnt vmcnt(0)
	s_waitcnt vmcnt(0) lgkmcnt(0)
	s_barrier
	ds_read_b128 v[94:97], v87 offset:32768
	ds_read_b128 v[102:105], v170 offset:16384
	ds_read_b128 v[180:183], v170 offset:18432
	ds_read_b128 v[184:187], v170 offset:20480
	ds_read_b128 v[98:101], v87 offset:34816
	ds_read_b128 v[188:191], v170 offset:22528
	ds_read_b128 v[192:195], v170 offset:24576
	ds_read_b128 v[196:199], v170 offset:26624
	ds_read_b128 v[200:203], v170 offset:28672
	ds_read_b128 v[204:207], v170 offset:30720
	v_or_b32_e32 v87, s31, v107
	v_add_u32_e32 v87, v87, v109
	s_waitcnt lgkmcnt(8)
	v_mfma_f32_16x16x32_bf16 v[32:35], v[94:97], v[102:105], v[32:35]
	s_mov_b32 s31, 1
	s_and_b64 vcc, exec, s[52:53]
	s_mov_b64 s[52:53], 0
	s_waitcnt lgkmcnt(7)
	v_mfma_f32_16x16x32_bf16 v[36:39], v[94:97], v[180:183], v[36:39]
	s_waitcnt lgkmcnt(6)
	v_mfma_f32_16x16x32_bf16 v[40:43], v[94:97], v[184:187], v[40:43]
	s_waitcnt lgkmcnt(4)
	v_mfma_f32_16x16x32_bf16 v[44:47], v[94:97], v[188:191], v[44:47]
	s_waitcnt lgkmcnt(3)
	v_mfma_f32_16x16x32_bf16 v[48:51], v[94:97], v[192:195], v[48:51]
	s_waitcnt lgkmcnt(2)
	v_mfma_f32_16x16x32_bf16 v[52:55], v[94:97], v[196:199], v[52:55]
	s_waitcnt lgkmcnt(1)
	v_mfma_f32_16x16x32_bf16 v[56:59], v[94:97], v[200:203], v[56:59]
	s_waitcnt lgkmcnt(0)
	v_mfma_f32_16x16x32_bf16 v[60:63], v[94:97], v[204:207], v[60:63]
	ds_read_b128 v[94:97], v87 offset:32768
	v_mfma_f32_16x16x32_bf16 v[0:3], v[98:101], v[102:105], v[0:3]
	v_mfma_f32_16x16x32_bf16 v[8:11], v[98:101], v[180:183], v[8:11]
	v_mfma_f32_16x16x32_bf16 v[12:15], v[98:101], v[184:187], v[12:15]
	v_mfma_f32_16x16x32_bf16 v[16:19], v[98:101], v[188:191], v[16:19]
	v_mfma_f32_16x16x32_bf16 v[20:23], v[98:101], v[192:195], v[20:23]
	v_mfma_f32_16x16x32_bf16 v[24:27], v[98:101], v[196:199], v[24:27]
	v_mfma_f32_16x16x32_bf16 v[28:31], v[98:101], v[200:203], v[28:31]
	v_mfma_f32_16x16x32_bf16 v[4:7], v[98:101], v[204:207], v[4:7]
	ds_read_b128 v[98:101], v87 offset:34816
	ds_read_b128 v[102:105], v172 offset:16384
	ds_read_b128 v[180:183], v172 offset:18432
	ds_read_b128 v[184:187], v172 offset:20480
	ds_read_b128 v[188:191], v172 offset:22528
	ds_read_b128 v[192:195], v172 offset:24576
	ds_read_b128 v[196:199], v172 offset:26624
	ds_read_b128 v[200:203], v172 offset:28672
	ds_read_b128 v[204:207], v172 offset:30720
	s_waitcnt lgkmcnt(7)
	v_mfma_f32_16x16x32_bf16 v[32:35], v[94:97], v[102:105], v[32:35]
	s_waitcnt lgkmcnt(0)
	s_barrier
	v_mfma_f32_16x16x32_bf16 v[36:39], v[94:97], v[180:183], v[36:39]
	v_mfma_f32_16x16x32_bf16 v[40:43], v[94:97], v[184:187], v[40:43]
	v_mfma_f32_16x16x32_bf16 v[44:47], v[94:97], v[188:191], v[44:47]
	v_mfma_f32_16x16x32_bf16 v[48:51], v[94:97], v[192:195], v[48:51]
	v_mfma_f32_16x16x32_bf16 v[52:55], v[94:97], v[196:199], v[52:55]
	v_mfma_f32_16x16x32_bf16 v[56:59], v[94:97], v[200:203], v[56:59]
	v_mfma_f32_16x16x32_bf16 v[60:63], v[94:97], v[204:207], v[60:63]
	v_mfma_f32_16x16x32_bf16 v[0:3], v[98:101], v[102:105], v[0:3]
	v_mfma_f32_16x16x32_bf16 v[8:11], v[98:101], v[180:183], v[8:11]
	v_mfma_f32_16x16x32_bf16 v[12:15], v[98:101], v[184:187], v[12:15]
	v_mfma_f32_16x16x32_bf16 v[16:19], v[98:101], v[188:191], v[16:19]
	v_mfma_f32_16x16x32_bf16 v[20:23], v[98:101], v[192:195], v[20:23]
	v_mfma_f32_16x16x32_bf16 v[24:27], v[98:101], v[196:199], v[24:27]
	v_mfma_f32_16x16x32_bf16 v[28:31], v[98:101], v[200:203], v[28:31]
	v_mfma_f32_16x16x32_bf16 v[4:7], v[98:101], v[204:207], v[4:7]
	s_cbranch_vccnz .LBB0_629
	v_and_b32_e32 v91, 64, v155
	v_xor_b32_e32 v87, 1, v155
	v_add_u32_e32 v92, 64, v91
	v_cmp_lt_i32_e32 vcc, v87, v92
	v_mov_b32_e32 v96, v56
	v_mov_b32_e32 v97, v60
	v_cndmask_b32_e32 v87, v155, v87, vcc
	v_lshlrev_b32_e32 v176, 2, v87
	v_xor_b32_e32 v87, 2, v155
	v_cmp_lt_i32_e32 vcc, v87, v92
	v_mov_b32_e32 v93, v44
	v_mul_f32_e32 v98, v96, v96
	v_mul_f32_e32 v99, v97, v97
	v_cndmask_b32_e32 v87, v155, v87, vcc
	v_lshlrev_b32_e32 v175, 2, v87
	v_xor_b32_e32 v87, 4, v155
	v_cmp_lt_i32_e32 vcc, v87, v92
	v_mov_b32_e32 v96, v41
	v_mov_b32_e32 v97, v45
	v_cndmask_b32_e32 v87, v155, v87, vcc
	v_lshlrev_b32_e32 v91, 2, v87
	v_xor_b32_e32 v87, 8, v155
	v_cmp_lt_i32_e32 vcc, v87, v92
	v_mov_b32_e32 v92, v40
	v_mul_f32_e32 v92, v92, v92
	v_mul_f32_e32 v93, v93, v93
	v_mul_f32_e32 v100, v96, v96
	v_mul_f32_e32 v101, v97, v97
	v_mul_f32_e32 v96, v38, v38
	v_mul_f32_e32 v97, v39, v39
	v_mul_f32_e32 v102, v36, v36
	v_mul_f32_e32 v103, v37, v37
	v_mov_b32_e32 v94, v48
	v_mov_b32_e32 v95, v52
	v_fma_f32 v180, v34, v34, v96
	v_fma_f32 v181, v35, v35, v97
	v_fma_f32 v102, v32, v32, v102
	v_fma_f32 v103, v33, v33, v103
	v_mov_b32_e32 v96, v49
	v_mov_b32_e32 v97, v53
	v_mov_b32_e32 v210, v100
	v_mov_b32_e32 v211, v92
	v_mul_f32_e32 v94, v94, v94
	v_mul_f32_e32 v95, v95, v95
	v_mul_f32_e32 v182, v96, v96
	v_mul_f32_e32 v183, v97, v97
	v_pk_add_f32 v[102:103], v[102:103], v[210:211] op_sel:[1,0] op_sel_hi:[0,1]
	v_mov_b32_e32 v92, v101
	v_mov_b32_e32 v96, v57
	v_mov_b32_e32 v97, v61
	v_add_f32_e32 v92, v102, v92
	v_add_f32_e32 v93, v103, v93
	v_mov_b32_e32 v100, v182
	v_mov_b32_e32 v101, v94
	v_mul_f32_e32 v184, v96, v96
	v_mul_f32_e32 v185, v97, v97
	v_add_f32_e32 v92, v92, v100
	v_add_f32_e32 v93, v93, v101
	v_mov_b32_e32 v94, v183
	v_add_f32_e32 v92, v92, v94
	v_add_f32_e32 v93, v93, v95
	v_mov_b32_e32 v94, v184
	v_mov_b32_e32 v95, v98
	v_add_f32_e32 v92, v92, v94
	v_add_f32_e32 v93, v93, v95
	v_mov_b32_e32 v98, v185
	v_add_f32_e32 v92, v92, v98
	v_add_f32_e32 v93, v93, v99
	ds_bpermute_b32 v95, v176, v93
	ds_bpermute_b32 v94, v176, v92
	v_mov_b32_e32 v96, v42
	v_mov_b32_e32 v97, v46
	v_mul_f32_e32 v186, v96, v96
	v_mul_f32_e32 v187, v97, v97
	v_mov_b32_e32 v96, v50
	s_waitcnt lgkmcnt(0)
	v_add_f32_e32 v92, v92, v94
	v_add_f32_e32 v93, v93, v95
	ds_bpermute_b32 v95, v175, v93
	ds_bpermute_b32 v94, v175, v92
	v_mov_b32_e32 v97, v54
	v_mul_f32_e32 v188, v96, v96
	v_mul_f32_e32 v189, v97, v97
	v_mov_b32_e32 v96, v58
	v_mov_b32_e32 v97, v62
	s_waitcnt lgkmcnt(0)
	v_add_f32_e32 v92, v92, v94
	v_add_f32_e32 v93, v93, v95
	ds_bpermute_b32 v185, v91, v93
	ds_bpermute_b32 v184, v91, v92
	v_mul_f32_e32 v190, v96, v96
	v_mul_f32_e32 v191, v97, v97
	v_mov_b32_e32 v96, v43
	v_mov_b32_e32 v97, v47
	v_cndmask_b32_e32 v87, v155, v87, vcc
	v_mul_f32_e32 v192, v96, v96
	v_mul_f32_e32 v193, v97, v97
	v_lshlrev_b32_e32 v87, 2, v87
	v_mov_b32_e32 v96, v51
	v_mov_b32_e32 v97, v55
	s_waitcnt lgkmcnt(0)
	v_add_f32_e32 v92, v92, v184
	v_add_f32_e32 v93, v93, v185
	v_mov_b32_e32 v212, v192
	v_mov_b32_e32 v213, v186
	v_mul_f32_e32 v194, v96, v96
	v_mul_f32_e32 v195, v97, v97
	v_mov_b32_e32 v98, v14
	v_mov_b32_e32 v99, v18
	ds_bpermute_b32 v185, v87, v93
	ds_bpermute_b32 v184, v87, v92
	v_pk_add_f32 v[180:181], v[180:181], v[212:213] op_sel:[1,0] op_sel_hi:[0,1]
	v_mov_b32_e32 v186, v193
	v_mov_b32_e32 v96, v59
	v_mov_b32_e32 v97, v63
	v_mul_f32_e32 v102, v98, v98
	v_mul_f32_e32 v103, v99, v99
	v_mov_b32_e32 v98, v22
	v_mov_b32_e32 v99, v26
	v_add_f32_e32 v180, v180, v186
	v_add_f32_e32 v181, v181, v187
	v_mov_b32_e32 v186, v194
	v_mov_b32_e32 v187, v188
	v_mul_f32_e32 v196, v96, v96
	v_mul_f32_e32 v197, v97, v97
	v_mul_f32_e32 v100, v98, v98
	v_mul_f32_e32 v101, v99, v99
	v_mov_b32_e32 v98, v30
	v_mov_b32_e32 v99, v6
	v_add_f32_e32 v180, v180, v186
	v_add_f32_e32 v181, v181, v187
	v_mov_b32_e32 v188, v195
	v_mov_b32_e32 v208, v29
	v_mov_b32_e32 v209, v5
	v_mul_f32_e32 v94, v98, v98
	v_mul_f32_e32 v95, v99, v99
	v_mov_b32_e32 v98, v15
	v_mov_b32_e32 v99, v19
	v_add_f32_e32 v180, v180, v188
	v_add_f32_e32 v181, v181, v189
	v_mov_b32_e32 v186, v196
	v_mov_b32_e32 v187, v190
	v_mul_f32_e32 v182, v208, v208
	v_mul_f32_e32 v183, v209, v209
	v_mul_f32_e32 v208, v98, v98
	v_mul_f32_e32 v209, v99, v99
	v_mov_b32_e32 v98, v23
	v_mov_b32_e32 v99, v27
	s_mov_b32 s38, 0x358637bd
	v_add_f32_e32 v180, v180, v186
	v_add_f32_e32 v181, v181, v187
	v_mov_b32_e32 v190, v197
	v_mul_f32_e32 v210, v98, v98
	v_mul_f32_e32 v211, v99, v99
	s_waitcnt lgkmcnt(0)
	v_add_f32_e32 v98, v92, v184
	v_add_f32_e32 v99, v93, v185
	v_mov_b64_e32 v[92:93], s[38:39]
	v_add_f32_e32 v180, v180, v190
	v_add_f32_e32 v181, v181, v191
	v_fma_f32 v184, v98, s46, v92
	v_fma_f32 v185, v99, s46, v92
	ds_bpermute_b32 v187, v176, v181
	ds_bpermute_b32 v186, v176, v180
	v_mul_f32_e32 v98, 0x4b800000, v185
	v_cmp_gt_f32_e32 vcc, s58, v185
	v_mov_b32_e32 v96, v12
	v_mov_b32_e32 v97, v16
	v_cndmask_b32_e32 v98, v185, v98, vcc
	v_rsq_f32_e32 v177, v98
	s_waitcnt lgkmcnt(0)
	v_add_f32_e32 v180, v180, v186
	v_add_f32_e32 v181, v181, v187
	ds_bpermute_b32 v187, v175, v181
	ds_bpermute_b32 v186, v175, v180
	v_mul_f32_e32 v185, 0x45800000, v177
	v_cndmask_b32_e32 v177, v177, v185, vcc
	v_mul_f32_e32 v214, v32, v177
	v_mul_f32_e32 v32, 0x4b800000, v184
	v_cmp_gt_f32_e32 vcc, s58, v184
	s_waitcnt lgkmcnt(0)
	v_add_f32_e32 v180, v180, v186
	v_add_f32_e32 v181, v181, v187
	ds_bpermute_b32 v185, v91, v181
	v_cndmask_b32_e32 v32, v184, v32, vcc
	v_rsq_f32_e32 v32, v32
	ds_bpermute_b32 v184, v91, v180
	v_mul_f32_e32 v215, v36, v177
	v_mul_f32_e32 v216, v40, v177
	v_mul_f32_e32 v36, 0x45800000, v32
	v_cndmask_b32_e32 v36, v32, v36, vcc
	v_mul_f32_e32 v44, v44, v177
	v_mul_f32_e32 v48, v48, v177
	v_mul_f32_e32 v52, v52, v177
	v_mul_f32_e32 v56, v56, v177
	v_mul_f32_e32 v60, v60, v177
	v_mul_f32_e32 v177, v33, v36
	s_waitcnt lgkmcnt(0)
	v_add_f32_e32 v32, v180, v184
	v_add_f32_e32 v33, v181, v185
	ds_bpermute_b32 v181, v87, v33
	ds_bpermute_b32 v180, v87, v32
	v_mul_f32_e32 v184, v37, v36
	v_mul_f32_e32 v198, v96, v96
	v_mul_f32_e32 v199, v97, v97
	v_mov_b32_e32 v96, v20
	v_mov_b32_e32 v97, v24
	s_waitcnt lgkmcnt(0)
	v_add_f32_e32 v32, v32, v180
	v_add_f32_e32 v33, v33, v181
	v_mul_f32_e32 v200, v96, v96
	v_mul_f32_e32 v201, v97, v97
	v_fma_f32 v32, v32, s46, v92
	v_fma_f32 v33, v33, s46, v92
	v_mov_b32_e32 v96, v28
	v_mul_f32_e32 v37, 0x4b800000, v33
	v_cmp_gt_f32_e32 vcc, s58, v33
	v_mov_b32_e32 v97, v4
	v_mul_f32_e32 v104, v96, v96
	v_mul_f32_e32 v105, v97, v97
	v_cndmask_b32_e32 v33, v33, v37, vcc
	v_rsq_f32_e32 v33, v33
	v_mov_b32_e32 v96, v13
	v_mov_b32_e32 v97, v17
	v_mul_f32_e32 v202, v96, v96
	v_mul_f32_e32 v203, v97, v97
	v_mul_f32_e32 v204, v8, v8
	v_mul_f32_e32 v205, v9, v9
	v_mul_f32_e32 v185, v41, v36
	v_mul_f32_e32 v45, v45, v36
	v_mul_f32_e32 v49, v49, v36
	v_mul_f32_e32 v53, v53, v36
	v_mul_f32_e32 v57, v57, v36
	v_mul_f32_e32 v61, v61, v36
	v_mul_f32_e32 v36, 0x45800000, v33
	v_fma_f32 v204, v0, v0, v204
	v_fma_f32 v205, v1, v1, v205
	v_mov_b32_e32 v206, v21
	v_mov_b32_e32 v207, v25
	v_cndmask_b32_e32 v180, v33, v36, vcc
	v_mov_b32_e32 v36, v202
	v_mov_b32_e32 v37, v198
	v_mul_f32_e32 v206, v206, v206
	v_mul_f32_e32 v207, v207, v207
	v_add_f32_e32 v36, v205, v36
	v_add_f32_e32 v37, v204, v37
	v_mov_b32_e32 v198, v203
	v_add_f32_e32 v36, v36, v198
	v_add_f32_e32 v37, v37, v199
	v_mov_b32_e32 v40, v206
	v_mov_b32_e32 v41, v200
	v_add_f32_e32 v36, v36, v40
	v_add_f32_e32 v37, v37, v41
	v_mov_b32_e32 v200, v207
	v_add_f32_e32 v36, v36, v200
	v_add_f32_e32 v37, v37, v201
	v_mov_b32_e32 v40, v182
	v_mov_b32_e32 v41, v104
	v_add_f32_e32 v36, v36, v40
	v_add_f32_e32 v37, v37, v41
	v_mov_b32_e32 v104, v183
	v_add_f32_e32 v36, v36, v104
	v_add_f32_e32 v37, v37, v105
	ds_bpermute_b32 v41, v176, v37
	ds_bpermute_b32 v40, v176, v36
	v_mul_f32_e32 v33, 0x4b800000, v32
	v_cmp_gt_f32_e32 vcc, s58, v32
	v_mul_f32_e32 v181, v34, v180
	v_mul_f32_e32 v186, v42, v180
	s_waitcnt lgkmcnt(0)
	v_add_f32_e32 v36, v36, v40
	v_add_f32_e32 v37, v37, v41
	ds_bpermute_b32 v41, v175, v37
	ds_bpermute_b32 v40, v175, v36
	v_cndmask_b32_e32 v32, v32, v33, vcc
	v_rsq_f32_e32 v34, v32
	v_mul_f32_e32 v96, v10, v10
	v_mul_f32_e32 v97, v11, v11
	v_mul_f32_e32 v38, v38, v180
	s_waitcnt lgkmcnt(0)
	v_add_f32_e32 v32, v36, v40
	v_add_f32_e32 v33, v37, v41
	ds_bpermute_b32 v37, v91, v33
	ds_bpermute_b32 v36, v91, v32
	v_mul_f32_e32 v40, 0x45800000, v34
	v_cndmask_b32_e32 v42, v34, v40, vcc
	v_mul_f32_e32 v104, v35, v42
	v_fma_f32 v96, v2, v2, v96
	v_fma_f32 v97, v3, v3, v97
	s_waitcnt lgkmcnt(0)
	v_add_f32_e32 v32, v32, v36
	v_add_f32_e32 v33, v33, v37
	ds_bpermute_b32 v35, v87, v33
	ds_bpermute_b32 v34, v87, v32
	v_mov_b32_e32 v36, v210
	v_mov_b32_e32 v37, v100
	v_mov_b32_e32 v100, v211
	v_mul_f32_e32 v39, v39, v42
	s_waitcnt lgkmcnt(0)
	v_add_f32_e32 v32, v32, v34
	v_add_f32_e32 v33, v33, v35
	v_mul_f32_e32 v105, v43, v42
	v_fma_f32 v40, v32, s46, v92
	v_fma_f32 v41, v33, s46, v92
	v_mul_f32_e32 v47, v47, v42
	v_mul_f32_e32 v32, 0x4b800000, v41
	v_cmp_gt_f32_e32 vcc, s58, v41
	v_mul_f32_e32 v51, v51, v42
	v_mul_f32_e32 v35, v55, v42
	v_cndmask_b32_e32 v32, v41, v32, vcc
	v_rsq_f32_e32 v32, v32
	v_mul_f32_e32 v41, v59, v42
	v_mul_f32_e32 v55, v63, v42
	v_add_u32_e32 v63, 0x400, v150
	v_mul_f32_e32 v33, 0x45800000, v32
	v_cndmask_b32_e32 v59, v32, v33, vcc
	v_mov_b32_e32 v32, v208
	v_mov_b32_e32 v33, v102
	v_add_f32_e32 v32, v97, v32
	v_add_f32_e32 v33, v96, v33
	v_mov_b32_e32 v102, v209
	v_add_f32_e32 v32, v32, v102
	v_add_f32_e32 v33, v33, v103
	s_lshl_b32 s38, s59, 1
	v_add_f32_e32 v32, v32, v36
	v_add_f32_e32 v33, v33, v37
	v_mul_f32_e32 v46, v46, v180
	v_add_f32_e32 v42, v32, v100
	v_add_f32_e32 v43, v33, v101
	v_lshl_add_u64 v[32:33], s[34:35], 0, v[68:69]
	v_lshlrev_b64 v[32:33], 12, v[32:33]
	v_lshl_add_u64 v[32:33], s[36:37], 0, v[32:33]
	v_mul_f32_e32 v50, v50, v180
	v_mul_f32_e32 v54, v54, v180
	v_mul_f32_e32 v58, v58, v180
	v_mul_f32_e32 v62, v62, v180
	ds_write2_b32 v150, v214, v215 offset1:16
	ds_write2_b32 v150, v177, v184 offset0:128 offset1:144
	ds_write2_b32 v63, v181, v38 offset1:16
	ds_write2_b32 v63, v104, v39 offset0:128 offset1:144
	ds_write2_b32 v150, v216, v44 offset0:32 offset1:48
	ds_write2_b32 v150, v185, v45 offset0:160 offset1:176
	ds_write2_b32 v63, v186, v46 offset0:32 offset1:48
	ds_write2_b32 v63, v105, v47 offset0:160 offset1:176
	ds_write2_b32 v150, v48, v52 offset0:64 offset1:80
	ds_write2_b32 v150, v49, v53 offset0:192 offset1:208
	ds_write2_b32 v63, v50, v54 offset0:64 offset1:80
	ds_write2_b32 v63, v51, v35 offset0:192 offset1:208
	ds_write2st64_b32 v151, v56, v57 offset1:2
	ds_write2st64_b32 v151, v58, v41 offset0:4 offset1:6
	ds_write2st64_b32 v154, v60, v61 offset1:2
	ds_write2st64_b32 v154, v62, v55 offset0:4 offset1:6
	v_lshl_add_u64 v[32:33], v[32:33], 0, s[38:39]
	v_lshl_add_u64 v[32:33], v[32:33], 0, v[64:65]
	global_load_dwordx4 v[36:39], v[32:33], off offset:2048
	v_mov_b32_e32 v98, v31
	v_mov_b32_e32 v99, v7
	v_mul_f32_e32 v98, v98, v98
	v_mul_f32_e32 v99, v99, v99
	v_mov_b32_e32 v45, v94
	v_mov_b32_e32 v44, v98
	v_add_f32_e32 v42, v42, v44
	v_add_f32_e32 v43, v43, v45
	v_mov_b32_e32 v94, v99
	v_add_f32_e32 v42, v42, v94
	v_add_f32_e32 v43, v43, v95
	ds_bpermute_b32 v45, v176, v43
	ds_bpermute_b32 v44, v176, v42
	v_mul_f32_e32 v34, v0, v59
	v_mul_f32_e32 v0, v12, v59
	v_mul_f32_e32 v12, 0x4b800000, v40
	v_cmp_gt_f32_e32 vcc, s58, v40
	s_waitcnt lgkmcnt(0)
	v_add_f32_e32 v42, v42, v44
	v_add_f32_e32 v43, v43, v45
	ds_bpermute_b32 v45, v175, v43
	ds_bpermute_b32 v44, v175, v42
	v_cndmask_b32_e32 v12, v40, v12, vcc
	v_rsq_f32_e32 v12, v12
	v_mul_f32_e32 v48, v4, v59
	v_mul_f32_e32 v46, v20, v59
	s_waitcnt lgkmcnt(0)
	v_add_f32_e32 v40, v42, v44
	v_add_f32_e32 v41, v43, v45
	ds_bpermute_b32 v43, v91, v41
	ds_bpermute_b32 v42, v91, v40
	v_mul_f32_e32 v4, 0x45800000, v12
	v_cndmask_b32_e32 v4, v12, v4, vcc
	v_mul_f32_e32 v49, v13, v4
	v_mul_f32_e32 v35, v16, v59
	s_waitcnt lgkmcnt(0)
	v_add_f32_e32 v40, v40, v42
	v_add_f32_e32 v41, v41, v43
	ds_bpermute_b32 v43, v87, v41
	ds_bpermute_b32 v42, v87, v40
	v_mul_f32_e32 v50, v17, v4
	v_lshl_add_u64 v[16:17], s[34:35], 0, v[70:71]
	v_mul_f32_e32 v1, v1, v4
	v_mul_f32_e32 v9, v9, v4
	s_waitcnt lgkmcnt(0)
	v_add_f32_e32 v12, v40, v42
	v_add_f32_e32 v13, v41, v43
	v_mul_f32_e32 v51, v21, v4
	v_fma_f32 v12, v12, s46, v92
	v_fma_f32 v13, v13, s46, v92
	v_lshlrev_b64 v[16:17], 12, v[16:17]
	v_mul_f32_e32 v20, 0x4b800000, v13
	v_cmp_gt_f32_e32 vcc, s58, v13
	v_mul_f32_e32 v52, v25, v4
	v_mul_f32_e32 v29, v29, v4
	v_cndmask_b32_e32 v13, v13, v20, vcc
	v_rsq_f32_e32 v13, v13
	v_mul_f32_e32 v53, v5, v4
	v_lshl_add_u64 v[16:17], s[36:37], 0, v[16:17]
	v_lshl_add_u64 v[16:17], v[16:17], 0, s[38:39]
	v_mul_f32_e32 v4, 0x45800000, v13
	v_cndmask_b32_e32 v4, v13, v4, vcc
	v_mul_f32_e32 v54, v2, v4
	v_mul_f32_e32 v2, 0x4b800000, v12
	v_cmp_gt_f32_e32 vcc, s58, v12
	v_lshl_add_u64 v[44:45], v[16:17], 0, v[64:65]
	global_load_dwordx4 v[40:43], v[44:45], off offset:2048
	v_cndmask_b32_e32 v2, v12, v2, vcc
	v_rsq_f32_e32 v2, v2
	v_mul_f32_e32 v8, v8, v59
	v_mul_f32_e32 v47, v24, v59
	v_mul_f32_e32 v28, v28, v59
	v_mul_f32_e32 v55, v10, v4
	v_mul_f32_e32 v56, v14, v4
	v_mul_f32_e32 v57, v18, v4
	v_mul_f32_e32 v58, v22, v4
	v_mul_f32_e32 v26, v26, v4
	v_mul_f32_e32 v30, v30, v4
	v_mul_f32_e32 v59, v6, v4
	v_mul_f32_e32 v4, 0x45800000, v2
	v_cndmask_b32_e32 v6, v2, v4, vcc
	v_mul_f32_e32 v60, v3, v6
	v_lshl_add_u64 v[2:3], s[34:35], 0, v[72:73]
	v_lshlrev_b64 v[2:3], 12, v[2:3]
	v_lshl_add_u64 v[2:3], s[36:37], 0, v[2:3]
	v_lshl_add_u64 v[2:3], v[2:3], 0, s[38:39]
	v_mul_f32_e32 v61, v11, v6
	v_mul_f32_e32 v91, v23, v6
	v_lshl_add_u64 v[22:23], v[2:3], 0, v[64:65]
	ds_read_b128 v[10:13], v149
	global_load_dwordx4 v[2:5], v[22:23], off offset:2048
	v_mul_f32_e32 v62, v15, v6
	v_mul_f32_e32 v87, v19, v6
	v_mul_f32_e32 v27, v27, v6
	v_mul_f32_e32 v31, v31, v6
	v_mul_f32_e32 v92, v7, v6
	s_waitcnt vmcnt(2)
	v_and_b32_e32 v7, 0xffff0000, v36
	v_lshlrev_b32_e32 v6, 16, v36
	ds_read_b128 v[14:17], v149 offset:16
	s_waitcnt lgkmcnt(1)
	v_mul_f32_e32 v6, v10, v6
	v_mul_f32_e32 v7, v11, v7
	v_and_b32_e32 v11, 0xffff0000, v37
	v_bfe_u32 v24, v7, 16, 1
	v_bfe_u32 v25, v6, 16, 1
	v_add3_u32 v25, v6, v25, s47
	v_add3_u32 v24, v7, v24, s47
	v_lshl_add_u64 v[6:7], s[34:35], 0, v[74:75]
	v_lshlrev_b32_e32 v10, 16, v37
	v_lshlrev_b64 v[6:7], 12, v[6:7]
	v_mul_f32_e32 v10, v12, v10
	v_mul_f32_e32 v11, v13, v11
	v_and_b32_e32 v13, 0xffff0000, v38
	v_lshlrev_b32_e32 v12, 16, v38
	v_lshl_add_u64 v[6:7], s[36:37], 0, v[6:7]
	s_waitcnt lgkmcnt(0)
	v_mul_f32_e32 v12, v14, v12
	v_mul_f32_e32 v13, v15, v13
	v_lshl_add_u64 v[6:7], v[6:7], 0, s[38:39]
	v_bfe_u32 v18, v13, 16, 1
	v_bfe_u32 v19, v12, 16, 1
	v_bfe_u32 v20, v11, 16, 1
	v_bfe_u32 v21, v10, 16, 1
	v_lshl_add_u64 v[6:7], v[6:7], 0, v[64:65]
	v_add3_u32 v21, v10, v21, s47
	v_add3_u32 v20, v11, v20, s47
	v_add3_u32 v19, v12, v19, s47
	v_add3_u32 v18, v13, v18, s47
	global_load_dwordx4 v[10:13], v[6:7], off offset:2048
	v_and_b32_e32 v15, 0xffff0000, v39
	v_lshlrev_b32_e32 v14, 16, v39
	v_mul_f32_e32 v14, v16, v14
	v_mul_f32_e32 v15, v17, v15
	s_add_i32 s30, s30, s3
	v_cvt_pk_bf16_f32 v17, v14, v15
	v_perm_b32 v16, v18, v19, s33
	v_perm_b32 v15, v20, v21, s33
	ds_read_b128 v[18:21], v157
	v_perm_b32 v14, v24, v25, s33
	global_store_dwordx4 v[32:33], v[14:17], off offset:2048
	ds_read_b128 v[14:17], v157 offset:16
	s_cmpk_lt_i32 s30, 0x400
	s_waitcnt vmcnt(3)
	v_and_b32_e32 v25, 0xffff0000, v40
	v_lshlrev_b32_e32 v24, 16, v40
	s_waitcnt lgkmcnt(1)
	v_mul_f32_e32 v18, v18, v24
	v_mul_f32_e32 v19, v19, v25
	v_and_b32_e32 v25, 0xffff0000, v41
	v_lshlrev_b32_e32 v24, 16, v41
	v_mul_f32_e32 v20, v20, v24
	v_mul_f32_e32 v21, v21, v25
	v_and_b32_e32 v25, 0xffff0000, v42
	v_lshlrev_b32_e32 v24, 16, v42
	s_waitcnt lgkmcnt(0)
	v_mul_f32_e32 v14, v14, v24
	v_mul_f32_e32 v15, v15, v25
	v_and_b32_e32 v25, 0xffff0000, v43
	v_lshlrev_b32_e32 v24, 16, v43
	v_mul_f32_e32 v16, v16, v24
	v_mul_f32_e32 v17, v17, v25
	v_cvt_pk_bf16_f32 v17, v16, v17
	v_cvt_pk_bf16_f32 v16, v14, v15
	v_cvt_pk_bf16_f32 v15, v20, v21
	v_cvt_pk_bf16_f32 v14, v18, v19
	ds_read_b128 v[18:21], v158
	global_store_dwordx4 v[44:45], v[14:17], off offset:2048
	ds_read_b128 v[14:17], v158 offset:16
	s_waitcnt vmcnt(3)
	v_and_b32_e32 v25, 0xffff0000, v2
	v_lshlrev_b32_e32 v24, 16, v2
	s_waitcnt lgkmcnt(1)
	v_mul_f32_e32 v18, v18, v24
	v_mul_f32_e32 v19, v19, v25
	v_and_b32_e32 v25, 0xffff0000, v3
	v_lshlrev_b32_e32 v24, 16, v3
	v_mul_f32_e32 v2, v20, v24
	v_mul_f32_e32 v3, v21, v25
	v_and_b32_e32 v21, 0xffff0000, v4
	v_lshlrev_b32_e32 v20, 16, v4
	s_waitcnt lgkmcnt(0)
	v_mul_f32_e32 v14, v14, v20
	v_mul_f32_e32 v15, v15, v21
	v_and_b32_e32 v21, 0xffff0000, v5
	v_lshlrev_b32_e32 v20, 16, v5
	v_mul_f32_e32 v4, v16, v20
	v_mul_f32_e32 v5, v17, v21
	v_cvt_pk_bf16_f32 v5, v4, v5
	v_cvt_pk_bf16_f32 v4, v14, v15
	ds_read_b128 v[14:17], v159
	v_cvt_pk_bf16_f32 v3, v2, v3
	v_cvt_pk_bf16_f32 v2, v18, v19
	global_store_dwordx4 v[22:23], v[2:5], off offset:2048
	ds_read_b128 v[2:5], v159 offset:16
	s_waitcnt vmcnt(3)
	v_and_b32_e32 v19, 0xffff0000, v10
	v_lshlrev_b32_e32 v18, 16, v10
	s_waitcnt lgkmcnt(1)
	v_mul_f32_e32 v14, v14, v18
	v_mul_f32_e32 v15, v15, v19
	v_and_b32_e32 v19, 0xffff0000, v11
	v_lshlrev_b32_e32 v18, 16, v11
	v_mul_f32_e32 v10, v16, v18
	v_mul_f32_e32 v11, v17, v19
	v_and_b32_e32 v17, 0xffff0000, v12
	v_lshlrev_b32_e32 v16, 16, v12
	s_waitcnt lgkmcnt(0)
	v_mul_f32_e32 v2, v2, v16
	v_mul_f32_e32 v3, v3, v17
	v_and_b32_e32 v17, 0xffff0000, v13
	v_lshlrev_b32_e32 v16, 16, v13
	v_mul_f32_e32 v4, v4, v16
	v_mul_f32_e32 v5, v5, v17
	v_cvt_pk_bf16_f32 v5, v4, v5
	v_cvt_pk_bf16_f32 v4, v2, v3
	v_cvt_pk_bf16_f32 v3, v10, v11
	v_cvt_pk_bf16_f32 v2, v14, v15
	global_store_dwordx4 v[6:7], v[2:5], off offset:2048
	ds_write2_b32 v150, v34, v8 offset1:16
	ds_write2_b32 v150, v1, v9 offset0:128 offset1:144
	ds_write2_b32 v63, v54, v55 offset1:16
	ds_write2_b32 v63, v60, v61 offset0:128 offset1:144
	ds_write2_b32 v150, v0, v35 offset0:32 offset1:48
	ds_write2_b32 v150, v49, v50 offset0:160 offset1:176
	ds_write2_b32 v63, v56, v57 offset0:32 offset1:48
	ds_write2_b32 v63, v62, v87 offset0:160 offset1:176
	ds_write2_b32 v150, v46, v47 offset0:64 offset1:80
	ds_write2_b32 v150, v51, v52 offset0:192 offset1:208
	ds_write2_b32 v63, v58, v26 offset0:64 offset1:80
	ds_write2_b32 v63, v91, v27 offset0:192 offset1:208
	ds_write2st64_b32 v151, v28, v29 offset1:2
	ds_write2st64_b32 v151, v30, v31 offset0:4 offset1:6
	ds_write2st64_b32 v154, v48, v53 offset1:2
	ds_write2st64_b32 v154, v59, v92 offset0:4 offset1:6
	v_lshl_add_u64 v[0:1], s[34:35], 0, v[76:77]
	v_lshlrev_b64 v[0:1], 12, v[0:1]
	v_lshl_add_u64 v[0:1], s[36:37], 0, v[0:1]
	v_lshl_add_u64 v[0:1], v[0:1], 0, s[38:39]
	v_lshl_add_u64 v[20:21], v[0:1], 0, v[64:65]
	global_load_dwordx4 v[0:3], v[20:21], off offset:2048
	v_lshl_add_u64 v[4:5], s[34:35], 0, v[78:79]
	v_lshlrev_b64 v[4:5], 12, v[4:5]
	v_lshl_add_u64 v[4:5], s[36:37], 0, v[4:5]
	v_lshl_add_u64 v[4:5], v[4:5], 0, s[38:39]
	v_lshl_add_u64 v[22:23], v[4:5], 0, v[64:65]
	global_load_dwordx4 v[4:7], v[22:23], off offset:2048
	v_lshl_add_u64 v[8:9], s[34:35], 0, v[80:81]
	v_lshlrev_b64 v[8:9], 12, v[8:9]
	v_lshl_add_u64 v[8:9], s[36:37], 0, v[8:9]
	v_lshl_add_u64 v[8:9], v[8:9], 0, s[38:39]
	v_lshl_add_u64 v[24:25], v[8:9], 0, v[64:65]
	global_load_dwordx4 v[8:11], v[24:25], off offset:2048
	ds_read_b128 v[12:15], v149
	ds_read_b128 v[16:19], v149 offset:16
	s_waitcnt vmcnt(2)
	v_and_b32_e32 v27, 0xffff0000, v0
	v_lshlrev_b32_e32 v26, 16, v0
	s_waitcnt lgkmcnt(1)
	v_mul_f32_e32 v12, v12, v26
	v_mul_f32_e32 v13, v13, v27
	v_and_b32_e32 v27, 0xffff0000, v1
	v_lshlrev_b32_e32 v26, 16, v1
	v_mul_f32_e32 v0, v14, v26
	v_mul_f32_e32 v1, v15, v27
	v_bfe_u32 v28, v13, 16, 1
	v_bfe_u32 v26, v1, 16, 1
	v_bfe_u32 v27, v0, 16, 1
	v_bfe_u32 v29, v12, 16, 1
	v_add3_u32 v12, v12, v29, s47
	v_add3_u32 v28, v13, v28, s47
	v_add3_u32 v13, v0, v27, s47
	v_add3_u32 v29, v1, v26, s47
	v_lshl_add_u64 v[0:1], s[34:35], 0, v[82:83]
	v_lshlrev_b64 v[0:1], 12, v[0:1]
	v_and_b32_e32 v15, 0xffff0000, v2
	v_lshlrev_b32_e32 v14, 16, v2
	v_lshl_add_u64 v[0:1], s[36:37], 0, v[0:1]
	s_waitcnt lgkmcnt(0)
	v_mul_f32_e32 v14, v16, v14
	v_mul_f32_e32 v15, v17, v15
	v_lshl_add_u64 v[0:1], v[0:1], 0, s[38:39]
	v_and_b32_e32 v17, 0xffff0000, v3
	v_lshlrev_b32_e32 v16, 16, v3
	v_lshl_add_u64 v[26:27], v[0:1], 0, v[64:65]
	global_load_dwordx4 v[0:3], v[26:27], off offset:2048
	v_mul_f32_e32 v16, v18, v16
	v_mul_f32_e32 v17, v19, v17
	v_cvt_pk_bf16_f32 v14, v14, v15
	v_bfe_u32 v18, v17, 16, 1
	v_bfe_u32 v19, v16, 16, 1
	v_add3_u32 v15, v16, v19, s47
	v_add3_u32 v16, v17, v18, s47
	v_perm_b32 v15, v16, v15, s33
	ds_read_b128 v[16:19], v157
	v_perm_b32 v13, v29, v13, s33
	v_perm_b32 v12, v28, v12, s33
	global_store_dwordx4 v[20:21], v[12:15], off offset:2048
	ds_read_b128 v[12:15], v157 offset:16
	s_waitcnt vmcnt(3)
	v_and_b32_e32 v21, 0xffff0000, v4
	v_lshlrev_b32_e32 v20, 16, v4
	s_waitcnt lgkmcnt(1)
	v_mul_f32_e32 v16, v16, v20
	v_mul_f32_e32 v17, v17, v21
	v_and_b32_e32 v21, 0xffff0000, v5
	v_lshlrev_b32_e32 v20, 16, v5
	v_mul_f32_e32 v4, v18, v20
	v_mul_f32_e32 v5, v19, v21
	v_and_b32_e32 v19, 0xffff0000, v6
	v_lshlrev_b32_e32 v18, 16, v6
	s_waitcnt lgkmcnt(0)
	v_mul_f32_e32 v12, v12, v18
	v_mul_f32_e32 v13, v13, v19
	v_and_b32_e32 v19, 0xffff0000, v7
	v_lshlrev_b32_e32 v18, 16, v7
	v_mul_f32_e32 v6, v14, v18
	v_mul_f32_e32 v7, v15, v19
	v_cvt_pk_bf16_f32 v7, v6, v7
	v_cvt_pk_bf16_f32 v6, v12, v13
	ds_read_b128 v[12:15], v158
	v_cvt_pk_bf16_f32 v5, v4, v5
	v_cvt_pk_bf16_f32 v4, v16, v17
	global_store_dwordx4 v[22:23], v[4:7], off offset:2048
	ds_read_b128 v[4:7], v158 offset:16
	s_waitcnt vmcnt(3)
	v_and_b32_e32 v17, 0xffff0000, v8
	v_lshlrev_b32_e32 v16, 16, v8
	s_waitcnt lgkmcnt(1)
	v_mul_f32_e32 v12, v12, v16
	v_mul_f32_e32 v13, v13, v17
	v_and_b32_e32 v17, 0xffff0000, v9
	v_lshlrev_b32_e32 v16, 16, v9
	v_mul_f32_e32 v8, v14, v16
	v_mul_f32_e32 v9, v15, v17
	v_and_b32_e32 v15, 0xffff0000, v10
	v_lshlrev_b32_e32 v14, 16, v10
	s_waitcnt lgkmcnt(0)
	v_mul_f32_e32 v4, v4, v14
	v_mul_f32_e32 v5, v5, v15
	v_and_b32_e32 v15, 0xffff0000, v11
	v_lshlrev_b32_e32 v14, 16, v11
	v_mul_f32_e32 v6, v6, v14
	v_mul_f32_e32 v7, v7, v15
	v_cvt_pk_bf16_f32 v7, v6, v7
	v_cvt_pk_bf16_f32 v6, v4, v5
	v_cvt_pk_bf16_f32 v5, v8, v9
	ds_read_b128 v[8:11], v159
	v_cvt_pk_bf16_f32 v4, v12, v13
	global_store_dwordx4 v[24:25], v[4:7], off offset:2048
	ds_read_b128 v[4:7], v159 offset:16
	s_waitcnt vmcnt(3)
	v_and_b32_e32 v13, 0xffff0000, v0
	v_lshlrev_b32_e32 v12, 16, v0
	s_waitcnt lgkmcnt(1)
	v_mul_f32_e32 v8, v8, v12
	v_mul_f32_e32 v9, v9, v13
	v_and_b32_e32 v13, 0xffff0000, v1
	v_lshlrev_b32_e32 v12, 16, v1
	v_mul_f32_e32 v0, v10, v12
	v_mul_f32_e32 v1, v11, v13
	v_and_b32_e32 v11, 0xffff0000, v2
	v_lshlrev_b32_e32 v10, 16, v2
	s_waitcnt lgkmcnt(0)
	v_mul_f32_e32 v4, v4, v10
	v_mul_f32_e32 v5, v5, v11
	v_and_b32_e32 v11, 0xffff0000, v3
	v_lshlrev_b32_e32 v10, 16, v3
	v_mul_f32_e32 v2, v6, v10
	v_mul_f32_e32 v3, v7, v11
	v_cvt_pk_bf16_f32 v3, v2, v3
	v_cvt_pk_bf16_f32 v2, v4, v5
	v_cvt_pk_bf16_f32 v1, v0, v1
	v_cvt_pk_bf16_f32 v0, v8, v9
	global_store_dwordx4 v[26:27], v[0:3], off offset:2048
	s_cbranch_scc1 .LBB0_624
	v_readlane_b32 s96, v247, 7
	v_readlane_b32 s54, v247, 5
	v_readlane_b32 s97, v247, 8
	v_readlane_b32 s55, v247, 6

.LBB0_687:
	s_and_b32 s40, s4, 0x8000
	s_add_i32 s41, s4, 0xffff8000
	v_or_b32_e32 v126, s40, v129
	v_lshl_add_u64 v[68:69], v[66:67], 0, s[30:31]
	s_and_b32 s41, s41, 0x8000
	v_readfirstlane_b32 s42, v126
	v_add_u32_e32 v127, 0x1000, v126
	v_lshl_add_u64 v[72:73], v[68:69], 0, s[10:11]
	v_add_u32_e32 v128, 0x2000, v126
	v_or_b32_e32 v134, s41, v101
	v_or_b32_e32 v135, s41, v103
	v_readfirstlane_b32 s41, v127
	s_mov_b32 m0, s42
	s_waitcnt vmcnt(0)
	s_barrier
	v_lshl_add_u64 v[74:75], v[68:69], 0, s[12:13]
	v_add_u32_e32 v130, 0x3000, v126
	v_readfirstlane_b32 s43, v128
	global_load_lds_dwordx4 v[72:73], off
	s_mov_b32 m0, s41
	v_lshl_add_u64 v[118:119], v[68:69], 0, s[14:15]
	v_or_b32_e32 v131, 0x4000, v126
	v_readfirstlane_b32 s44, v130
	global_load_lds_dwordx4 v[74:75], off
	s_mov_b32 m0, s43
	v_lshl_add_u64 v[70:71], v[64:65], 0, s[30:31]
	v_lshl_add_u64 v[68:69], v[68:69], 0, s[16:17]
	v_add_u32_e32 v132, 0x5000, v126
	v_readfirstlane_b32 s45, v131
	global_load_lds_dwordx4 v[118:119], off
	s_mov_b32 m0, s44
	v_lshl_add_u64 v[120:121], v[70:71], 0, s[18:19]
	v_add_u32_e32 v133, 0x6000, v126
	v_readfirstlane_b32 s46, v132
	global_load_lds_dwordx4 v[68:69], off
	s_mov_b32 m0, s45
	v_lshl_add_u64 v[122:123], v[70:71], 0, s[20:21]
	v_add_u32_e32 v126, 0x7000, v126
	v_readfirstlane_b32 s47, v133
	global_load_lds_dwordx4 v[120:121], off
	s_mov_b32 m0, s46
	v_lshl_add_u64 v[124:125], v[70:71], 0, s[22:23]
	v_readfirstlane_b32 s48, v126
	global_load_lds_dwordx4 v[122:123], off
	s_mov_b32 m0, s47
	v_lshl_add_u64 v[70:71], v[70:71], 0, s[24:25]
	global_load_lds_dwordx4 v[124:125], off
	s_mov_b32 m0, s48
	v_add_u32_e32 v126, v134, v102
	global_load_lds_dwordx4 v[70:71], off
	v_add_u32_e32 v127, v134, v100
	ds_read_b128 v[68:71], v126
	ds_read_b128 v[72:75], v127 offset:16384
	ds_read_b128 v[118:121], v127 offset:18432
	ds_read_b128 v[122:125], v127 offset:20480
	ds_read_b128 v[130:133], v126 offset:2048
	v_add_u32_e32 v128, v135, v102
	v_add_u32_e32 v190, v135, v100
	ds_read_b128 v[134:137], v127 offset:22528
	ds_read_b128 v[138:141], v127 offset:24576
	ds_read_b128 v[142:145], v127 offset:26624
	ds_read_b128 v[146:149], v127 offset:28672
	ds_read_b128 v[150:153], v127 offset:30720
	ds_read_b128 v[154:157], v128
	ds_read_b128 v[158:161], v128 offset:2048
	ds_read_b128 v[162:165], v190 offset:16384
	ds_read_b128 v[166:169], v190 offset:18432
	ds_read_b128 v[170:173], v190 offset:20480
	ds_read_b128 v[174:177], v190 offset:22528
	ds_read_b128 v[178:181], v190 offset:24576
	ds_read_b128 v[182:185], v190 offset:26624
	ds_read_b128 v[186:189], v190 offset:28672
	ds_read_b128 v[190:193], v190 offset:30720
	s_waitcnt lgkmcnt(0)
	v_mfma_f32_16x16x32_bf16 v[44:47], v[68:71], v[72:75], v[44:47]
	s_add_u32 s30, s30, 0x80
	s_addc_u32 s31, s31, 0
	s_add_i32 s4, s4, 0x8000
	v_mfma_f32_16x16x32_bf16 v[28:31], v[68:71], v[118:121], v[28:31]
	s_cmpk_eq_i32 s30, 0xf80
	v_mfma_f32_16x16x32_bf16 v[60:63], v[68:71], v[122:125], v[60:63]
	v_mfma_f32_16x16x32_bf16 v[20:23], v[68:71], v[134:137], v[20:23]
	v_mfma_f32_16x16x32_bf16 v[52:55], v[68:71], v[138:141], v[52:55]
	v_mfma_f32_16x16x32_bf16 v[24:27], v[68:71], v[142:145], v[24:27]
	v_mfma_f32_16x16x32_bf16 v[56:59], v[68:71], v[146:149], v[56:59]
	v_mfma_f32_16x16x32_bf16 v[12:15], v[68:71], v[150:153], v[12:15]
	v_mfma_f32_16x16x32_bf16 v[48:51], v[130:133], v[72:75], v[48:51]
	v_mfma_f32_16x16x32_bf16 v[16:19], v[130:133], v[118:121], v[16:19]
	v_mfma_f32_16x16x32_bf16 v[40:43], v[130:133], v[122:125], v[40:43]
	v_mfma_f32_16x16x32_bf16 v[0:3], v[130:133], v[134:137], v[0:3]
	v_mfma_f32_16x16x32_bf16 v[36:39], v[130:133], v[138:141], v[36:39]
	v_mfma_f32_16x16x32_bf16 v[8:11], v[130:133], v[142:145], v[8:11]
	v_mfma_f32_16x16x32_bf16 v[32:35], v[130:133], v[146:149], v[32:35]
	v_mfma_f32_16x16x32_bf16 v[4:7], v[130:133], v[150:153], v[4:7]
	v_mfma_f32_16x16x32_bf16 v[44:47], v[154:157], v[162:165], v[44:47]
	v_mfma_f32_16x16x32_bf16 v[28:31], v[154:157], v[166:169], v[28:31]
	v_mfma_f32_16x16x32_bf16 v[60:63], v[154:157], v[170:173], v[60:63]
	v_mfma_f32_16x16x32_bf16 v[20:23], v[154:157], v[174:177], v[20:23]
	v_mfma_f32_16x16x32_bf16 v[52:55], v[154:157], v[178:181], v[52:55]
	v_mfma_f32_16x16x32_bf16 v[24:27], v[154:157], v[182:185], v[24:27]
	v_mfma_f32_16x16x32_bf16 v[56:59], v[154:157], v[186:189], v[56:59]
	v_mfma_f32_16x16x32_bf16 v[12:15], v[154:157], v[190:193], v[12:15]
	v_mfma_f32_16x16x32_bf16 v[48:51], v[158:161], v[162:165], v[48:51]
	v_mfma_f32_16x16x32_bf16 v[16:19], v[158:161], v[166:169], v[16:19]
	v_mfma_f32_16x16x32_bf16 v[40:43], v[158:161], v[170:173], v[40:43]
	v_mfma_f32_16x16x32_bf16 v[0:3], v[158:161], v[174:177], v[0:3]
	v_mfma_f32_16x16x32_bf16 v[36:39], v[158:161], v[178:181], v[36:39]
	v_mfma_f32_16x16x32_bf16 v[8:11], v[158:161], v[182:185], v[8:11]
	v_mfma_f32_16x16x32_bf16 v[32:35], v[158:161], v[186:189], v[32:35]
	v_mfma_f32_16x16x32_bf16 v[4:7], v[158:161], v[190:193], v[4:7]
	s_cbranch_scc0 .LBB0_687
	v_add_u32_e32 v68, s40, v101
	v_add_u32_e32 v69, v68, v102
	s_waitcnt vmcnt(0)
	s_barrier
	ds_read_b128 v[64:67], v69
	v_add_u32_e32 v126, v68, v100
	ds_read_b128 v[72:75], v126 offset:16384
	ds_read_b128 v[118:121], v126 offset:20480
	ds_read_b128 v[122:125], v126 offset:24576
	s_ashr_i32 s39, s39, 5
	s_mul_hi_i32 s4, s39, 0x3000
	s_waitcnt lgkmcnt(0)
	v_mfma_f32_16x16x32_bf16 v[130:133], v[64:67], v[72:75], v[44:47]
	v_add_u32_e32 v128, 0x400, v105
	s_nop 1
	ds_read_b128 v[44:47], v69 offset:2048
	v_mfma_f32_16x16x32_bf16 v[134:137], v[64:67], v[118:121], v[60:63]
	ds_read_b128 v[68:71], v126 offset:18432
	v_mfma_f32_16x16x32_bf16 v[138:141], v[64:67], v[122:125], v[52:55]
	s_nop 2
	ds_read_b128 v[52:55], v126 offset:22528
	s_waitcnt lgkmcnt(0)
	v_mfma_f32_16x16x32_bf16 v[48:51], v[44:47], v[72:75], v[48:51]
	ds_read_b128 v[72:75], v126 offset:26624
	v_mfma_f32_16x16x32_bf16 v[118:121], v[44:47], v[118:121], v[40:43]
	ds_read_b128 v[142:145], v126 offset:28672
	s_waitcnt lgkmcnt(0)
	v_mfma_f32_16x16x32_bf16 v[56:59], v[64:67], v[142:145], v[56:59]
	ds_read_b128 v[40:43], v126 offset:30720
	v_mfma_f32_16x16x32_bf16 v[122:125], v[44:47], v[122:125], v[36:39]
	s_nop 2
	v_add_u32_e32 v36, s40, v103
	v_add_u32_e32 v37, v36, v102
	ds_read_b128 v[60:63], v37
	v_mfma_f32_16x16x32_bf16 v[142:145], v[44:47], v[142:145], v[32:35]
	v_add_u32_e32 v126, v36, v100
	s_mul_i32 s40, s39, 0x3000
	s_add_u32 s30, s33, s40
	ds_read_b128 v[32:35], v37 offset:2048
	v_mfma_f32_16x16x32_bf16 v[146:149], v[64:67], v[68:71], v[28:31]
	s_addc_u32 s31, s34, s4
	s_lshl_b32 s4, s38, 9
	s_add_u32 s30, s30, s4
	ds_read_b128 v[28:31], v126 offset:16384
	s_waitcnt lgkmcnt(0)
	v_mfma_f32_16x16x32_bf16 v[130:133], v[60:63], v[28:31], v[130:133]
	ds_read_b128 v[150:153], v126 offset:18432
	s_addc_u32 s31, s31, 0
	v_mfma_f32_16x16x32_bf16 v[28:31], v[32:35], v[28:31], v[48:51]
	ds_read_b128 v[36:39], v126 offset:20480
	s_waitcnt lgkmcnt(0)
	v_mfma_f32_16x16x32_bf16 v[134:137], v[60:63], v[36:39], v[134:137]
	ds_read_b128 v[154:157], v126 offset:22528
	v_mfma_f32_16x16x32_bf16 v[36:39], v[32:35], v[36:39], v[118:121]
	ds_read_b128 v[48:51], v126 offset:24576
	s_waitcnt lgkmcnt(0)
	v_mfma_f32_16x16x32_bf16 v[118:121], v[60:63], v[48:51], v[138:141]
	s_nop 2
	ds_read_b128 v[138:141], v126 offset:26624
	v_mfma_f32_16x16x32_bf16 v[48:51], v[32:35], v[48:51], v[122:125]
	s_nop 2
	ds_read_b128 v[122:125], v126 offset:28672
	s_waitcnt lgkmcnt(0)
	v_mfma_f32_16x16x32_bf16 v[158:161], v[60:63], v[122:125], v[56:59]
	ds_read_b128 v[162:165], v126 offset:30720
	s_barrier
	v_mfma_f32_16x16x32_bf16 v[56:59], v[32:35], v[122:125], v[142:145]
	v_mfma_f32_16x16x32_bf16 v[24:27], v[64:67], v[72:75], v[24:27]
	v_mfma_f32_16x16x32_bf16 v[16:19], v[44:47], v[68:71], v[16:19]
	v_mfma_f32_16x16x32_bf16 v[8:11], v[44:47], v[72:75], v[8:11]
	v_mfma_f32_16x16x32_bf16 v[68:71], v[60:63], v[150:153], v[146:149]
	v_mfma_f32_16x16x32_bf16 v[24:27], v[60:63], v[138:141], v[24:27]
	v_mfma_f32_16x16x32_bf16 v[16:19], v[32:35], v[150:153], v[16:19]
	v_mfma_f32_16x16x32_bf16 v[8:11], v[32:35], v[138:141], v[8:11]
	v_mfma_f32_16x16x32_bf16 v[20:23], v[64:67], v[52:55], v[20:23]
	v_mfma_f32_16x16x32_bf16 v[12:15], v[64:67], v[40:43], v[12:15]
	v_lshl_add_u64 v[64:65], s[30:31], 0, v[76:77]
	s_add_i32 s30, s39, 4
	s_add_i32 s31, s40, 0xc000
	s_mul_hi_i32 s30, s30, 0x3000
	s_add_u32 s31, s33, s31
	s_addc_u32 s38, s34, s30
	v_lshl_add_u64 v[66:67], v[64:65], 0, s[26:27]
	v_add_co_u32_e32 v64, vcc, s37, v64
	s_add_u32 s30, s31, s4
	s_nop 0
	v_addc_co_u32_e32 v65, vcc, 0, v65, vcc
	s_addc_u32 s31, s38, 0
	v_mfma_f32_16x16x32_bf16 v[20:23], v[60:63], v[154:157], v[20:23]
	s_waitcnt lgkmcnt(0)
	v_mfma_f32_16x16x32_bf16 v[12:15], v[60:63], v[162:165], v[12:15]
	ds_write2_b32 v105, v130, v68 offset1:16
	global_load_dwordx4 v[60:63], v[64:65], off
	ds_write2_b32 v105, v131, v69 offset0:128 offset1:144
	v_lshl_add_u64 v[68:69], s[30:31], 0, v[76:77]
	s_add_i32 s30, s39, 8
	s_add_i32 s31, s40, 0x18000
	s_mul_hi_i32 s30, s30, 0x3000
	s_add_u32 s31, s33, s31
	s_addc_u32 s38, s34, s30
	v_lshl_add_u64 v[122:123], v[68:69], 0, s[26:27]
	v_add_co_u32_e32 v68, vcc, s37, v68
	s_add_u32 s30, s31, s4
	s_nop 0
	v_addc_co_u32_e32 v69, vcc, 0, v69, vcc
	s_addc_u32 s31, s38, 0
	global_load_dwordx4 v[64:67], v[66:67], off offset:16
	ds_write2_b32 v128, v132, v70 offset1:16
	global_load_dwordx4 v[72:75], v[68:69], off
	ds_write2_b32 v128, v133, v71 offset0:128 offset1:144
	global_load_dwordx4 v[68:71], v[122:123], off offset:16
	v_lshl_add_u64 v[122:123], s[30:31], 0, v[76:77]
	s_add_i32 s30, s39, 12
	s_add_i32 s31, s40, 0x24000
	s_mul_hi_i32 s30, s30, 0x3000
	s_add_u32 s31, s33, s31
	s_addc_u32 s38, s34, s30
	v_lshl_add_u64 v[126:127], v[122:123], 0, s[26:27]
	v_add_co_u32_e32 v122, vcc, s37, v122
	s_add_u32 s30, s31, s4
	s_nop 0
	v_addc_co_u32_e32 v123, vcc, 0, v123, vcc
	s_addc_u32 s31, s38, 0
	ds_write2_b32 v105, v134, v20 offset0:32 offset1:48
	global_load_dwordx4 v[122:125], v[122:123], off
	ds_write2_b32 v105, v135, v21 offset0:160 offset1:176
	v_lshl_add_u64 v[20:21], s[30:31], 0, v[76:77]
	s_add_i32 s30, s39, 16
	s_add_i32 s31, s40, 0x30000
	s_mul_hi_i32 s30, s30, 0x3000
	s_add_u32 s31, s33, s31
	s_addc_u32 s38, s34, s30
	global_load_dwordx4 v[130:133], v[126:127], off offset:16
	v_lshl_add_u64 v[126:127], v[20:21], 0, s[26:27]
	v_add_co_u32_e32 v20, vcc, s37, v20
	s_add_u32 s30, s31, s4
	s_nop 0
	v_addc_co_u32_e32 v21, vcc, 0, v21, vcc
	s_addc_u32 s31, s38, 0
	ds_write2_b32 v128, v136, v22 offset0:32 offset1:48
	global_load_dwordx4 v[138:141], v[20:21], off
	ds_write2_b32 v128, v137, v23 offset0:160 offset1:176
	global_load_dwordx4 v[20:23], v[126:127], off offset:16
	v_lshl_add_u64 v[126:127], s[30:31], 0, v[76:77]
	s_add_i32 s30, s39, 20
	s_add_i32 s31, s40, 0x3c000
	s_mul_hi_i32 s30, s30, 0x3000
	s_add_u32 s31, s33, s31
	s_addc_u32 s38, s34, s30
	v_lshl_add_u64 v[142:143], v[126:127], 0, s[26:27]
	v_add_co_u32_e32 v126, vcc, s37, v126
	s_add_u32 s30, s31, s4
	s_nop 0
	v_addc_co_u32_e32 v127, vcc, 0, v127, vcc
	s_addc_u32 s31, s38, 0
	ds_write2_b32 v105, v118, v24 offset0:64 offset1:80
	global_load_dwordx4 v[134:137], v[126:127], off
	ds_write2_b32 v105, v119, v25 offset0:192 offset1:208
	v_lshl_add_u64 v[24:25], s[30:31], 0, v[76:77]
	s_add_i32 s30, s39, 24
	s_add_i32 s31, s40, 0x48000
	s_mul_hi_i32 s30, s30, 0x3000
	s_add_u32 s31, s33, s31
	s_addc_u32 s38, s34, s30
	v_lshl_add_u64 v[118:119], v[24:25], 0, s[26:27]
	v_add_co_u32_e32 v24, vcc, s37, v24
	s_add_u32 s30, s31, s4
	s_nop 0
	v_addc_co_u32_e32 v25, vcc, 0, v25, vcc
	s_addc_u32 s31, s38, 0
	s_add_i32 s39, s39, 28
	s_add_i32 s40, s40, 0x54000
	global_load_dwordx4 v[142:145], v[142:143], off offset:16
	ds_write2_b32 v128, v120, v26 offset0:64 offset1:80
	global_load_dwordx4 v[146:149], v[24:25], off
	ds_write2_b32 v128, v121, v27 offset0:192 offset1:208
	global_load_dwordx4 v[24:27], v[118:119], off offset:16
	v_lshl_add_u64 v[118:119], s[30:31], 0, v[76:77]
	s_mul_hi_i32 s30, s39, 0x3000
	s_add_u32 s31, s33, s40
	s_addc_u32 s38, s34, s30
	v_lshl_add_u64 v[126:127], v[118:119], 0, s[26:27]
	v_add_co_u32_e32 v118, vcc, s37, v118
	s_add_u32 s30, s31, s4
	s_nop 0
	v_addc_co_u32_e32 v119, vcc, 0, v119, vcc
	s_addc_u32 s31, s38, 0
	ds_write2st64_b32 v106, v158, v159 offset1:2
	global_load_dwordx4 v[118:121], v[118:119], off
	ds_write2st64_b32 v106, v160, v161 offset0:4 offset1:6
	global_load_dwordx4 v[150:153], v[126:127], off offset:16
	v_lshl_add_u64 v[126:127], s[30:31], 0, v[76:77]
	v_lshl_add_u64 v[166:167], v[126:127], 0, s[26:27]
	v_add_co_u32_e32 v126, vcc, s37, v126
	ds_write2st64_b32 v107, v12, v13 offset1:2
	s_nop 0
	v_addc_co_u32_e32 v127, vcc, 0, v127, vcc
	global_load_dwordx4 v[158:161], v[126:127], off
	ds_write2st64_b32 v107, v14, v15 offset0:4 offset1:6
	global_load_dwordx4 v[12:15], v[166:167], off offset:16
	v_mfma_f32_16x16x32_bf16 v[0:3], v[44:47], v[52:55], v[0:3]
	v_lshl_add_u64 v[126:127], v[82:83], 0, s[28:29]
	v_lshl_add_u64 v[126:127], v[126:127], 0, s[4:5]
	v_mfma_f32_16x16x32_bf16 v[4:7], v[44:47], v[40:43], v[4:7]
	s_waitcnt vmcnt(0)
	v_add_f32_e32 v62, 0, v62
	v_add_f32_e32 v63, 0, v63
	v_add_f32_e32 v60, 0, v60
	v_add_f32_e32 v61, 0, v61
	v_add_f32_e32 v66, 0, v66
	v_add_f32_e32 v67, 0, v67
	v_mfma_f32_16x16x32_bf16 v[0:3], v[32:35], v[154:157], v[0:3]
	v_add_f32_e64 v64, v64, 0
	v_add_f32_e64 v65, v65, 0
	v_add_f32_e32 v62, v62, v74
	v_add_f32_e32 v63, v63, v75
	v_add_f32_e32 v60, v60, v72
	v_add_f32_e32 v61, v61, v73
	v_mfma_f32_16x16x32_bf16 v[4:7], v[32:35], v[162:165], v[4:7]
	ds_read_b128 v[32:35], v104
	ds_read_b128 v[154:157], v104 offset:16
	ds_read_b128 v[174:177], v108
	ds_read_b128 v[166:169], v110 offset:16
	ds_read_b128 v[170:173], v110
	ds_read_b128 v[52:55], v109 offset:16
	ds_read_b128 v[40:43], v109
	ds_read_b128 v[44:47], v108 offset:16
	global_load_dwordx4 v[162:165], v[126:127], off offset:16 nt
	global_load_dwordx4 v[178:181], v[126:127], off nt
	v_add_f32_e32 v66, v66, v70
	v_add_f32_e32 v67, v67, v71
	v_add_f32_e32 v64, v64, v68
	v_add_f32_e32 v65, v65, v69
	v_add_f32_e32 v62, v62, v124
	v_add_f32_e32 v63, v63, v125
	v_add_f32_e32 v60, v60, v122
	v_add_f32_e32 v61, v61, v123
	v_add_f32_e32 v66, v66, v132
	v_add_f32_e32 v67, v67, v133
	v_add_f32_e32 v64, v64, v130
	v_add_f32_e32 v65, v65, v131
	v_add_f32_e32 v62, v62, v140
	v_add_f32_e32 v63, v63, v141
	v_add_f32_e32 v60, v60, v138
	v_add_f32_e32 v61, v61, v139
	v_add_f32_e32 v22, v66, v22
	v_add_f32_e32 v23, v67, v23
	v_add_f32_e32 v20, v64, v20
	v_add_f32_e32 v21, v65, v21
	v_add_f32_e32 v62, v62, v136
	v_add_f32_e32 v63, v63, v137
	v_add_f32_e32 v60, v60, v134
	v_add_f32_e32 v61, v61, v135
	s_add_i32 s2, s2, s3
	s_add_i32 s35, s35, s36
	s_cmpk_gt_i32 s2, 0x3ff
	v_add_f32_e32 v22, v22, v144
	v_add_f32_e32 v23, v23, v145
	v_add_f32_e32 v20, v20, v142
	v_add_f32_e32 v21, v21, v143
	v_add_f32_e32 v62, v62, v148
	v_add_f32_e32 v63, v63, v149
	v_add_f32_e32 v60, v60, v146
	v_add_f32_e32 v61, v61, v147
	v_add_f32_e32 v22, v22, v26
	v_add_f32_e32 v23, v23, v27
	v_add_f32_e32 v20, v20, v24
	v_add_f32_e32 v21, v21, v25
	v_add_f32_e32 v24, v62, v120
	v_add_f32_e32 v25, v63, v121
	v_add_f32_e32 v26, v60, v118
	v_add_f32_e32 v27, v61, v119
	v_add_f32_e32 v22, v22, v152
	v_add_f32_e32 v23, v23, v153
	v_add_f32_e32 v20, v20, v150
	v_add_f32_e32 v21, v21, v151
	v_add_f32_e32 v60, v24, v160
	v_add_f32_e32 v61, v25, v161
	v_add_f32_e32 v62, v26, v158
	v_add_f32_e32 v63, v27, v159
	v_add_f32_e32 v64, v22, v14
	v_add_f32_e32 v65, v23, v15
	v_add_f32_e32 v66, v20, v12
	v_add_f32_e32 v67, v21, v13
	v_lshl_add_u64 v[26:27], v[88:89], 0, s[28:29]
	v_lshl_add_u64 v[26:27], v[26:27], 0, s[4:5]
	s_waitcnt vmcnt(1) lgkmcnt(6)
	v_fma_f32 v22, v64, v156, v164
	v_fma_f32 v23, v65, v157, v165
	s_waitcnt vmcnt(0)
	v_fma_f32 v14, v60, v34, v180
	v_fma_f32 v15, v61, v35, v181
	v_fma_f32 v12, v62, v32, v178
	v_fma_f32 v13, v63, v33, v179
	v_fma_f32 v20, v66, v154, v162
	v_fma_f32 v21, v67, v155, v163
	global_store_dwordx4 v[126:127], v[12:15], off
	global_store_dwordx4 v[126:127], v[20:23], off offset:16
	s_nop 0
	v_lshl_add_u64 v[12:13], v[84:85], 0, s[28:29]
	v_lshl_add_u64 v[24:25], v[12:13], 0, s[4:5]
	global_load_dwordx4 v[12:15], v[24:25], off offset:16 nt
	global_load_dwordx4 v[20:23], v[24:25], off nt
	s_waitcnt vmcnt(1) lgkmcnt(0)
	v_fma_f32 v14, v64, v46, v14
	v_fma_f32 v15, v65, v47, v15
	v_fma_f32 v12, v66, v44, v12
	v_fma_f32 v13, v67, v45, v13
	s_waitcnt vmcnt(0)
	v_fma_f32 v22, v60, v176, v22
	v_fma_f32 v23, v61, v177, v23
	v_fma_f32 v20, v62, v174, v20
	v_fma_f32 v21, v63, v175, v21
	global_store_dwordx4 v[24:25], v[12:15], off offset:16
	global_store_dwordx4 v[24:25], v[20:23], off
	s_nop 0
	v_lshl_add_u64 v[12:13], v[86:87], 0, s[28:29]
	v_lshl_add_u64 v[24:25], v[12:13], 0, s[4:5]
	global_load_dwordx4 v[12:15], v[24:25], off offset:16 nt
	global_load_dwordx4 v[20:23], v[24:25], off nt
	s_waitcnt vmcnt(1)
	v_fma_f32 v14, v64, v54, v14
	v_fma_f32 v15, v65, v55, v15
	s_waitcnt vmcnt(0)
	v_fma_f32 v22, v60, v42, v22
	v_fma_f32 v23, v61, v43, v23
	v_fma_f32 v20, v62, v40, v20
	v_fma_f32 v21, v63, v41, v21
	v_fma_f32 v12, v66, v52, v12
	v_fma_f32 v13, v67, v53, v13
	global_store_dwordx4 v[24:25], v[20:23], off
	global_store_dwordx4 v[24:25], v[12:15], off offset:16
	global_load_dwordx4 v[12:15], v[26:27], off offset:16 nt
	v_lshl_add_u64 v[24:25], v[90:91], 0, s[28:29]
	global_load_dwordx4 v[20:23], v[26:27], off nt
	v_lshl_add_u64 v[40:41], v[24:25], 0, s[4:5]
	v_lshl_add_u64 v[42:43], v[92:93], 0, s[28:29]
	v_lshl_add_u64 v[42:43], v[42:43], 0, s[4:5]
	s_waitcnt vmcnt(1)
	v_fma_f32 v14, v64, v168, v14
	v_fma_f32 v15, v65, v169, v15
	v_fma_f32 v12, v66, v166, v12
	v_fma_f32 v13, v67, v167, v13
	s_waitcnt vmcnt(0)
	v_fma_f32 v22, v60, v172, v22
	v_fma_f32 v23, v61, v173, v23
	v_fma_f32 v20, v62, v170, v20
	v_fma_f32 v21, v63, v171, v21
	global_store_dwordx4 v[26:27], v[20:23], off
	global_store_dwordx4 v[26:27], v[12:15], off offset:16
	ds_write2_b32 v105, v28, v16 offset1:16
	ds_write2_b32 v105, v29, v17 offset0:128 offset1:144
	ds_write2_b32 v128, v30, v18 offset1:16
	ds_write2_b32 v128, v31, v19 offset0:128 offset1:144
	ds_write2_b32 v105, v36, v0 offset0:32 offset1:48
	ds_write2_b32 v105, v37, v1 offset0:160 offset1:176
	ds_write2_b32 v128, v38, v2 offset0:32 offset1:48
	ds_write2_b32 v128, v39, v3 offset0:160 offset1:176
	ds_write2_b32 v105, v48, v8 offset0:64 offset1:80
	ds_write2_b32 v105, v49, v9 offset0:192 offset1:208
	ds_write2_b32 v128, v50, v10 offset0:64 offset1:80
	ds_write2_b32 v128, v51, v11 offset0:192 offset1:208
	ds_write2st64_b32 v106, v56, v57 offset1:2
	ds_write2st64_b32 v106, v58, v59 offset0:4 offset1:6
	ds_write2st64_b32 v107, v4, v5 offset1:2
	ds_write2st64_b32 v107, v6, v7 offset0:4 offset1:6
	ds_read_b128 v[28:31], v104
	ds_read_b128 v[24:27], v104 offset:16
	ds_read_b128 v[20:23], v108
	ds_read_b128 v[16:19], v108 offset:16
	ds_read_b128 v[12:15], v109
	ds_read_b128 v[8:11], v109 offset:16
	ds_read_b128 v[4:7], v110
	ds_read_b128 v[0:3], v110 offset:16
	global_load_dwordx4 v[32:35], v[40:41], off offset:16 nt
	global_load_dwordx4 v[36:39], v[40:41], off nt
	s_waitcnt vmcnt(1) lgkmcnt(6)
	v_fma_f32 v26, v64, v26, v34
	v_fma_f32 v27, v65, v27, v35
	s_waitcnt vmcnt(0)
	v_fma_f32 v30, v60, v30, v38
	v_fma_f32 v31, v61, v31, v39
	v_fma_f32 v28, v62, v28, v36
	v_fma_f32 v29, v63, v29, v37
	v_fma_f32 v24, v66, v24, v32
	v_fma_f32 v25, v67, v25, v33
	global_store_dwordx4 v[40:41], v[28:31], off
	global_store_dwordx4 v[40:41], v[24:27], off offset:16
	global_load_dwordx4 v[24:27], v[42:43], off offset:16 nt
	v_lshl_add_u64 v[32:33], v[94:95], 0, s[28:29]
	global_load_dwordx4 v[28:31], v[42:43], off nt
	v_lshl_add_u64 v[32:33], v[32:33], 0, s[4:5]
	s_waitcnt vmcnt(1) lgkmcnt(4)
	v_fma_f32 v18, v64, v18, v26
	v_fma_f32 v19, v65, v19, v27
	v_fma_f32 v16, v66, v16, v24
	v_fma_f32 v17, v67, v17, v25
	s_waitcnt vmcnt(0)
	v_fma_f32 v22, v60, v22, v30
	v_fma_f32 v23, v61, v23, v31
	v_fma_f32 v20, v62, v20, v28
	v_fma_f32 v21, v63, v21, v29
	global_store_dwordx4 v[42:43], v[20:23], off
	global_store_dwordx4 v[42:43], v[16:19], off offset:16
	global_load_dwordx4 v[16:19], v[32:33], off offset:16 nt
	v_lshl_add_u64 v[24:25], v[96:97], 0, s[28:29]
	global_load_dwordx4 v[20:23], v[32:33], off nt
	v_lshl_add_u64 v[24:25], v[24:25], 0, s[4:5]
	s_waitcnt vmcnt(1) lgkmcnt(2)
	v_fma_f32 v10, v64, v10, v18
	v_fma_f32 v11, v65, v11, v19
	v_fma_f32 v8, v66, v8, v16
	v_fma_f32 v9, v67, v9, v17
	s_waitcnt vmcnt(0)
	v_fma_f32 v14, v60, v14, v22
	v_fma_f32 v15, v61, v15, v23
	v_fma_f32 v12, v62, v12, v20
	v_fma_f32 v13, v63, v13, v21
	global_store_dwordx4 v[32:33], v[12:15], off
	global_store_dwordx4 v[32:33], v[8:11], off offset:16
	global_load_dwordx4 v[8:11], v[24:25], off offset:16 nt
	s_waitcnt vmcnt(0) lgkmcnt(0)
	v_fma_f32 v2, v64, v2, v10
	v_fma_f32 v3, v65, v3, v11
	global_load_dwordx4 v[12:15], v[24:25], off nt
	v_fma_f32 v0, v66, v0, v8
	v_fma_f32 v1, v67, v1, v9
	global_store_dwordx4 v[24:25], v[0:3], off offset:16
	s_waitcnt vmcnt(1)
	v_fma_f32 v6, v60, v6, v14
	v_fma_f32 v7, v61, v7, v15
	v_fma_f32 v4, v62, v4, v12
	v_fma_f32 v5, v63, v5, v13
	global_store_dwordx4 v[24:25], v[4:7], off
	s_cbranch_scc0 .LBB0_686
